# v66 + GEMM K-loops: SALU runs after each loop barrier moved in front of it (7.11 back-edge rotation, all 12 instances)
# baseline (speedup 1.0000x reference)
; #define PG8_STAGE(bufoff, gbase, X) do { _Pragma("unroll") for (int _i = 0; _i < 2; ++_i) { \
;         const char* gp_ = (const char*)(gbase) + (_i ? rs##X : (size_t)0); const unsigned la_ = (unsigned)(size_t)(lds + (bufoff) + ldsw + _i * 8192); \
;         asm volatile("s_mov_b32 m0, %2\n\ts_nop 0\n\tglobal_load_lds_dwordx4 %0, %1" :: "v"(voff##X), "s"(gp_), "s"(la_) : "memory", "m0"); } } while (0)
; #define PG8_LDA(dst, b, h) do { _Pragma("unroll") for (int m = 0; m < 4; ++m) _Pragma("unroll") for (int k = 0; k < 2; ++k) dst[m][k] = *(const LAS bf16x8*)(lds + PG8_SA(b, h) + aoff + m * 2048 + k * 1024); } while (0)
; #define PG8_LDB(dst, b, h) do { _Pragma("unroll") for (int n = 0; n < 2; ++n) _Pragma("unroll") for (int k = 0; k < 2; ++k) dst[n][k] = *(const LAS bf16x8*)(lds + PG8_SB(b, h) + boff + n * 2048 + k * 1024); } while (0)
; #define PG8_WAIT_V(n) asm volatile("s_waitcnt vmcnt(" #n ")" ::: "memory")
; #define PG8_WAIT_L(n) asm volatile("s_waitcnt lgkmcnt(" #n ")" ::: "memory")
; #define PG8_BAR __builtin_amdgcn_s_barrier()
; #define PG8_SCHED __builtin_amdgcn_sched_barrier(0)
; template <class Epi>
; __device__ __forceinline__ void gemm_phase(LAS unsigned char* lds, const Gemm g_in, const StaticOrder& S, const Epi& E) {
;     ...
;         const bool has_next = S.next(ui + 1, nxt);
;         const char* nA = has_next ? (const char*)g.A + (size_t)nxt.pm * tsA : cA; const char* nB = has_next ? (const char*)g.Bt + (size_t)nxt.pn * tsB : cB;
;         for (int t = 0; t < nt; t += 2) {
;             const bool last = (t == nt - 2);
;             const char* a1 = cA + (size_t)(t + 1) * kstep;
;             const char* a2 = last ? nA : cA + (size_t)(t + 2) * kstep; const char* b2 = last ? nB : cB + (size_t)(t + 2) * kstep;
;             const char* a3 = a2 + kstep; const char* b3 = b2 + kstep;
;             PG8_LDB(B0, 0, 0); PG8_LDB(B1, 0, 1); PG8_SCHED; PG8_LDA(At, 0, 0); PG8_STAGE(PG8_SA(1, 1), a1 + hsA, A);
;             PG8_WAIT_V(8); PG8_WAIT_L(0); PG8_BAR; PG8_MMA(0, 0, At, B0); PG8_MMA(0, 1, At, B1); PG8_BAR; PG8_SCHED;
;             PG8_LDA(At, 0, 1); PG8_STAGE(PG8_SB(0, 0), b2, B); PG8_STAGE(PG8_SB(0, 1), b2 + hsB, B); PG8_STAGE(PG8_SA(0, 0), a2, A);
;             PG8_WAIT_V(8); PG8_WAIT_L(0); PG8_BAR; PG8_MMA(1, 0, At, B0); PG8_MMA(1, 1, At, B1); PG8_BAR; PG8_SCHED;
.LBB0_156:
	v_add_u32_e32 v139, 0x10000, v137
	ds_read_b128 v[140:143], v139
	ds_read_b128 v[144:147], v139 offset:1024
	ds_read_b128 v[148:151], v139 offset:2048
	ds_read_b128 v[152:155], v139 offset:3072
	v_add_u32_e32 v139, 0x14000, v137
	ds_read_b128 v[156:159], v139
	ds_read_b128 v[172:175], v139 offset:1024
	ds_read_b128 v[182:185], v139 offset:2048
	ds_read_b128 v[186:189], v139 offset:3072
	s_add_i32 s63, s8, 2
	s_add_u32 s26, s4, 0xfff40080
	s_addc_u32 s9, s5, -1
	s_cmp_eq_u32 s55, s8
	s_cselect_b32 s8, s21, s26
	s_cselect_b32 s9, s19, s9
	s_cselect_b32 s28, s60, s61
	s_cselect_b32 s29, s59, s62
	s_add_u32 s26, s8, 0x80
	s_addc_u32 s27, s9, 0
	ds_read_b128 v[190:193], v138
	ds_read_b128 v[194:197], v138 offset:1024
	ds_read_b128 v[198:201], v138 offset:2048
	ds_read_b128 v[202:205], v138 offset:3072
	ds_read_b128 v[206:209], v138 offset:4096
	ds_read_b128 v[210:213], v138 offset:5120
	ds_read_b128 v[214:217], v138 offset:6144
	ds_read_b128 v[218:221], v138 offset:7168
	s_add_u32 s64, s4, 0xfffc0000
	s_addc_u32 s65, s5, -1
	s_mov_b32 m0, s56
	s_nop 0
	global_load_lds_dwordx4 v1, s[64:65]
	s_nop 0
	s_mov_b32 m0, s57
	s_nop 0
	global_load_lds_dwordx4 v1, s[4:5]
	s_waitcnt vmcnt(8)
	s_waitcnt lgkmcnt(0)
	s_barrier
	s_setprio 1
	s_waitcnt lgkmcnt(7)
	v_mfma_i32_16x16x64_i8 v[126:129], v[140:143], v[190:193], v[126:129]
	v_mfma_i32_16x16x64_i8 v[118:121], v[148:151], v[190:193], v[118:121]
	s_waitcnt lgkmcnt(5)
	v_mfma_i32_16x16x64_i8 v[110:113], v[140:143], v[198:201], v[110:113]
	v_mfma_i32_16x16x64_i8 v[102:105], v[148:151], v[198:201], v[102:105]
	s_waitcnt lgkmcnt(3)
	v_mfma_i32_16x16x64_i8 v[94:97], v[140:143], v[206:209], v[94:97]
	v_mfma_i32_16x16x64_i8 v[86:89], v[148:151], v[206:209], v[86:89]
	s_waitcnt lgkmcnt(1)
	v_mfma_i32_16x16x64_i8 v[78:81], v[140:143], v[214:217], v[78:81]
	v_mfma_i32_16x16x64_i8 v[70:73], v[148:151], v[214:217], v[70:73]
	v_mfma_i32_16x16x64_i8 v[126:129], v[144:147], v[194:197], v[126:129]
	v_mfma_i32_16x16x64_i8 v[118:121], v[152:155], v[194:197], v[118:121]
	v_mfma_i32_16x16x64_i8 v[110:113], v[144:147], v[202:205], v[110:113]
	v_mfma_i32_16x16x64_i8 v[102:105], v[152:155], v[202:205], v[102:105]
	v_mfma_i32_16x16x64_i8 v[94:97], v[144:147], v[210:213], v[94:97]
	v_mfma_i32_16x16x64_i8 v[86:89], v[152:155], v[210:213], v[86:89]
	s_waitcnt lgkmcnt(0)
	v_mfma_i32_16x16x64_i8 v[78:81], v[144:147], v[218:221], v[78:81]
	v_mfma_i32_16x16x64_i8 v[70:73], v[152:155], v[218:221], v[70:73]
	s_setprio 0
	s_setprio 1
	v_mfma_i32_16x16x64_i8 v[122:125], v[156:159], v[190:193], v[122:125]
	v_mfma_i32_16x16x64_i8 v[114:117], v[182:185], v[190:193], v[114:117]
	v_mfma_i32_16x16x64_i8 v[106:109], v[156:159], v[198:201], v[106:109]
	v_mfma_i32_16x16x64_i8 v[98:101], v[182:185], v[198:201], v[98:101]
	v_mfma_i32_16x16x64_i8 v[90:93], v[156:159], v[206:209], v[90:93]
	v_mfma_i32_16x16x64_i8 v[82:85], v[182:185], v[206:209], v[82:85]
	v_mfma_i32_16x16x64_i8 v[74:77], v[156:159], v[214:217], v[74:77]
	v_mfma_i32_16x16x64_i8 v[66:69], v[182:185], v[214:217], v[66:69]
	v_mfma_i32_16x16x64_i8 v[122:125], v[172:175], v[194:197], v[122:125]
	v_mfma_i32_16x16x64_i8 v[114:117], v[186:189], v[194:197], v[114:117]
	v_mfma_i32_16x16x64_i8 v[106:109], v[172:175], v[202:205], v[106:109]
	v_mfma_i32_16x16x64_i8 v[98:101], v[186:189], v[202:205], v[98:101]
	v_mfma_i32_16x16x64_i8 v[90:93], v[172:175], v[210:213], v[90:93]
	v_mfma_i32_16x16x64_i8 v[82:85], v[186:189], v[210:213], v[82:85]
	v_mfma_i32_16x16x64_i8 v[74:77], v[172:175], v[218:221], v[74:77]
	v_mfma_i32_16x16x64_i8 v[66:69], v[186:189], v[218:221], v[66:69]
	s_setprio 0
	s_add_u32 s64, s28, 0x40000
	s_barrier
	ds_read_b128 v[190:193], v138 offset:16384
	ds_read_b128 v[194:197], v138 offset:17408
	ds_read_b128 v[198:201], v138 offset:18432
	ds_read_b128 v[202:205], v138 offset:19456
	ds_read_b128 v[206:209], v138 offset:20480
	ds_read_b128 v[210:213], v138 offset:21504
	ds_read_b128 v[214:217], v138 offset:22528
	ds_read_b128 v[218:221], v138 offset:23552
	s_mov_b32 m0, s38
	s_nop 0
	global_load_lds_dwordx4 v134, s[28:29]
	s_addc_u32 s65, s29, 0
	s_mov_b32 m0, s39
	s_nop 0
	global_load_lds_dwordx4 v134, s[64:65]
	s_add_u32 s64, s28, 0x80000
	s_addc_u32 s65, s29, 0
	s_mov_b32 m0, s40
	s_nop 0
	global_load_lds_dwordx4 v134, s[64:65]
	s_add_u32 s64, s28, 0xc0000
	s_addc_u32 s65, s29, 0
	s_mov_b32 m0, s41
	s_nop 0
	global_load_lds_dwordx4 v134, s[64:65]
	s_add_u32 s64, s8, 0x40000
	s_mov_b32 m0, s37
	s_nop 0
	global_load_lds_dwordx4 v1, s[8:9]
	s_addc_u32 s65, s9, 0
	s_mov_b32 m0, s42
	s_nop 0
	global_load_lds_dwordx4 v1, s[64:65]
	s_waitcnt vmcnt(8)
	s_waitcnt lgkmcnt(0)
	s_barrier
; #define PG8_STAGE(bufoff, gbase, X) do { _Pragma("unroll") for (int _i = 0; _i < 2; ++_i) { \
;         const char* gp_ = (const char*)(gbase) + (_i ? rs##X : (size_t)0); const unsigned la_ = (unsigned)(size_t)(lds + (bufoff) + ldsw + _i * 8192); \
;         asm volatile("s_mov_b32 m0, %2\n\ts_nop 0\n\tglobal_load_lds_dwordx4 %0, %1" :: "v"(voff##X), "s"(gp_), "s"(la_) : "memory", "m0"); } } while (0)
; #define PG8_LDA(dst, b, h) do { _Pragma("unroll") for (int m = 0; m < 4; ++m) _Pragma("unroll") for (int k = 0; k < 2; ++k) dst[m][k] = *(const LAS bf16x8*)(lds + PG8_SA(b, h) + aoff + m * 2048 + k * 1024); } while (0)
; #define PG8_LDB(dst, b, h) do { _Pragma("unroll") for (int n = 0; n < 2; ++n) _Pragma("unroll") for (int k = 0; k < 2; ++k) dst[n][k] = *(const LAS bf16x8*)(lds + PG8_SB(b, h) + boff + n * 2048 + k * 1024); } while (0)
; #define PG8_WAIT_V(n) asm volatile("s_waitcnt vmcnt(" #n ")" ::: "memory")
; #define PG8_WAIT_L(n) asm volatile("s_waitcnt lgkmcnt(" #n ")" ::: "memory")
; #define PG8_BAR __builtin_amdgcn_s_barrier()
; #define PG8_SCHED __builtin_amdgcn_sched_barrier(0)
; template <class Epi>
; __device__ __forceinline__ void gemm_phase(LAS unsigned char* lds, const Gemm g_in, const StaticOrder& S, const Epi& E) {
;     ...
;             PG8_WAIT_V(8); PG8_WAIT_L(0); PG8_BAR; PG8_MMA(1, 0, At, B0); PG8_MMA(1, 1, At, B1); PG8_BAR; PG8_SCHED;
;             PG8_LDB(B0, 1, 0); PG8_LDB(B1, 1, 1); PG8_SCHED; PG8_LDA(At, 1, 0); PG8_STAGE(PG8_SA(0, 1), a2 + hsA, A);
;             PG8_WAIT_V(8); PG8_WAIT_L(0); PG8_BAR; PG8_MMA(0, 0, At, B0); PG8_MMA(0, 1, At, B1); PG8_BAR; PG8_SCHED;
;             PG8_LDA(At, 1, 1); PG8_STAGE(PG8_SB(1, 0), b3, B); PG8_STAGE(PG8_SB(1, 1), b3 + hsB, B); PG8_STAGE(PG8_SA(1, 0), a3, A);
	s_setprio 1
	s_waitcnt lgkmcnt(7)
	v_mfma_i32_16x16x64_i8 v[62:65], v[140:143], v[190:193], v[62:65]
	v_mfma_i32_16x16x64_i8 v[54:57], v[148:151], v[190:193], v[54:57]
	s_waitcnt lgkmcnt(5)
	v_mfma_i32_16x16x64_i8 v[46:49], v[140:143], v[198:201], v[46:49]
	v_mfma_i32_16x16x64_i8 v[38:41], v[148:151], v[198:201], v[38:41]
	s_waitcnt lgkmcnt(3)
	v_mfma_i32_16x16x64_i8 v[30:33], v[140:143], v[206:209], v[30:33]
	v_mfma_i32_16x16x64_i8 v[22:25], v[148:151], v[206:209], v[22:25]
	s_waitcnt lgkmcnt(1)
	v_mfma_i32_16x16x64_i8 v[14:17], v[140:143], v[214:217], v[14:17]
	v_mfma_i32_16x16x64_i8 v[6:9], v[148:151], v[214:217], v[6:9]
	v_mfma_i32_16x16x64_i8 v[62:65], v[144:147], v[194:197], v[62:65]
	v_mfma_i32_16x16x64_i8 v[54:57], v[152:155], v[194:197], v[54:57]
	v_mfma_i32_16x16x64_i8 v[46:49], v[144:147], v[202:205], v[46:49]
	v_mfma_i32_16x16x64_i8 v[38:41], v[152:155], v[202:205], v[38:41]
	v_mfma_i32_16x16x64_i8 v[30:33], v[144:147], v[210:213], v[30:33]
	v_mfma_i32_16x16x64_i8 v[22:25], v[152:155], v[210:213], v[22:25]
	s_waitcnt lgkmcnt(0)
	v_mfma_i32_16x16x64_i8 v[14:17], v[144:147], v[218:221], v[14:17]
	v_mfma_i32_16x16x64_i8 v[6:9], v[152:155], v[218:221], v[6:9]
	s_setprio 0
	s_setprio 1
	v_mfma_i32_16x16x64_i8 v[58:61], v[156:159], v[190:193], v[58:61]
	v_mfma_i32_16x16x64_i8 v[50:53], v[182:185], v[190:193], v[50:53]
	v_mfma_i32_16x16x64_i8 v[42:45], v[156:159], v[198:201], v[42:45]
	v_mfma_i32_16x16x64_i8 v[34:37], v[182:185], v[198:201], v[34:37]
	v_mfma_i32_16x16x64_i8 v[26:29], v[156:159], v[206:209], v[26:29]
	v_mfma_i32_16x16x64_i8 v[18:21], v[182:185], v[206:209], v[18:21]
	v_mfma_i32_16x16x64_i8 v[10:13], v[156:159], v[214:217], v[10:13]
	v_mfma_i32_16x16x64_i8 v[2:5], v[182:185], v[214:217], v[2:5]
	v_mfma_i32_16x16x64_i8 v[58:61], v[172:175], v[194:197], v[58:61]
	v_mfma_i32_16x16x64_i8 v[50:53], v[186:189], v[194:197], v[50:53]
	v_mfma_i32_16x16x64_i8 v[42:45], v[172:175], v[202:205], v[42:45]
	v_mfma_i32_16x16x64_i8 v[34:37], v[186:189], v[202:205], v[34:37]
	v_mfma_i32_16x16x64_i8 v[26:29], v[172:175], v[210:213], v[26:29]
	v_mfma_i32_16x16x64_i8 v[18:21], v[186:189], v[210:213], v[18:21]
	v_mfma_i32_16x16x64_i8 v[10:13], v[172:175], v[218:221], v[10:13]
	v_mfma_i32_16x16x64_i8 v[2:5], v[186:189], v[218:221], v[2:5]
	s_setprio 0
	s_barrier
	v_add_u32_e32 v139, 0x18000, v137
	ds_read_b128 v[140:143], v139
	ds_read_b128 v[144:147], v139 offset:1024
	ds_read_b128 v[148:151], v139 offset:2048
	ds_read_b128 v[152:155], v139 offset:3072
	v_add_u32_e32 v139, 0x1c000, v137
	ds_read_b128 v[156:159], v139
	ds_read_b128 v[172:175], v139 offset:1024
	ds_read_b128 v[182:185], v139 offset:2048
	ds_read_b128 v[186:189], v139 offset:3072
	ds_read_b128 v[190:193], v138 offset:32768
	ds_read_b128 v[194:197], v138 offset:33792
	ds_read_b128 v[198:201], v138 offset:34816
	ds_read_b128 v[202:205], v138 offset:35840
	ds_read_b128 v[206:209], v138 offset:36864
	ds_read_b128 v[210:213], v138 offset:37888
	ds_read_b128 v[214:217], v138 offset:38912
	ds_read_b128 v[218:221], v138 offset:39936
	s_add_u32 s64, s8, 0x80000
	s_addc_u32 s65, s9, 0
	s_mov_b32 m0, s43
	s_nop 0
	global_load_lds_dwordx4 v1, s[64:65]
	s_add_u32 s64, s8, 0xc0000
	s_addc_u32 s65, s9, 0
	s_mov_b32 m0, s44
	s_nop 0
	global_load_lds_dwordx4 v1, s[64:65]
	s_waitcnt vmcnt(8)
	s_waitcnt lgkmcnt(0)
	s_barrier
	s_setprio 1
	s_waitcnt lgkmcnt(7)
	v_mfma_i32_16x16x64_i8 v[126:129], v[140:143], v[190:193], v[126:129]
	v_mfma_i32_16x16x64_i8 v[118:121], v[148:151], v[190:193], v[118:121]
	s_waitcnt lgkmcnt(5)
	v_mfma_i32_16x16x64_i8 v[110:113], v[140:143], v[198:201], v[110:113]
	v_mfma_i32_16x16x64_i8 v[102:105], v[148:151], v[198:201], v[102:105]
	s_waitcnt lgkmcnt(3)
	v_mfma_i32_16x16x64_i8 v[94:97], v[140:143], v[206:209], v[94:97]
	v_mfma_i32_16x16x64_i8 v[86:89], v[148:151], v[206:209], v[86:89]
	s_waitcnt lgkmcnt(1)
	v_mfma_i32_16x16x64_i8 v[78:81], v[140:143], v[214:217], v[78:81]
	v_mfma_i32_16x16x64_i8 v[70:73], v[148:151], v[214:217], v[70:73]
	v_mfma_i32_16x16x64_i8 v[126:129], v[144:147], v[194:197], v[126:129]
	v_mfma_i32_16x16x64_i8 v[118:121], v[152:155], v[194:197], v[118:121]
	v_mfma_i32_16x16x64_i8 v[110:113], v[144:147], v[202:205], v[110:113]
	v_mfma_i32_16x16x64_i8 v[102:105], v[152:155], v[202:205], v[102:105]
	v_mfma_i32_16x16x64_i8 v[94:97], v[144:147], v[210:213], v[94:97]
	v_mfma_i32_16x16x64_i8 v[86:89], v[152:155], v[210:213], v[86:89]
	s_waitcnt lgkmcnt(0)
	v_mfma_i32_16x16x64_i8 v[78:81], v[144:147], v[218:221], v[78:81]
	v_mfma_i32_16x16x64_i8 v[70:73], v[152:155], v[218:221], v[70:73]
	s_setprio 0
	s_setprio 1
	v_mfma_i32_16x16x64_i8 v[122:125], v[156:159], v[190:193], v[122:125]
	v_mfma_i32_16x16x64_i8 v[114:117], v[182:185], v[190:193], v[114:117]
	v_mfma_i32_16x16x64_i8 v[106:109], v[156:159], v[198:201], v[106:109]
	v_mfma_i32_16x16x64_i8 v[98:101], v[182:185], v[198:201], v[98:101]
	v_mfma_i32_16x16x64_i8 v[90:93], v[156:159], v[206:209], v[90:93]
	v_mfma_i32_16x16x64_i8 v[82:85], v[182:185], v[206:209], v[82:85]
	v_mfma_i32_16x16x64_i8 v[74:77], v[156:159], v[214:217], v[74:77]
	v_mfma_i32_16x16x64_i8 v[66:69], v[182:185], v[214:217], v[66:69]
	v_mfma_i32_16x16x64_i8 v[122:125], v[172:175], v[194:197], v[122:125]
	v_mfma_i32_16x16x64_i8 v[114:117], v[186:189], v[194:197], v[114:117]
	v_mfma_i32_16x16x64_i8 v[106:109], v[172:175], v[202:205], v[106:109]
	v_mfma_i32_16x16x64_i8 v[98:101], v[186:189], v[202:205], v[98:101]
	v_mfma_i32_16x16x64_i8 v[90:93], v[172:175], v[210:213], v[90:93]
	v_mfma_i32_16x16x64_i8 v[82:85], v[186:189], v[210:213], v[82:85]
	v_mfma_i32_16x16x64_i8 v[74:77], v[172:175], v[218:221], v[74:77]
	v_mfma_i32_16x16x64_i8 v[66:69], v[186:189], v[218:221], v[66:69]
	s_setprio 0
	s_add_u32 s64, s28, 0x80
	s_addc_u32 s65, s29, 0
	s_barrier
; #define PG8_STAGE(bufoff, gbase, X) do { _Pragma("unroll") for (int _i = 0; _i < 2; ++_i) { \
;         const char* gp_ = (const char*)(gbase) + (_i ? rs##X : (size_t)0); const unsigned la_ = (unsigned)(size_t)(lds + (bufoff) + ldsw + _i * 8192); \
;         asm volatile("s_mov_b32 m0, %2\n\ts_nop 0\n\tglobal_load_lds_dwordx4 %0, %1" :: "v"(voff##X), "s"(gp_), "s"(la_) : "memory", "m0"); } } while (0)
; #define PG8_LDA(dst, b, h) do { _Pragma("unroll") for (int m = 0; m < 4; ++m) _Pragma("unroll") for (int k = 0; k < 2; ++k) dst[m][k] = *(const LAS bf16x8*)(lds + PG8_SA(b, h) + aoff + m * 2048 + k * 1024); } while (0)
; #define PG8_WAIT_V(n) asm volatile("s_waitcnt vmcnt(" #n ")" ::: "memory")
; #define PG8_WAIT_L(n) asm volatile("s_waitcnt lgkmcnt(" #n ")" ::: "memory")
; #define PG8_BAR __builtin_amdgcn_s_barrier()
; #define PG8_SCHED __builtin_amdgcn_sched_barrier(0)
; template <class Epi>
; __device__ __forceinline__ void gemm_phase(LAS unsigned char* lds, const Gemm g_in, const StaticOrder& S, const Epi& E) {
;     ...
;             PG8_LDA(At, 1, 1); PG8_STAGE(PG8_SB(1, 0), b3, B); PG8_STAGE(PG8_SB(1, 1), b3 + hsB, B); PG8_STAGE(PG8_SA(1, 0), a3, A);
;             PG8_WAIT_V(8); PG8_WAIT_L(0); PG8_BAR; PG8_MMA(1, 0, At, B0); PG8_MMA(1, 1, At, B1); PG8_BAR; PG8_SCHED;
;         }
	ds_read_b128 v[190:193], v138 offset:49152
	ds_read_b128 v[194:197], v138 offset:50176
	ds_read_b128 v[198:201], v138 offset:51200
	ds_read_b128 v[202:205], v138 offset:52224
	ds_read_b128 v[206:209], v138 offset:53248
	ds_read_b128 v[210:213], v138 offset:54272
	ds_read_b128 v[214:217], v138 offset:55296
	ds_read_b128 v[218:221], v138 offset:56320
	s_mov_b32 m0, s47
	s_nop 0
	global_load_lds_dwordx4 v134, s[64:65]
	s_add_u32 s64, s28, 0x40080
	s_addc_u32 s65, s29, 0
	s_mov_b32 m0, s50
	s_nop 0
	global_load_lds_dwordx4 v134, s[64:65]
	s_add_u32 s64, s28, 0x80080
	s_addc_u32 s65, s29, 0
	s_mov_b32 m0, s53
	s_nop 0
	global_load_lds_dwordx4 v134, s[64:65]
	s_add_u32 s28, s28, 0xc0080
	s_addc_u32 s29, s29, 0
	s_mov_b32 m0, s54
	s_nop 0
	global_load_lds_dwordx4 v134, s[28:29]
	s_add_u32 s8, s8, 0x40080
	s_mov_b32 m0, s51
	s_nop 0
	global_load_lds_dwordx4 v1, s[26:27]
	s_addc_u32 s9, s9, 0
	s_mov_b32 m0, s52
	s_nop 0
	global_load_lds_dwordx4 v1, s[8:9]
	s_waitcnt vmcnt(8)
	s_waitcnt lgkmcnt(0)
	s_barrier
	s_setprio 1
	s_waitcnt lgkmcnt(7)
	v_mfma_i32_16x16x64_i8 v[62:65], v[140:143], v[190:193], v[62:65]
	v_mfma_i32_16x16x64_i8 v[54:57], v[148:151], v[190:193], v[54:57]
	s_waitcnt lgkmcnt(5)
	v_mfma_i32_16x16x64_i8 v[46:49], v[140:143], v[198:201], v[46:49]
	v_mfma_i32_16x16x64_i8 v[38:41], v[148:151], v[198:201], v[38:41]
	s_waitcnt lgkmcnt(3)
	v_mfma_i32_16x16x64_i8 v[30:33], v[140:143], v[206:209], v[30:33]
	v_mfma_i32_16x16x64_i8 v[22:25], v[148:151], v[206:209], v[22:25]
	s_waitcnt lgkmcnt(1)
	v_mfma_i32_16x16x64_i8 v[14:17], v[140:143], v[214:217], v[14:17]
	v_mfma_i32_16x16x64_i8 v[6:9], v[148:151], v[214:217], v[6:9]
	v_mfma_i32_16x16x64_i8 v[62:65], v[144:147], v[194:197], v[62:65]
	v_mfma_i32_16x16x64_i8 v[54:57], v[152:155], v[194:197], v[54:57]
	v_mfma_i32_16x16x64_i8 v[46:49], v[144:147], v[202:205], v[46:49]
	v_mfma_i32_16x16x64_i8 v[38:41], v[152:155], v[202:205], v[38:41]
	v_mfma_i32_16x16x64_i8 v[30:33], v[144:147], v[210:213], v[30:33]
	v_mfma_i32_16x16x64_i8 v[22:25], v[152:155], v[210:213], v[22:25]
	s_waitcnt lgkmcnt(0)
	v_mfma_i32_16x16x64_i8 v[14:17], v[144:147], v[218:221], v[14:17]
	v_mfma_i32_16x16x64_i8 v[6:9], v[152:155], v[218:221], v[6:9]
	s_setprio 0
	s_setprio 1
	v_mfma_i32_16x16x64_i8 v[58:61], v[156:159], v[190:193], v[58:61]
	v_mfma_i32_16x16x64_i8 v[50:53], v[182:185], v[190:193], v[50:53]
	v_mfma_i32_16x16x64_i8 v[42:45], v[156:159], v[198:201], v[42:45]
	v_mfma_i32_16x16x64_i8 v[34:37], v[182:185], v[198:201], v[34:37]
	v_mfma_i32_16x16x64_i8 v[26:29], v[156:159], v[206:209], v[26:29]
	v_mfma_i32_16x16x64_i8 v[18:21], v[182:185], v[206:209], v[18:21]
	v_mfma_i32_16x16x64_i8 v[10:13], v[156:159], v[214:217], v[10:13]
	v_mfma_i32_16x16x64_i8 v[2:5], v[182:185], v[214:217], v[2:5]
	v_mfma_i32_16x16x64_i8 v[58:61], v[172:175], v[194:197], v[58:61]
	v_mfma_i32_16x16x64_i8 v[50:53], v[186:189], v[194:197], v[50:53]
	v_mfma_i32_16x16x64_i8 v[42:45], v[172:175], v[202:205], v[42:45]
	v_mfma_i32_16x16x64_i8 v[34:37], v[186:189], v[202:205], v[34:37]
	v_mfma_i32_16x16x64_i8 v[26:29], v[172:175], v[210:213], v[26:29]
	v_mfma_i32_16x16x64_i8 v[18:21], v[186:189], v[210:213], v[18:21]
	v_mfma_i32_16x16x64_i8 v[10:13], v[172:175], v[218:221], v[10:13]
	v_mfma_i32_16x16x64_i8 v[2:5], v[186:189], v[218:221], v[2:5]
	s_setprio 0
	s_add_u32 s61, s61, 0x100
	s_addc_u32 s62, s62, 0
	s_add_u32 s4, s4, 0x100
	s_addc_u32 s5, s5, 0
	s_cmp_ge_i32 s63, s34
	s_mov_b32 s8, s63
	s_barrier
	s_cbranch_scc0 .LBB0_156
	s_and_b64 vcc, exec, s[14:15]
	s_cbranch_vccz .LBB0_159

; #define PG8_STAGE(bufoff, gbase, X) do { _Pragma("unroll") for (int _i = 0; _i < 2; ++_i) { \
;         const char* gp_ = (const char*)(gbase) + (_i ? rs##X : (size_t)0); const unsigned la_ = (unsigned)(size_t)(lds + (bufoff) + ldsw + _i * 8192); \
;         asm volatile("s_mov_b32 m0, %2\n\ts_nop 0\n\tglobal_load_lds_dwordx4 %0, %1" :: "v"(voff##X), "s"(gp_), "s"(la_) : "memory", "m0"); } } while (0)
; #define PG8_LDA(dst, b, h) do { _Pragma("unroll") for (int m = 0; m < 4; ++m) _Pragma("unroll") for (int k = 0; k < 2; ++k) dst[m][k] = *(const LAS bf16x8*)(lds + PG8_SA(b, h) + aoff + m * 2048 + k * 1024); } while (0)
; #define PG8_LDB(dst, b, h) do { _Pragma("unroll") for (int n = 0; n < 2; ++n) _Pragma("unroll") for (int k = 0; k < 2; ++k) dst[n][k] = *(const LAS bf16x8*)(lds + PG8_SB(b, h) + boff + n * 2048 + k * 1024); } while (0)
; #define PG8_WAIT_V(n) asm volatile("s_waitcnt vmcnt(" #n ")" ::: "memory")
; template <class Epi>
; __device__ __forceinline__ void gemm_phase(LAS unsigned char* lds, const Gemm g_in, const StaticOrder& S, const Epi& E) {
;     ...
;         const bool has_next = S.next(ui + 1, nxt);
;         const char* nA = has_next ? (const char*)g.A + (size_t)nxt.pm * tsA : cA; const char* nB = has_next ? (const char*)g.Bt + (size_t)nxt.pn * tsB : cB;
;         for (int t = 0; t < nt; t += 2) {
;             const bool last = (t == nt - 2);
;             const char* a1 = cA + (size_t)(t + 1) * kstep;
;             const char* a2 = last ? nA : cA + (size_t)(t + 2) * kstep; const char* b2 = last ? nB : cB + (size_t)(t + 2) * kstep;
;             const char* a3 = a2 + kstep; const char* b3 = b2 + kstep;
;             PG8_LDB(B0, 0, 0); PG8_LDB(B1, 0, 1); PG8_SCHED; PG8_LDA(At, 0, 0); PG8_STAGE(PG8_SA(1, 1), a1 + hsA, A);
;             PG8_WAIT_V(8); PG8_WAIT_L(0); PG8_BAR; PG8_MMA(0, 0, At, B0); PG8_MMA(0, 1, At, B1); PG8_BAR; PG8_SCHED;
;             PG8_LDA(At, 0, 1); PG8_STAGE(PG8_SB(0, 0), b2, B); PG8_STAGE(PG8_SB(0, 1), b2 + hsB, B); PG8_STAGE(PG8_SA(0, 0), a2, A);
;             PG8_WAIT_V(8); PG8_WAIT_L(0); PG8_BAR; PG8_MMA(1, 0, At, B0); PG8_MMA(1, 1, At, B1); PG8_BAR; PG8_SCHED;
;             PG8_LDB(B0, 1, 0); PG8_LDB(B1, 1, 1); PG8_SCHED; PG8_LDA(At, 1, 0); PG8_STAGE(PG8_SA(0, 1), a2 + hsA, A);
;             PG8_WAIT_V(8); PG8_WAIT_L(0); PG8_BAR; PG8_MMA(0, 0, At, B0); PG8_MMA(0, 1, At, B1); PG8_BAR; PG8_SCHED;
.LBB0_238:
	ds_read_b128 v[26:29], v235
	ds_read_b128 v[30:33], v235 offset:1024
	ds_read_b128 v[18:21], v235 offset:2048
	ds_read_b128 v[22:25], v235 offset:3072
	ds_read_b128 v[10:13], v236
	ds_read_b128 v[14:17], v236 offset:1024
	ds_read_b128 v[2:5], v236 offset:2048
	ds_read_b128 v[6:9], v236 offset:3072
	s_add_i32 s68, s4, 2
	s_add_u32 s8, s0, 0xffdfc080
	s_addc_u32 s5, s1, -1
	s_cmp_eq_u32 s54, s4
	s_cselect_b32 s4, s12, s8
	s_cselect_b32 s5, s13, s5
	s_cselect_b32 s30, s28, s66
	s_cselect_b32 s31, s29, s67
	s_add_u32 s8, s4, 0x80
	s_addc_u32 s9, s5, 0
	ds_read_b128 v[182:185], v237
	ds_read_b128 v[186:189], v237 offset:1024
	ds_read_b128 v[190:193], v237 offset:2048
	ds_read_b128 v[194:197], v237 offset:3072
	ds_read_b128 v[198:201], v237 offset:4096
	ds_read_b128 v[202:205], v237 offset:5120
	ds_read_b128 v[206:209], v237 offset:6144
	ds_read_b128 v[210:213], v237 offset:7168
	s_add_u32 s70, s0, 0xfff54000
	s_addc_u32 s71, s1, -1
	s_mov_b32 m0, s55
	s_nop 0
	global_load_lds_dwordx4 v1, s[70:71]
	s_nop 0
	s_mov_b32 m0, s56
	s_nop 0
	global_load_lds_dwordx4 v1, s[0:1]
	s_waitcnt vmcnt(8)
	s_waitcnt lgkmcnt(0)
	s_barrier
	s_setprio 1
	s_waitcnt lgkmcnt(0)
	v_mfma_f32_16x16x128_f8f6f4 v[82:85], v[26:33], v[182:189], v[82:85]
	v_mfma_f32_16x16x128_f8f6f4 v[110:113], v[18:25], v[182:189], v[110:113]
	v_mfma_f32_16x16x128_f8f6f4 v[78:81], v[26:33], v[190:197], v[78:81]
	v_mfma_f32_16x16x128_f8f6f4 v[74:77], v[18:25], v[190:197], v[74:77]
	v_mfma_f32_16x16x128_f8f6f4 v[62:65], v[26:33], v[198:205], v[62:65]
	v_mfma_f32_16x16x128_f8f6f4 v[58:61], v[18:25], v[198:205], v[58:61]
	v_mfma_f32_16x16x128_f8f6f4 v[46:49], v[26:33], v[206:213], v[46:49]
	v_mfma_f32_16x16x128_f8f6f4 v[42:45], v[18:25], v[206:213], v[42:45]
	s_setprio 0
	s_setprio 1
	v_mfma_f32_16x16x128_f8f6f4 v[158:161], v[10:17], v[182:189], v[158:161]
	v_mfma_f32_16x16x128_f8f6f4 v[154:157], v[2:9], v[182:189], v[154:157]
	v_mfma_f32_16x16x128_f8f6f4 v[142:145], v[10:17], v[190:197], v[142:145]
	v_mfma_f32_16x16x128_f8f6f4 v[138:141], v[2:9], v[190:197], v[138:141]
	v_mfma_f32_16x16x128_f8f6f4 v[126:129], v[10:17], v[198:205], v[126:129]
	v_mfma_f32_16x16x128_f8f6f4 v[122:125], v[2:9], v[198:205], v[122:125]
	v_mfma_f32_16x16x128_f8f6f4 v[106:109], v[10:17], v[206:213], v[106:109]
	v_mfma_f32_16x16x128_f8f6f4 v[102:105], v[2:9], v[206:213], v[102:105]
	s_setprio 0
	s_add_u32 s70, s30, 0xac000
	s_barrier
	ds_read_b128 v[182:185], v237 offset:16384
	ds_read_b128 v[186:189], v237 offset:17408
	ds_read_b128 v[190:193], v237 offset:18432
	ds_read_b128 v[194:197], v237 offset:19456
	ds_read_b128 v[198:201], v237 offset:20480
	ds_read_b128 v[202:205], v237 offset:21504
	ds_read_b128 v[206:209], v237 offset:22528
	ds_read_b128 v[210:213], v237 offset:23552
	s_mov_b32 m0, s38
	s_nop 0
	global_load_lds_dwordx4 v169, s[30:31]
	s_addc_u32 s71, s31, 0
	s_mov_b32 m0, s39
	s_nop 0
	global_load_lds_dwordx4 v169, s[70:71]
	s_add_u32 s70, s30, 0x158000
	s_addc_u32 s71, s31, 0
	s_mov_b32 m0, s40
	s_nop 0
	global_load_lds_dwordx4 v169, s[70:71]
	s_add_u32 s70, s30, 0x204000
	s_addc_u32 s71, s31, 0
	s_mov_b32 m0, s41
	s_nop 0
	global_load_lds_dwordx4 v169, s[70:71]
	s_add_u32 s70, s4, 0xac000
	s_mov_b32 m0, s37
	s_nop 0
	global_load_lds_dwordx4 v1, s[4:5]
	s_addc_u32 s71, s5, 0
	s_mov_b32 m0, s42
	s_nop 0
	global_load_lds_dwordx4 v1, s[70:71]
	s_waitcnt vmcnt(8)
	s_waitcnt lgkmcnt(0)
	s_barrier
	s_setprio 1
	s_waitcnt lgkmcnt(6)
	v_mfma_f32_16x16x128_f8f6f4 v[98:101], v[26:33], v[182:189], v[98:101]
	v_mfma_f32_16x16x128_f8f6f4 v[94:97], v[18:25], v[182:189], v[94:97]
	s_waitcnt lgkmcnt(4)
	v_mfma_f32_16x16x128_f8f6f4 v[70:73], v[26:33], v[190:197], v[70:73]
	v_mfma_f32_16x16x128_f8f6f4 v[66:69], v[18:25], v[190:197], v[66:69]
	s_waitcnt lgkmcnt(2)
	v_mfma_f32_16x16x128_f8f6f4 v[54:57], v[26:33], v[198:205], v[54:57]
	v_mfma_f32_16x16x128_f8f6f4 v[50:53], v[18:25], v[198:205], v[50:53]
	s_waitcnt lgkmcnt(0)
	v_mfma_f32_16x16x128_f8f6f4 v[38:41], v[26:33], v[206:213], v[38:41]
	v_mfma_f32_16x16x128_f8f6f4 v[34:37], v[18:25], v[206:213], v[34:37]
	s_setprio 0
	s_setprio 1
	v_mfma_f32_16x16x128_f8f6f4 v[150:153], v[10:17], v[182:189], v[150:153]
	v_mfma_f32_16x16x128_f8f6f4 v[146:149], v[2:9], v[182:189], v[146:149]
	v_mfma_f32_16x16x128_f8f6f4 v[134:137], v[10:17], v[190:197], v[134:137]
	v_mfma_f32_16x16x128_f8f6f4 v[130:133], v[2:9], v[190:197], v[130:133]
	v_mfma_f32_16x16x128_f8f6f4 v[118:121], v[10:17], v[198:205], v[118:121]
	v_mfma_f32_16x16x128_f8f6f4 v[114:117], v[2:9], v[198:205], v[114:117]
	v_mfma_f32_16x16x128_f8f6f4 v[90:93], v[10:17], v[206:213], v[90:93]
	v_mfma_f32_16x16x128_f8f6f4 v[86:89], v[2:9], v[206:213], v[86:89]
	s_setprio 0
	s_barrier
	ds_read_b128 v[18:21], v238
	ds_read_b128 v[22:25], v238 offset:1024
	ds_read_b128 v[26:29], v238 offset:2048
	ds_read_b128 v[30:33], v238 offset:3072
	ds_read_b128 v[10:13], v239
	ds_read_b128 v[14:17], v239 offset:1024
	ds_read_b128 v[2:5], v239 offset:2048
	ds_read_b128 v[6:9], v239 offset:3072
	ds_read_b128 v[182:185], v237 offset:32768
	ds_read_b128 v[186:189], v237 offset:33792
	ds_read_b128 v[190:193], v237 offset:34816
	ds_read_b128 v[194:197], v237 offset:35840
	ds_read_b128 v[198:201], v237 offset:36864
	ds_read_b128 v[202:205], v237 offset:37888
	ds_read_b128 v[206:209], v237 offset:38912
	ds_read_b128 v[210:213], v237 offset:39936
	s_add_u32 s70, s4, 0x158000
	s_addc_u32 s71, s5, 0
	s_mov_b32 m0, s44
	s_nop 0
	global_load_lds_dwordx4 v1, s[70:71]
	s_add_u32 s70, s4, 0x204000
	s_addc_u32 s71, s5, 0
	s_mov_b32 m0, s45
	s_nop 0
	global_load_lds_dwordx4 v1, s[70:71]
	s_waitcnt vmcnt(8)
	s_waitcnt lgkmcnt(0)
	s_barrier
; #define PG8_STAGE(bufoff, gbase, X) do { _Pragma("unroll") for (int _i = 0; _i < 2; ++_i) { \
;         const char* gp_ = (const char*)(gbase) + (_i ? rs##X : (size_t)0); const unsigned la_ = (unsigned)(size_t)(lds + (bufoff) + ldsw + _i * 8192); \
;         asm volatile("s_mov_b32 m0, %2\n\ts_nop 0\n\tglobal_load_lds_dwordx4 %0, %1" :: "v"(voff##X), "s"(gp_), "s"(la_) : "memory", "m0"); } } while (0)
; #define PG8_LDA(dst, b, h) do { _Pragma("unroll") for (int m = 0; m < 4; ++m) _Pragma("unroll") for (int k = 0; k < 2; ++k) dst[m][k] = *(const LAS bf16x8*)(lds + PG8_SA(b, h) + aoff + m * 2048 + k * 1024); } while (0)
; #define PG8_WAIT_V(n) asm volatile("s_waitcnt vmcnt(" #n ")" ::: "memory")
; #define PG8_WAIT_L(n) asm volatile("s_waitcnt lgkmcnt(" #n ")" ::: "memory")
; #define PG8_BAR __builtin_amdgcn_s_barrier()
; #define PG8_SCHED __builtin_amdgcn_sched_barrier(0)
; template <class Epi>
; __device__ __forceinline__ void gemm_phase(LAS unsigned char* lds, const Gemm g_in, const StaticOrder& S, const Epi& E) {
;     ...
;             PG8_WAIT_V(8); PG8_WAIT_L(0); PG8_BAR; PG8_MMA(0, 0, At, B0); PG8_MMA(0, 1, At, B1); PG8_BAR; PG8_SCHED;
;             PG8_LDA(At, 1, 1); PG8_STAGE(PG8_SB(1, 0), b3, B); PG8_STAGE(PG8_SB(1, 1), b3 + hsB, B); PG8_STAGE(PG8_SA(1, 0), a3, A);
;             PG8_WAIT_V(8); PG8_WAIT_L(0); PG8_BAR; PG8_MMA(1, 0, At, B0); PG8_MMA(1, 1, At, B1); PG8_BAR; PG8_SCHED;
;         }
	s_setprio 1
	s_waitcnt lgkmcnt(6)
	v_mfma_f32_16x16x128_f8f6f4 v[82:85], v[18:25], v[182:189], v[82:85]
	v_mfma_f32_16x16x128_f8f6f4 v[110:113], v[26:33], v[182:189], v[110:113]
	s_waitcnt lgkmcnt(4)
	v_mfma_f32_16x16x128_f8f6f4 v[78:81], v[18:25], v[190:197], v[78:81]
	v_mfma_f32_16x16x128_f8f6f4 v[74:77], v[26:33], v[190:197], v[74:77]
	s_waitcnt lgkmcnt(2)
	v_mfma_f32_16x16x128_f8f6f4 v[62:65], v[18:25], v[198:205], v[62:65]
	v_mfma_f32_16x16x128_f8f6f4 v[58:61], v[26:33], v[198:205], v[58:61]
	s_waitcnt lgkmcnt(0)
	v_mfma_f32_16x16x128_f8f6f4 v[46:49], v[18:25], v[206:213], v[46:49]
	v_mfma_f32_16x16x128_f8f6f4 v[42:45], v[26:33], v[206:213], v[42:45]
	s_setprio 0
	s_setprio 1
	v_mfma_f32_16x16x128_f8f6f4 v[158:161], v[10:17], v[182:189], v[158:161]
	v_mfma_f32_16x16x128_f8f6f4 v[154:157], v[2:9], v[182:189], v[154:157]
	v_mfma_f32_16x16x128_f8f6f4 v[142:145], v[10:17], v[190:197], v[142:145]
	v_mfma_f32_16x16x128_f8f6f4 v[138:141], v[2:9], v[190:197], v[138:141]
	v_mfma_f32_16x16x128_f8f6f4 v[126:129], v[10:17], v[198:205], v[126:129]
	v_mfma_f32_16x16x128_f8f6f4 v[122:125], v[2:9], v[198:205], v[122:125]
	v_mfma_f32_16x16x128_f8f6f4 v[106:109], v[10:17], v[206:213], v[106:109]
	v_mfma_f32_16x16x128_f8f6f4 v[102:105], v[2:9], v[206:213], v[102:105]
	s_setprio 0
	s_add_u32 s70, s30, 0x80
	s_addc_u32 s71, s31, 0
	s_barrier
	ds_read_b128 v[182:185], v237 offset:49152
	ds_read_b128 v[186:189], v237 offset:50176
	ds_read_b128 v[190:193], v237 offset:51200
	ds_read_b128 v[194:197], v237 offset:52224
	ds_read_b128 v[198:201], v237 offset:53248
	ds_read_b128 v[202:205], v237 offset:54272
	ds_read_b128 v[206:209], v237 offset:55296
	ds_read_b128 v[210:213], v237 offset:56320
	s_mov_b32 m0, s46
	s_nop 0
	global_load_lds_dwordx4 v169, s[70:71]
	s_add_u32 s70, s30, 0xac080
	s_addc_u32 s71, s31, 0
	s_mov_b32 m0, s47
	s_nop 0
	global_load_lds_dwordx4 v169, s[70:71]
	s_add_u32 s70, s30, 0x158080
	s_addc_u32 s71, s31, 0
	s_mov_b32 m0, s52
	s_nop 0
	global_load_lds_dwordx4 v169, s[70:71]
	s_add_u32 s30, s30, 0x204080
	s_addc_u32 s31, s31, 0
	s_mov_b32 m0, s53
	s_nop 0
	global_load_lds_dwordx4 v169, s[30:31]
	s_add_u32 s4, s4, 0xac080
	s_mov_b32 m0, s50
	s_nop 0
	global_load_lds_dwordx4 v1, s[8:9]
	s_addc_u32 s5, s5, 0
	s_mov_b32 m0, s51
	s_nop 0
	global_load_lds_dwordx4 v1, s[4:5]
	s_waitcnt vmcnt(8)
	s_waitcnt lgkmcnt(0)
	s_barrier
	s_setprio 1
	s_waitcnt lgkmcnt(6)
	v_mfma_f32_16x16x128_f8f6f4 v[98:101], v[18:25], v[182:189], v[98:101]
	v_mfma_f32_16x16x128_f8f6f4 v[94:97], v[26:33], v[182:189], v[94:97]
	s_waitcnt lgkmcnt(4)
	v_mfma_f32_16x16x128_f8f6f4 v[70:73], v[18:25], v[190:197], v[70:73]
	v_mfma_f32_16x16x128_f8f6f4 v[66:69], v[26:33], v[190:197], v[66:69]
	s_waitcnt lgkmcnt(2)
	v_mfma_f32_16x16x128_f8f6f4 v[54:57], v[18:25], v[198:205], v[54:57]
	v_mfma_f32_16x16x128_f8f6f4 v[50:53], v[26:33], v[198:205], v[50:53]
	s_waitcnt lgkmcnt(0)
	v_mfma_f32_16x16x128_f8f6f4 v[38:41], v[18:25], v[206:213], v[38:41]
	v_mfma_f32_16x16x128_f8f6f4 v[34:37], v[26:33], v[206:213], v[34:37]
	s_setprio 0
	s_setprio 1
	v_mfma_f32_16x16x128_f8f6f4 v[150:153], v[10:17], v[182:189], v[150:153]
	v_mfma_f32_16x16x128_f8f6f4 v[146:149], v[2:9], v[182:189], v[146:149]
	v_mfma_f32_16x16x128_f8f6f4 v[134:137], v[10:17], v[190:197], v[134:137]
	v_mfma_f32_16x16x128_f8f6f4 v[130:133], v[2:9], v[190:197], v[130:133]
	v_mfma_f32_16x16x128_f8f6f4 v[118:121], v[10:17], v[198:205], v[118:121]
	v_mfma_f32_16x16x128_f8f6f4 v[114:117], v[2:9], v[198:205], v[114:117]
	v_mfma_f32_16x16x128_f8f6f4 v[90:93], v[10:17], v[206:213], v[90:93]
	v_mfma_f32_16x16x128_f8f6f4 v[86:89], v[2:9], v[206:213], v[86:89]
	s_setprio 0
	s_add_u32 s66, s66, 0x100
	s_addc_u32 s67, s67, 0
	s_add_u32 s0, s0, 0x100
	s_addc_u32 s1, s1, 0
	s_cmp_ge_i32 s68, s35
	s_mov_b32 s4, s68
	s_barrier
	s_cbranch_scc0 .LBB0_238
;     __device__ __forceinline__ void operator()(const f32x4 (&acc)[2][2][4][2], const Unit& u, int wr, int wc, int fr, int fq) const {
;     ...
;                     for (int bj = 0; bj < 2; ++bj) { f32x4 a0 = acc[ai][bj][m][0], a1 = acc[ai][bj][m][1];
;                         if (IN == 2) { a0 = __builtin_convertvector(__builtin_bit_cast(i32x4, a0), f32x4); a1 = __builtin_convertvector(__builtin_bit_cast(i32x4, a1), f32x4); }
;                         const f32x4 v0 = bv[m][bj][0] * ALPHA + a0 * scale, v1 = bv[m][bj][1] * ALPHA + a1 * scale;
	v_pk_mul_f32 v[232:233], v[84:85], s[24:25] op_sel_hi:[1,0]
	v_pk_mul_f32 v[230:231], v[82:83], s[24:25] op_sel_hi:[1,0]
	v_pk_mul_f32 v[228:229], v[112:113], s[24:25] op_sel_hi:[1,0]
	v_pk_mul_f32 v[226:227], v[110:111], s[24:25] op_sel_hi:[1,0]
	v_pk_mul_f32 v[220:221], v[160:161], s[24:25] op_sel_hi:[1,0]
	v_pk_mul_f32 v[218:219], v[158:159], s[24:25] op_sel_hi:[1,0]
	v_pk_mul_f32 v[214:215], v[156:157], s[24:25] op_sel_hi:[1,0]
	v_pk_mul_f32 v[210:211], v[154:155], s[24:25] op_sel_hi:[1,0]
	v_pk_mul_f32 v[224:225], v[80:81], s[24:25] op_sel_hi:[1,0]
	v_pk_mul_f32 v[222:223], v[78:79], s[24:25] op_sel_hi:[1,0]
	v_pk_mul_f32 v[216:217], v[76:77], s[24:25] op_sel_hi:[1,0]
	v_pk_mul_f32 v[212:213], v[74:75], s[24:25] op_sel_hi:[1,0]
	v_pk_mul_f32 v[204:205], v[144:145], s[24:25] op_sel_hi:[1,0]
	v_pk_mul_f32 v[202:203], v[142:143], s[24:25] op_sel_hi:[1,0]
	v_pk_mul_f32 v[198:199], v[140:141], s[24:25] op_sel_hi:[1,0]
	v_pk_mul_f32 v[194:195], v[138:139], s[24:25] op_sel_hi:[1,0]
	v_pk_mul_f32 v[208:209], v[64:65], s[24:25] op_sel_hi:[1,0]
	v_pk_mul_f32 v[206:207], v[62:63], s[24:25] op_sel_hi:[1,0]
	v_pk_mul_f32 v[200:201], v[60:61], s[24:25] op_sel_hi:[1,0]
	v_pk_mul_f32 v[196:197], v[58:59], s[24:25] op_sel_hi:[1,0]
	v_pk_mul_f32 v[192:193], v[128:129], s[24:25] op_sel_hi:[1,0]
	v_pk_mul_f32 v[190:191], v[126:127], s[24:25] op_sel_hi:[1,0]
	v_pk_mul_f32 v[188:189], v[124:125], s[24:25] op_sel_hi:[1,0]
	v_pk_mul_f32 v[186:187], v[122:123], s[24:25] op_sel_hi:[1,0]
	v_pk_mul_f32 v[184:185], v[48:49], s[24:25] op_sel_hi:[1,0]
	v_pk_mul_f32 v[182:183], v[46:47], s[24:25] op_sel_hi:[1,0]
	v_pk_mul_f32 v[160:161], v[44:45], s[24:25] op_sel_hi:[1,0]
	v_pk_mul_f32 v[158:159], v[42:43], s[24:25] op_sel_hi:[1,0]
	v_pk_mul_f32 v[156:157], v[108:109], s[24:25] op_sel_hi:[1,0]
	v_pk_mul_f32 v[154:155], v[106:107], s[24:25] op_sel_hi:[1,0]
	v_pk_mul_f32 v[144:145], v[104:105], s[24:25] op_sel_hi:[1,0]
	v_pk_mul_f32 v[142:143], v[102:103], s[24:25] op_sel_hi:[1,0]
	v_pk_mul_f32 v[140:141], v[100:101], s[24:25] op_sel_hi:[1,0]
	v_pk_mul_f32 v[138:139], v[98:99], s[24:25] op_sel_hi:[1,0]
	v_pk_mul_f32 v[128:129], v[96:97], s[24:25] op_sel_hi:[1,0]
	v_pk_mul_f32 v[126:127], v[94:95], s[24:25] op_sel_hi:[1,0]
	v_pk_mul_f32 v[112:113], v[152:153], s[24:25] op_sel_hi:[1,0]
	v_pk_mul_f32 v[110:111], v[150:151], s[24:25] op_sel_hi:[1,0]
	v_pk_mul_f32 v[106:107], v[148:149], s[24:25] op_sel_hi:[1,0]
	v_pk_mul_f32 v[102:103], v[146:147], s[24:25] op_sel_hi:[1,0]
	v_pk_mul_f32 v[124:125], v[72:73], s[24:25] op_sel_hi:[1,0]
	v_pk_mul_f32 v[122:123], v[70:71], s[24:25] op_sel_hi:[1,0]
	v_pk_mul_f32 v[108:109], v[68:69], s[24:25] op_sel_hi:[1,0]
	v_pk_mul_f32 v[104:105], v[66:67], s[24:25] op_sel_hi:[1,0]
	v_pk_mul_f32 v[96:97], v[136:137], s[24:25] op_sel_hi:[1,0]
	v_pk_mul_f32 v[94:95], v[134:135], s[24:25] op_sel_hi:[1,0]
	v_pk_mul_f32 v[82:83], v[132:133], s[24:25] op_sel_hi:[1,0]
	v_pk_mul_f32 v[78:79], v[130:131], s[24:25] op_sel_hi:[1,0]
	v_pk_mul_f32 v[100:101], v[56:57], s[24:25] op_sel_hi:[1,0]
	v_pk_mul_f32 v[98:99], v[54:55], s[24:25] op_sel_hi:[1,0]
	v_pk_mul_f32 v[84:85], v[52:53], s[24:25] op_sel_hi:[1,0]
	v_pk_mul_f32 v[80:81], v[50:51], s[24:25] op_sel_hi:[1,0]
	v_pk_mul_f32 v[76:77], v[120:121], s[24:25] op_sel_hi:[1,0]
	v_pk_mul_f32 v[74:75], v[118:119], s[24:25] op_sel_hi:[1,0]
	v_pk_mul_f32 v[72:73], v[116:117], s[24:25] op_sel_hi:[1,0]
	v_pk_mul_f32 v[70:71], v[114:115], s[24:25] op_sel_hi:[1,0]
	v_pk_mul_f32 v[68:69], v[40:41], s[24:25] op_sel_hi:[1,0]
	v_pk_mul_f32 v[66:67], v[38:39], s[24:25] op_sel_hi:[1,0]
	v_pk_mul_f32 v[64:65], v[36:37], s[24:25] op_sel_hi:[1,0]
	v_pk_mul_f32 v[62:63], v[34:35], s[24:25] op_sel_hi:[1,0]
	v_pk_mul_f32 v[60:61], v[92:93], s[24:25] op_sel_hi:[1,0]
	v_pk_mul_f32 v[58:59], v[90:91], s[24:25] op_sel_hi:[1,0]
	v_pk_mul_f32 v[56:57], v[88:89], s[24:25] op_sel_hi:[1,0]
	v_pk_mul_f32 v[54:55], v[86:87], s[24:25] op_sel_hi:[1,0]
	s_and_b64 vcc, exec, s[22:23]
	s_cbranch_vccz .LBB0_241

; #define PG8_STAGE(bufoff, gbase, X) do { _Pragma("unroll") for (int _i = 0; _i < 2; ++_i) { \
;         const char* gp_ = (const char*)(gbase) + (_i ? rs##X : (size_t)0); const unsigned la_ = (unsigned)(size_t)(lds + (bufoff) + ldsw + _i * 8192); \
;         asm volatile("s_mov_b32 m0, %2\n\ts_nop 0\n\tglobal_load_lds_dwordx4 %0, %1" :: "v"(voff##X), "s"(gp_), "s"(la_) : "memory", "m0"); } } while (0)
; #define PG8_LDA(dst, b, h) do { _Pragma("unroll") for (int m = 0; m < 4; ++m) _Pragma("unroll") for (int k = 0; k < 2; ++k) dst[m][k] = *(const LAS bf16x8*)(lds + PG8_SA(b, h) + aoff + m * 2048 + k * 1024); } while (0)
; #define PG8_LDB(dst, b, h) do { _Pragma("unroll") for (int n = 0; n < 2; ++n) _Pragma("unroll") for (int k = 0; k < 2; ++k) dst[n][k] = *(const LAS bf16x8*)(lds + PG8_SB(b, h) + boff + n * 2048 + k * 1024); } while (0)
; #define PG8_WAIT_V(n) asm volatile("s_waitcnt vmcnt(" #n ")" ::: "memory")
; #define PG8_WAIT_L(n) asm volatile("s_waitcnt lgkmcnt(" #n ")" ::: "memory")
; #define PG8_BAR __builtin_amdgcn_s_barrier()
; #define PG8_SCHED __builtin_amdgcn_sched_barrier(0)
; template <class Epi>
; __device__ __forceinline__ void gemm_phase(LAS unsigned char* lds, const Gemm g_in, const StaticOrder& S, const Epi& E) {
;     ...
;             const bool last = (t == nt - 2);
;             const char* a1 = cA + (size_t)(t + 1) * kstep;
;             const char* a2 = last ? nA : cA + (size_t)(t + 2) * kstep; const char* b2 = last ? nB : cB + (size_t)(t + 2) * kstep;
;             const char* a3 = a2 + kstep; const char* b3 = b2 + kstep;
;             PG8_LDB(B0, 0, 0); PG8_LDB(B1, 0, 1); PG8_SCHED; PG8_LDA(At, 0, 0); PG8_STAGE(PG8_SA(1, 1), a1 + hsA, A);
;             PG8_WAIT_V(8); PG8_WAIT_L(0); PG8_BAR; PG8_MMA(0, 0, At, B0); PG8_MMA(0, 1, At, B1); PG8_BAR; PG8_SCHED;
;             PG8_LDA(At, 0, 1); PG8_STAGE(PG8_SB(0, 0), b2, B); PG8_STAGE(PG8_SB(0, 1), b2 + hsB, B); PG8_STAGE(PG8_SA(0, 0), a2, A);
.LBB0_388:
	ds_read_b128 v[142:145], v137
	ds_read_b128 v[146:149], v137 offset:1024
	ds_read_b128 v[150:153], v137 offset:2048
	ds_read_b128 v[154:157], v137 offset:3072
	ds_read_b128 v[158:161], v138
	ds_read_b128 v[170:173], v138 offset:1024
	ds_read_b128 v[174:177], v138 offset:2048
	ds_read_b128 v[184:187], v138 offset:3072
	s_add_i32 s62, s22, 2
	s_add_u32 s24, s20, 0xffe80080
	s_addc_u32 s23, s21, -1
	s_cmp_eq_u32 s54, s22
	s_cselect_b32 s22, s15, s24
	s_cselect_b32 s23, s13, s23
	s_cselect_b32 s26, s59, s60
	s_cselect_b32 s27, s58, s61
	s_add_u32 s24, s22, 0x80
	s_addc_u32 s25, s23, 0
	ds_read_b128 v[188:191], v139
	ds_read_b128 v[192:195], v139 offset:1024
	ds_read_b128 v[196:199], v139 offset:2048
	ds_read_b128 v[204:207], v139 offset:3072
	ds_read_b128 v[208:211], v139 offset:4096
	ds_read_b128 v[212:215], v139 offset:5120
	ds_read_b128 v[216:219], v139 offset:6144
	ds_read_b128 v[220:223], v139 offset:7168
	s_add_u32 s64, s20, 0xfff80000
	s_addc_u32 s65, s21, -1
	s_mov_b32 m0, s55
	s_nop 0
	global_load_lds_dwordx4 v1, s[64:65]
	s_nop 0
	s_mov_b32 m0, s56
	s_nop 0
	global_load_lds_dwordx4 v1, s[20:21]
	s_waitcnt vmcnt(8)
	s_waitcnt lgkmcnt(0)
	s_barrier
	s_setprio 1
	s_waitcnt lgkmcnt(7)
	v_mfma_f32_16x16x32_bf16 v[126:129], v[142:145], v[188:191], v[126:129]
	v_mfma_f32_16x16x32_bf16 v[122:125], v[150:153], v[188:191], v[122:125]
	s_waitcnt lgkmcnt(5)
	v_mfma_f32_16x16x32_bf16 v[110:113], v[142:145], v[196:199], v[110:113]
	v_mfma_f32_16x16x32_bf16 v[106:109], v[150:153], v[196:199], v[106:109]
	s_waitcnt lgkmcnt(3)
	v_mfma_f32_16x16x32_bf16 v[94:97], v[142:145], v[208:211], v[94:97]
	v_mfma_f32_16x16x32_bf16 v[90:93], v[150:153], v[208:211], v[90:93]
	s_waitcnt lgkmcnt(1)
	v_mfma_f32_16x16x32_bf16 v[78:81], v[142:145], v[216:219], v[78:81]
	v_mfma_f32_16x16x32_bf16 v[74:77], v[150:153], v[216:219], v[74:77]
	v_mfma_f32_16x16x32_bf16 v[126:129], v[146:149], v[192:195], v[126:129]
	v_mfma_f32_16x16x32_bf16 v[122:125], v[154:157], v[192:195], v[122:125]
	v_mfma_f32_16x16x32_bf16 v[110:113], v[146:149], v[204:207], v[110:113]
	v_mfma_f32_16x16x32_bf16 v[106:109], v[154:157], v[204:207], v[106:109]
	v_mfma_f32_16x16x32_bf16 v[94:97], v[146:149], v[212:215], v[94:97]
	v_mfma_f32_16x16x32_bf16 v[90:93], v[154:157], v[212:215], v[90:93]
	s_waitcnt lgkmcnt(0)
	v_mfma_f32_16x16x32_bf16 v[78:81], v[146:149], v[220:223], v[78:81]
	v_mfma_f32_16x16x32_bf16 v[74:77], v[154:157], v[220:223], v[74:77]
	s_setprio 0
	s_setprio 1
	v_mfma_f32_16x16x32_bf16 v[118:121], v[158:161], v[188:191], v[118:121]
	v_mfma_f32_16x16x32_bf16 v[114:117], v[174:177], v[188:191], v[114:117]
	v_mfma_f32_16x16x32_bf16 v[102:105], v[158:161], v[196:199], v[102:105]
	v_mfma_f32_16x16x32_bf16 v[98:101], v[174:177], v[196:199], v[98:101]
	v_mfma_f32_16x16x32_bf16 v[86:89], v[158:161], v[208:211], v[86:89]
	v_mfma_f32_16x16x32_bf16 v[82:85], v[174:177], v[208:211], v[82:85]
	v_mfma_f32_16x16x32_bf16 v[70:73], v[158:161], v[216:219], v[70:73]
	v_mfma_f32_16x16x32_bf16 v[66:69], v[174:177], v[216:219], v[66:69]
	v_mfma_f32_16x16x32_bf16 v[118:121], v[170:173], v[192:195], v[118:121]
	v_mfma_f32_16x16x32_bf16 v[114:117], v[184:187], v[192:195], v[114:117]
	v_mfma_f32_16x16x32_bf16 v[102:105], v[170:173], v[204:207], v[102:105]
	v_mfma_f32_16x16x32_bf16 v[98:101], v[184:187], v[204:207], v[98:101]
	v_mfma_f32_16x16x32_bf16 v[86:89], v[170:173], v[212:215], v[86:89]
	v_mfma_f32_16x16x32_bf16 v[82:85], v[184:187], v[212:215], v[82:85]
	v_mfma_f32_16x16x32_bf16 v[70:73], v[170:173], v[220:223], v[70:73]
	v_mfma_f32_16x16x32_bf16 v[66:69], v[184:187], v[220:223], v[66:69]
	s_setprio 0
	s_add_u32 s64, s26, 0x80000
	s_barrier
	ds_read_b128 v[188:191], v139 offset:16384
	ds_read_b128 v[192:195], v139 offset:17408
	ds_read_b128 v[196:199], v139 offset:18432
	ds_read_b128 v[204:207], v139 offset:19456
	ds_read_b128 v[208:211], v139 offset:20480
	ds_read_b128 v[212:215], v139 offset:21504
	ds_read_b128 v[216:219], v139 offset:22528
	ds_read_b128 v[220:223], v139 offset:23552
	s_mov_b32 m0, s37
	s_nop 0
	global_load_lds_dwordx4 v134, s[26:27]
	s_addc_u32 s65, s27, 0
	s_mov_b32 m0, s38
	s_nop 0
	global_load_lds_dwordx4 v134, s[64:65]
	s_add_u32 s64, s26, 0x100000
	s_addc_u32 s65, s27, 0
	s_mov_b32 m0, s39
	s_nop 0
	global_load_lds_dwordx4 v134, s[64:65]
	s_add_u32 s64, s26, 0x180000
	s_addc_u32 s65, s27, 0
	s_mov_b32 m0, s40
	s_nop 0
	global_load_lds_dwordx4 v134, s[64:65]
	s_add_u32 s64, s22, 0x80000
	s_mov_b32 m0, s36
	s_nop 0
	global_load_lds_dwordx4 v1, s[22:23]
	s_addc_u32 s65, s23, 0
	s_mov_b32 m0, s41
	s_nop 0
	global_load_lds_dwordx4 v1, s[64:65]
	s_waitcnt vmcnt(8)
	s_waitcnt lgkmcnt(0)
	s_barrier
; #define PG8_STAGE(bufoff, gbase, X) do { _Pragma("unroll") for (int _i = 0; _i < 2; ++_i) { \
;         const char* gp_ = (const char*)(gbase) + (_i ? rs##X : (size_t)0); const unsigned la_ = (unsigned)(size_t)(lds + (bufoff) + ldsw + _i * 8192); \
;         asm volatile("s_mov_b32 m0, %2\n\ts_nop 0\n\tglobal_load_lds_dwordx4 %0, %1" :: "v"(voff##X), "s"(gp_), "s"(la_) : "memory", "m0"); } } while (0)
; #define PG8_LDA(dst, b, h) do { _Pragma("unroll") for (int m = 0; m < 4; ++m) _Pragma("unroll") for (int k = 0; k < 2; ++k) dst[m][k] = *(const LAS bf16x8*)(lds + PG8_SA(b, h) + aoff + m * 2048 + k * 1024); } while (0)
; #define PG8_LDB(dst, b, h) do { _Pragma("unroll") for (int n = 0; n < 2; ++n) _Pragma("unroll") for (int k = 0; k < 2; ++k) dst[n][k] = *(const LAS bf16x8*)(lds + PG8_SB(b, h) + boff + n * 2048 + k * 1024); } while (0)
; #define PG8_WAIT_V(n) asm volatile("s_waitcnt vmcnt(" #n ")" ::: "memory")
; #define PG8_WAIT_L(n) asm volatile("s_waitcnt lgkmcnt(" #n ")" ::: "memory")
; #define PG8_BAR __builtin_amdgcn_s_barrier()
; #define PG8_SCHED __builtin_amdgcn_sched_barrier(0)
; template <class Epi>
; __device__ __forceinline__ void gemm_phase(LAS unsigned char* lds, const Gemm g_in, const StaticOrder& S, const Epi& E) {
;     ...
;             PG8_WAIT_V(8); PG8_WAIT_L(0); PG8_BAR; PG8_MMA(1, 0, At, B0); PG8_MMA(1, 1, At, B1); PG8_BAR; PG8_SCHED;
;             PG8_LDB(B0, 1, 0); PG8_LDB(B1, 1, 1); PG8_SCHED; PG8_LDA(At, 1, 0); PG8_STAGE(PG8_SA(0, 1), a2 + hsA, A);
;             PG8_WAIT_V(8); PG8_WAIT_L(0); PG8_BAR; PG8_MMA(0, 0, At, B0); PG8_MMA(0, 1, At, B1); PG8_BAR; PG8_SCHED;
	s_setprio 1
	s_waitcnt lgkmcnt(7)
	v_mfma_f32_16x16x32_bf16 v[62:65], v[142:145], v[188:191], v[62:65]
	v_mfma_f32_16x16x32_bf16 v[58:61], v[150:153], v[188:191], v[58:61]
	s_waitcnt lgkmcnt(5)
	v_mfma_f32_16x16x32_bf16 v[46:49], v[142:145], v[196:199], v[46:49]
	v_mfma_f32_16x16x32_bf16 v[42:45], v[150:153], v[196:199], v[42:45]
	s_waitcnt lgkmcnt(3)
	v_mfma_f32_16x16x32_bf16 v[30:33], v[142:145], v[208:211], v[30:33]
	v_mfma_f32_16x16x32_bf16 v[26:29], v[150:153], v[208:211], v[26:29]
	s_waitcnt lgkmcnt(1)
	v_mfma_f32_16x16x32_bf16 v[14:17], v[142:145], v[216:219], v[14:17]
	v_mfma_f32_16x16x32_bf16 v[10:13], v[150:153], v[216:219], v[10:13]
	v_mfma_f32_16x16x32_bf16 v[62:65], v[146:149], v[192:195], v[62:65]
	v_mfma_f32_16x16x32_bf16 v[58:61], v[154:157], v[192:195], v[58:61]
	v_mfma_f32_16x16x32_bf16 v[46:49], v[146:149], v[204:207], v[46:49]
	v_mfma_f32_16x16x32_bf16 v[42:45], v[154:157], v[204:207], v[42:45]
	v_mfma_f32_16x16x32_bf16 v[30:33], v[146:149], v[212:215], v[30:33]
	v_mfma_f32_16x16x32_bf16 v[26:29], v[154:157], v[212:215], v[26:29]
	s_waitcnt lgkmcnt(0)
	v_mfma_f32_16x16x32_bf16 v[14:17], v[146:149], v[220:223], v[14:17]
	v_mfma_f32_16x16x32_bf16 v[10:13], v[154:157], v[220:223], v[10:13]
	s_setprio 0
	s_setprio 1
	v_mfma_f32_16x16x32_bf16 v[54:57], v[158:161], v[188:191], v[54:57]
	v_mfma_f32_16x16x32_bf16 v[50:53], v[174:177], v[188:191], v[50:53]
	v_mfma_f32_16x16x32_bf16 v[38:41], v[158:161], v[196:199], v[38:41]
	v_mfma_f32_16x16x32_bf16 v[34:37], v[174:177], v[196:199], v[34:37]
	v_mfma_f32_16x16x32_bf16 v[22:25], v[158:161], v[208:211], v[22:25]
	v_mfma_f32_16x16x32_bf16 v[18:21], v[174:177], v[208:211], v[18:21]
	v_mfma_f32_16x16x32_bf16 v[6:9], v[158:161], v[216:219], v[6:9]
	v_mfma_f32_16x16x32_bf16 v[2:5], v[174:177], v[216:219], v[2:5]
	v_mfma_f32_16x16x32_bf16 v[54:57], v[170:173], v[192:195], v[54:57]
	v_mfma_f32_16x16x32_bf16 v[50:53], v[184:187], v[192:195], v[50:53]
	v_mfma_f32_16x16x32_bf16 v[38:41], v[170:173], v[204:207], v[38:41]
	v_mfma_f32_16x16x32_bf16 v[34:37], v[184:187], v[204:207], v[34:37]
	v_mfma_f32_16x16x32_bf16 v[22:25], v[170:173], v[212:215], v[22:25]
	v_mfma_f32_16x16x32_bf16 v[18:21], v[184:187], v[212:215], v[18:21]
	v_mfma_f32_16x16x32_bf16 v[6:9], v[170:173], v[220:223], v[6:9]
	v_mfma_f32_16x16x32_bf16 v[2:5], v[184:187], v[220:223], v[2:5]
	s_setprio 0
	s_barrier
	ds_read_b128 v[142:145], v140
	ds_read_b128 v[146:149], v140 offset:1024
	ds_read_b128 v[150:153], v140 offset:2048
	ds_read_b128 v[154:157], v140 offset:3072
	ds_read_b128 v[158:161], v141
	ds_read_b128 v[170:173], v141 offset:1024
	ds_read_b128 v[174:177], v141 offset:2048
	ds_read_b128 v[184:187], v141 offset:3072
	ds_read_b128 v[188:191], v139 offset:32768
	ds_read_b128 v[192:195], v139 offset:33792
	ds_read_b128 v[196:199], v139 offset:34816
	ds_read_b128 v[204:207], v139 offset:35840
	ds_read_b128 v[208:211], v139 offset:36864
	ds_read_b128 v[212:215], v139 offset:37888
	ds_read_b128 v[216:219], v139 offset:38912
	ds_read_b128 v[220:223], v139 offset:39936
	s_add_u32 s64, s22, 0x100000
	s_addc_u32 s65, s23, 0
	s_mov_b32 m0, s42
	s_nop 0
	global_load_lds_dwordx4 v1, s[64:65]
	s_add_u32 s64, s22, 0x180000
	s_addc_u32 s65, s23, 0
	s_mov_b32 m0, s43
	s_nop 0
	global_load_lds_dwordx4 v1, s[64:65]
	s_waitcnt vmcnt(8)
	s_waitcnt lgkmcnt(0)
	s_barrier
	s_setprio 1
	s_waitcnt lgkmcnt(7)
	v_mfma_f32_16x16x32_bf16 v[126:129], v[142:145], v[188:191], v[126:129]
	v_mfma_f32_16x16x32_bf16 v[122:125], v[150:153], v[188:191], v[122:125]
	s_waitcnt lgkmcnt(5)
	v_mfma_f32_16x16x32_bf16 v[110:113], v[142:145], v[196:199], v[110:113]
	v_mfma_f32_16x16x32_bf16 v[106:109], v[150:153], v[196:199], v[106:109]
	s_waitcnt lgkmcnt(3)
	v_mfma_f32_16x16x32_bf16 v[94:97], v[142:145], v[208:211], v[94:97]
	v_mfma_f32_16x16x32_bf16 v[90:93], v[150:153], v[208:211], v[90:93]
	s_waitcnt lgkmcnt(1)
	v_mfma_f32_16x16x32_bf16 v[78:81], v[142:145], v[216:219], v[78:81]
	v_mfma_f32_16x16x32_bf16 v[74:77], v[150:153], v[216:219], v[74:77]
	v_mfma_f32_16x16x32_bf16 v[126:129], v[146:149], v[192:195], v[126:129]
	v_mfma_f32_16x16x32_bf16 v[122:125], v[154:157], v[192:195], v[122:125]
	v_mfma_f32_16x16x32_bf16 v[110:113], v[146:149], v[204:207], v[110:113]
	v_mfma_f32_16x16x32_bf16 v[106:109], v[154:157], v[204:207], v[106:109]
	v_mfma_f32_16x16x32_bf16 v[94:97], v[146:149], v[212:215], v[94:97]
	v_mfma_f32_16x16x32_bf16 v[90:93], v[154:157], v[212:215], v[90:93]
	s_waitcnt lgkmcnt(0)
	v_mfma_f32_16x16x32_bf16 v[78:81], v[146:149], v[220:223], v[78:81]
	v_mfma_f32_16x16x32_bf16 v[74:77], v[154:157], v[220:223], v[74:77]
	s_setprio 0
	s_setprio 1
	v_mfma_f32_16x16x32_bf16 v[118:121], v[158:161], v[188:191], v[118:121]
	v_mfma_f32_16x16x32_bf16 v[114:117], v[174:177], v[188:191], v[114:117]
	v_mfma_f32_16x16x32_bf16 v[102:105], v[158:161], v[196:199], v[102:105]
	v_mfma_f32_16x16x32_bf16 v[98:101], v[174:177], v[196:199], v[98:101]
	v_mfma_f32_16x16x32_bf16 v[86:89], v[158:161], v[208:211], v[86:89]
	v_mfma_f32_16x16x32_bf16 v[82:85], v[174:177], v[208:211], v[82:85]
	v_mfma_f32_16x16x32_bf16 v[70:73], v[158:161], v[216:219], v[70:73]
	v_mfma_f32_16x16x32_bf16 v[66:69], v[174:177], v[216:219], v[66:69]
	v_mfma_f32_16x16x32_bf16 v[118:121], v[170:173], v[192:195], v[118:121]
	v_mfma_f32_16x16x32_bf16 v[114:117], v[184:187], v[192:195], v[114:117]
	v_mfma_f32_16x16x32_bf16 v[102:105], v[170:173], v[204:207], v[102:105]
	v_mfma_f32_16x16x32_bf16 v[98:101], v[184:187], v[204:207], v[98:101]
	v_mfma_f32_16x16x32_bf16 v[86:89], v[170:173], v[212:215], v[86:89]
	v_mfma_f32_16x16x32_bf16 v[82:85], v[184:187], v[212:215], v[82:85]
	v_mfma_f32_16x16x32_bf16 v[70:73], v[170:173], v[220:223], v[70:73]
	v_mfma_f32_16x16x32_bf16 v[66:69], v[184:187], v[220:223], v[66:69]
	s_setprio 0
	s_add_u32 s64, s26, 0x80
	s_addc_u32 s65, s27, 0
	s_barrier
; #define PG8_STAGE(bufoff, gbase, X) do { _Pragma("unroll") for (int _i = 0; _i < 2; ++_i) { \
;         const char* gp_ = (const char*)(gbase) + (_i ? rs##X : (size_t)0); const unsigned la_ = (unsigned)(size_t)(lds + (bufoff) + ldsw + _i * 8192); \
;         asm volatile("s_mov_b32 m0, %2\n\ts_nop 0\n\tglobal_load_lds_dwordx4 %0, %1" :: "v"(voff##X), "s"(gp_), "s"(la_) : "memory", "m0"); } } while (0)
; #define PG8_LDA(dst, b, h) do { _Pragma("unroll") for (int m = 0; m < 4; ++m) _Pragma("unroll") for (int k = 0; k < 2; ++k) dst[m][k] = *(const LAS bf16x8*)(lds + PG8_SA(b, h) + aoff + m * 2048 + k * 1024); } while (0)
; #define PG8_WAIT_V(n) asm volatile("s_waitcnt vmcnt(" #n ")" ::: "memory")
; #define PG8_WAIT_L(n) asm volatile("s_waitcnt lgkmcnt(" #n ")" ::: "memory")
; #define PG8_BAR __builtin_amdgcn_s_barrier()
; #define PG8_SCHED __builtin_amdgcn_sched_barrier(0)
; template <class Epi>
; __device__ __forceinline__ void gemm_phase(LAS unsigned char* lds, const Gemm g_in, const StaticOrder& S, const Epi& E) {
;     ...
;         for (int t = 0; t < nt; t += 2) {
;     ...
;             PG8_LDA(At, 1, 1); PG8_STAGE(PG8_SB(1, 0), b3, B); PG8_STAGE(PG8_SB(1, 1), b3 + hsB, B); PG8_STAGE(PG8_SA(1, 0), a3, A);
;             PG8_WAIT_V(8); PG8_WAIT_L(0); PG8_BAR; PG8_MMA(1, 0, At, B0); PG8_MMA(1, 1, At, B1); PG8_BAR; PG8_SCHED;
;         }
	ds_read_b128 v[188:191], v139 offset:49152
	ds_read_b128 v[192:195], v139 offset:50176
	ds_read_b128 v[196:199], v139 offset:51200
	ds_read_b128 v[204:207], v139 offset:52224
	ds_read_b128 v[208:211], v139 offset:53248
	ds_read_b128 v[212:215], v139 offset:54272
	ds_read_b128 v[216:219], v139 offset:55296
	ds_read_b128 v[220:223], v139 offset:56320
	s_mov_b32 m0, s46
	s_nop 0
	global_load_lds_dwordx4 v134, s[64:65]
	s_add_u32 s64, s26, 0x80080
	s_addc_u32 s65, s27, 0
	s_mov_b32 m0, s47
	s_nop 0
	global_load_lds_dwordx4 v134, s[64:65]
	s_add_u32 s64, s26, 0x100080
	s_addc_u32 s65, s27, 0
	s_mov_b32 m0, s52
	s_nop 0
	global_load_lds_dwordx4 v134, s[64:65]
	s_add_u32 s26, s26, 0x180080
	s_addc_u32 s27, s27, 0
	s_mov_b32 m0, s53
	s_nop 0
	global_load_lds_dwordx4 v134, s[26:27]
	s_add_u32 s22, s22, 0x80080
	s_mov_b32 m0, s50
	s_nop 0
	global_load_lds_dwordx4 v1, s[24:25]
	s_addc_u32 s23, s23, 0
	s_mov_b32 m0, s51
	s_nop 0
	global_load_lds_dwordx4 v1, s[22:23]
	s_waitcnt vmcnt(8)
	s_waitcnt lgkmcnt(0)
	s_barrier
	s_setprio 1
	s_waitcnt lgkmcnt(7)
	v_mfma_f32_16x16x32_bf16 v[62:65], v[142:145], v[188:191], v[62:65]
	v_mfma_f32_16x16x32_bf16 v[58:61], v[150:153], v[188:191], v[58:61]
	s_waitcnt lgkmcnt(5)
	v_mfma_f32_16x16x32_bf16 v[46:49], v[142:145], v[196:199], v[46:49]
	v_mfma_f32_16x16x32_bf16 v[42:45], v[150:153], v[196:199], v[42:45]
	s_waitcnt lgkmcnt(3)
	v_mfma_f32_16x16x32_bf16 v[30:33], v[142:145], v[208:211], v[30:33]
	v_mfma_f32_16x16x32_bf16 v[26:29], v[150:153], v[208:211], v[26:29]
	s_waitcnt lgkmcnt(1)
	v_mfma_f32_16x16x32_bf16 v[14:17], v[142:145], v[216:219], v[14:17]
	v_mfma_f32_16x16x32_bf16 v[10:13], v[150:153], v[216:219], v[10:13]
	v_mfma_f32_16x16x32_bf16 v[62:65], v[146:149], v[192:195], v[62:65]
	v_mfma_f32_16x16x32_bf16 v[58:61], v[154:157], v[192:195], v[58:61]
	v_mfma_f32_16x16x32_bf16 v[46:49], v[146:149], v[204:207], v[46:49]
	v_mfma_f32_16x16x32_bf16 v[42:45], v[154:157], v[204:207], v[42:45]
	v_mfma_f32_16x16x32_bf16 v[30:33], v[146:149], v[212:215], v[30:33]
	v_mfma_f32_16x16x32_bf16 v[26:29], v[154:157], v[212:215], v[26:29]
	s_waitcnt lgkmcnt(0)
	v_mfma_f32_16x16x32_bf16 v[14:17], v[146:149], v[220:223], v[14:17]
	v_mfma_f32_16x16x32_bf16 v[10:13], v[154:157], v[220:223], v[10:13]
	s_setprio 0
	s_setprio 1
	v_mfma_f32_16x16x32_bf16 v[54:57], v[158:161], v[188:191], v[54:57]
	v_mfma_f32_16x16x32_bf16 v[50:53], v[174:177], v[188:191], v[50:53]
	v_mfma_f32_16x16x32_bf16 v[38:41], v[158:161], v[196:199], v[38:41]
	v_mfma_f32_16x16x32_bf16 v[34:37], v[174:177], v[196:199], v[34:37]
	v_mfma_f32_16x16x32_bf16 v[22:25], v[158:161], v[208:211], v[22:25]
	v_mfma_f32_16x16x32_bf16 v[18:21], v[174:177], v[208:211], v[18:21]
	v_mfma_f32_16x16x32_bf16 v[6:9], v[158:161], v[216:219], v[6:9]
	v_mfma_f32_16x16x32_bf16 v[2:5], v[174:177], v[216:219], v[2:5]
	v_mfma_f32_16x16x32_bf16 v[54:57], v[170:173], v[192:195], v[54:57]
	v_mfma_f32_16x16x32_bf16 v[50:53], v[184:187], v[192:195], v[50:53]
	v_mfma_f32_16x16x32_bf16 v[38:41], v[170:173], v[204:207], v[38:41]
	v_mfma_f32_16x16x32_bf16 v[34:37], v[184:187], v[204:207], v[34:37]
	v_mfma_f32_16x16x32_bf16 v[22:25], v[170:173], v[212:215], v[22:25]
	v_mfma_f32_16x16x32_bf16 v[18:21], v[184:187], v[212:215], v[18:21]
	v_mfma_f32_16x16x32_bf16 v[6:9], v[170:173], v[220:223], v[6:9]
	v_mfma_f32_16x16x32_bf16 v[2:5], v[184:187], v[220:223], v[2:5]
	s_setprio 0
	s_add_u32 s60, s60, 0x100
	s_addc_u32 s61, s61, 0
	s_add_u32 s20, s20, 0x100
	s_addc_u32 s21, s21, 0
	s_cmp_ge_i32 s62, s31
	s_mov_b32 s22, s62
	s_barrier
	s_cbranch_scc0 .LBB0_388
	s_and_b64 vcc, exec, s[6:7]
	s_cbranch_vccz .LBB0_391

; #define PG8_STAGE(bufoff, gbase, X) do { _Pragma("unroll") for (int _i = 0; _i < 2; ++_i) { \
;         const char* gp_ = (const char*)(gbase) + (_i ? rs##X : (size_t)0); const unsigned la_ = (unsigned)(size_t)(lds + (bufoff) + ldsw + _i * 8192); \
;         asm volatile("s_mov_b32 m0, %2\n\ts_nop 0\n\tglobal_load_lds_dwordx4 %0, %1" :: "v"(voff##X), "s"(gp_), "s"(la_) : "memory", "m0"); } } while (0)
; #define PG8_LDA(dst, b, h) do { _Pragma("unroll") for (int m = 0; m < 4; ++m) _Pragma("unroll") for (int k = 0; k < 2; ++k) dst[m][k] = *(const LAS bf16x8*)(lds + PG8_SA(b, h) + aoff + m * 2048 + k * 1024); } while (0)
; #define PG8_LDB(dst, b, h) do { _Pragma("unroll") for (int n = 0; n < 2; ++n) _Pragma("unroll") for (int k = 0; k < 2; ++k) dst[n][k] = *(const LAS bf16x8*)(lds + PG8_SB(b, h) + boff + n * 2048 + k * 1024); } while (0)
; #define PG8_WAIT_V(n) asm volatile("s_waitcnt vmcnt(" #n ")" ::: "memory")
; #define PG8_WAIT_L(n) asm volatile("s_waitcnt lgkmcnt(" #n ")" ::: "memory")
; #define PG8_BAR __builtin_amdgcn_s_barrier()
; #define PG8_SCHED __builtin_amdgcn_sched_barrier(0)
; template <class Epi>
; __device__ __forceinline__ void gemm_phase(LAS unsigned char* lds, const Gemm g_in, const StaticOrder& S, const Epi& E) {
;     ...
;             const bool last = (t == nt - 2);
;             const char* a1 = cA + (size_t)(t + 1) * kstep;
;             const char* a2 = last ? nA : cA + (size_t)(t + 2) * kstep; const char* b2 = last ? nB : cB + (size_t)(t + 2) * kstep;
;             const char* a3 = a2 + kstep; const char* b3 = b2 + kstep;
;             PG8_LDB(B0, 0, 0); PG8_LDB(B1, 0, 1); PG8_SCHED; PG8_LDA(At, 0, 0); PG8_STAGE(PG8_SA(1, 1), a1 + hsA, A);
;             PG8_WAIT_V(8); PG8_WAIT_L(0); PG8_BAR; PG8_MMA(0, 0, At, B0); PG8_MMA(0, 1, At, B1); PG8_BAR; PG8_SCHED;
;             PG8_LDA(At, 0, 1); PG8_STAGE(PG8_SB(0, 0), b2, B); PG8_STAGE(PG8_SB(0, 1), b2 + hsB, B); PG8_STAGE(PG8_SA(0, 0), a2, A);
.LBB0_406:
	v_add_u32_e32 v143, 0x10000, v141
	ds_read_b128 v[134:137], v143
	ds_read_b128 v[144:147], v143 offset:1024
	ds_read_b128 v[148:151], v143 offset:2048
	ds_read_b128 v[152:155], v143 offset:3072
	v_add_u32_e32 v143, 0x14000, v141
	ds_read_b128 v[156:159], v143
	ds_read_b128 v[170:173], v143 offset:1024
	ds_read_b128 v[174:177], v143 offset:2048
	ds_read_b128 v[184:187], v143 offset:3072
	s_add_i32 s70, s30, 2
	s_add_u32 s34, s28, 0xfff40080
	s_addc_u32 s31, s29, -1
	s_cmp_eq_u32 s62, s30
	s_cselect_b32 s30, s21, s34
	s_cselect_b32 s31, s19, s31
	s_cselect_b32 s36, s67, s68
	s_cselect_b32 s37, s66, s69
	s_add_u32 s34, s30, 0x80
	s_addc_u32 s35, s31, 0
	ds_read_b128 v[188:191], v142
	ds_read_b128 v[192:195], v142 offset:1024
	ds_read_b128 v[196:199], v142 offset:2048
	ds_read_b128 v[204:207], v142 offset:3072
	ds_read_b128 v[208:211], v142 offset:4096
	ds_read_b128 v[212:215], v142 offset:5120
	ds_read_b128 v[216:219], v142 offset:6144
	ds_read_b128 v[220:223], v142 offset:7168
	s_add_u32 s72, s28, 0xfffc0000
	s_addc_u32 s73, s29, -1
	s_mov_b32 m0, s63
	s_nop 0
	global_load_lds_dwordx4 v1, s[72:73]
	s_nop 0
	s_mov_b32 m0, s64
	s_nop 0
	global_load_lds_dwordx4 v1, s[28:29]
	s_waitcnt vmcnt(8)
	s_waitcnt lgkmcnt(0)
	s_barrier
	s_setprio 1
	s_waitcnt lgkmcnt(7)
	v_mfma_i32_16x16x64_i8 v[126:129], v[134:137], v[188:191], v[126:129]
	v_mfma_i32_16x16x64_i8 v[122:125], v[148:151], v[188:191], v[122:125]
	s_waitcnt lgkmcnt(5)
	v_mfma_i32_16x16x64_i8 v[118:121], v[134:137], v[196:199], v[118:121]
	v_mfma_i32_16x16x64_i8 v[110:113], v[148:151], v[196:199], v[110:113]
	s_waitcnt lgkmcnt(3)
	v_mfma_i32_16x16x64_i8 v[102:105], v[134:137], v[208:211], v[102:105]
	v_mfma_i32_16x16x64_i8 v[94:97], v[148:151], v[208:211], v[94:97]
	s_waitcnt lgkmcnt(1)
	v_mfma_i32_16x16x64_i8 v[86:89], v[134:137], v[216:219], v[86:89]
	v_mfma_i32_16x16x64_i8 v[78:81], v[148:151], v[216:219], v[78:81]
	v_mfma_i32_16x16x64_i8 v[126:129], v[144:147], v[192:195], v[126:129]
	v_mfma_i32_16x16x64_i8 v[122:125], v[152:155], v[192:195], v[122:125]
	v_mfma_i32_16x16x64_i8 v[118:121], v[144:147], v[204:207], v[118:121]
	v_mfma_i32_16x16x64_i8 v[110:113], v[152:155], v[204:207], v[110:113]
	v_mfma_i32_16x16x64_i8 v[102:105], v[144:147], v[212:215], v[102:105]
	v_mfma_i32_16x16x64_i8 v[94:97], v[152:155], v[212:215], v[94:97]
	s_waitcnt lgkmcnt(0)
	v_mfma_i32_16x16x64_i8 v[86:89], v[144:147], v[220:223], v[86:89]
	v_mfma_i32_16x16x64_i8 v[78:81], v[152:155], v[220:223], v[78:81]
	s_setprio 0
	s_setprio 1
	v_mfma_i32_16x16x64_i8 v[114:117], v[156:159], v[188:191], v[114:117]
	v_mfma_i32_16x16x64_i8 v[106:109], v[174:177], v[188:191], v[106:109]
	v_mfma_i32_16x16x64_i8 v[98:101], v[156:159], v[196:199], v[98:101]
	v_mfma_i32_16x16x64_i8 v[90:93], v[174:177], v[196:199], v[90:93]
	v_mfma_i32_16x16x64_i8 v[82:85], v[156:159], v[208:211], v[82:85]
	v_mfma_i32_16x16x64_i8 v[74:77], v[174:177], v[208:211], v[74:77]
	v_mfma_i32_16x16x64_i8 v[70:73], v[156:159], v[216:219], v[70:73]
	v_mfma_i32_16x16x64_i8 v[66:69], v[174:177], v[216:219], v[66:69]
	v_mfma_i32_16x16x64_i8 v[114:117], v[170:173], v[192:195], v[114:117]
	v_mfma_i32_16x16x64_i8 v[106:109], v[184:187], v[192:195], v[106:109]
	v_mfma_i32_16x16x64_i8 v[98:101], v[170:173], v[204:207], v[98:101]
	v_mfma_i32_16x16x64_i8 v[90:93], v[184:187], v[204:207], v[90:93]
	v_mfma_i32_16x16x64_i8 v[82:85], v[170:173], v[212:215], v[82:85]
	v_mfma_i32_16x16x64_i8 v[74:77], v[184:187], v[212:215], v[74:77]
	v_mfma_i32_16x16x64_i8 v[70:73], v[170:173], v[220:223], v[70:73]
	v_mfma_i32_16x16x64_i8 v[66:69], v[184:187], v[220:223], v[66:69]
	s_setprio 0
	s_add_u32 s72, s36, 0x40000
	s_barrier
	ds_read_b128 v[188:191], v142 offset:16384
	ds_read_b128 v[192:195], v142 offset:17408
	ds_read_b128 v[196:199], v142 offset:18432
	ds_read_b128 v[204:207], v142 offset:19456
	ds_read_b128 v[208:211], v142 offset:20480
	ds_read_b128 v[212:215], v142 offset:21504
	ds_read_b128 v[216:219], v142 offset:22528
	ds_read_b128 v[220:223], v142 offset:23552
	s_mov_b32 m0, s44
	s_nop 0
	global_load_lds_dwordx4 v138, s[36:37]
	s_addc_u32 s73, s37, 0
	s_mov_b32 m0, s45
	s_nop 0
	global_load_lds_dwordx4 v138, s[72:73]
	s_add_u32 s72, s36, 0x80000
	s_addc_u32 s73, s37, 0
	s_mov_b32 m0, s46
	s_nop 0
	global_load_lds_dwordx4 v138, s[72:73]
	s_add_u32 s72, s36, 0xc0000
	s_addc_u32 s73, s37, 0
	s_mov_b32 m0, s47
	s_nop 0
	global_load_lds_dwordx4 v138, s[72:73]
	s_add_u32 s72, s30, 0x40000
	s_mov_b32 m0, s23
	s_nop 0
	global_load_lds_dwordx4 v1, s[30:31]
	s_addc_u32 s73, s31, 0
	s_mov_b32 m0, s50
	s_nop 0
	global_load_lds_dwordx4 v1, s[72:73]
	s_waitcnt vmcnt(8)
	s_waitcnt lgkmcnt(0)
	s_barrier
; #define PG8_STAGE(bufoff, gbase, X) do { _Pragma("unroll") for (int _i = 0; _i < 2; ++_i) { \
;         const char* gp_ = (const char*)(gbase) + (_i ? rs##X : (size_t)0); const unsigned la_ = (unsigned)(size_t)(lds + (bufoff) + ldsw + _i * 8192); \
;         asm volatile("s_mov_b32 m0, %2\n\ts_nop 0\n\tglobal_load_lds_dwordx4 %0, %1" :: "v"(voff##X), "s"(gp_), "s"(la_) : "memory", "m0"); } } while (0)
; #define PG8_LDA(dst, b, h) do { _Pragma("unroll") for (int m = 0; m < 4; ++m) _Pragma("unroll") for (int k = 0; k < 2; ++k) dst[m][k] = *(const LAS bf16x8*)(lds + PG8_SA(b, h) + aoff + m * 2048 + k * 1024); } while (0)
; #define PG8_LDB(dst, b, h) do { _Pragma("unroll") for (int n = 0; n < 2; ++n) _Pragma("unroll") for (int k = 0; k < 2; ++k) dst[n][k] = *(const LAS bf16x8*)(lds + PG8_SB(b, h) + boff + n * 2048 + k * 1024); } while (0)
; #define PG8_WAIT_V(n) asm volatile("s_waitcnt vmcnt(" #n ")" ::: "memory")
; #define PG8_WAIT_L(n) asm volatile("s_waitcnt lgkmcnt(" #n ")" ::: "memory")
; #define PG8_BAR __builtin_amdgcn_s_barrier()
; #define PG8_SCHED __builtin_amdgcn_sched_barrier(0)
; template <class Epi>
; __device__ __forceinline__ void gemm_phase(LAS unsigned char* lds, const Gemm g_in, const StaticOrder& S, const Epi& E) {
;     ...
;             PG8_WAIT_V(8); PG8_WAIT_L(0); PG8_BAR; PG8_MMA(1, 0, At, B0); PG8_MMA(1, 1, At, B1); PG8_BAR; PG8_SCHED;
;             PG8_LDB(B0, 1, 0); PG8_LDB(B1, 1, 1); PG8_SCHED; PG8_LDA(At, 1, 0); PG8_STAGE(PG8_SA(0, 1), a2 + hsA, A);
;             PG8_WAIT_V(8); PG8_WAIT_L(0); PG8_BAR; PG8_MMA(0, 0, At, B0); PG8_MMA(0, 1, At, B1); PG8_BAR; PG8_SCHED;
	s_setprio 1
	s_waitcnt lgkmcnt(7)
	v_mfma_i32_16x16x64_i8 v[62:65], v[134:137], v[188:191], v[62:65]
	v_mfma_i32_16x16x64_i8 v[58:61], v[148:151], v[188:191], v[58:61]
	s_waitcnt lgkmcnt(5)
	v_mfma_i32_16x16x64_i8 v[54:57], v[134:137], v[196:199], v[54:57]
	v_mfma_i32_16x16x64_i8 v[46:49], v[148:151], v[196:199], v[46:49]
	s_waitcnt lgkmcnt(3)
	v_mfma_i32_16x16x64_i8 v[38:41], v[134:137], v[208:211], v[38:41]
	v_mfma_i32_16x16x64_i8 v[30:33], v[148:151], v[208:211], v[30:33]
	s_waitcnt lgkmcnt(1)
	v_mfma_i32_16x16x64_i8 v[22:25], v[134:137], v[216:219], v[22:25]
	v_mfma_i32_16x16x64_i8 v[14:17], v[148:151], v[216:219], v[14:17]
	v_mfma_i32_16x16x64_i8 v[62:65], v[144:147], v[192:195], v[62:65]
	v_mfma_i32_16x16x64_i8 v[58:61], v[152:155], v[192:195], v[58:61]
	v_mfma_i32_16x16x64_i8 v[54:57], v[144:147], v[204:207], v[54:57]
	v_mfma_i32_16x16x64_i8 v[46:49], v[152:155], v[204:207], v[46:49]
	v_mfma_i32_16x16x64_i8 v[38:41], v[144:147], v[212:215], v[38:41]
	v_mfma_i32_16x16x64_i8 v[30:33], v[152:155], v[212:215], v[30:33]
	s_waitcnt lgkmcnt(0)
	v_mfma_i32_16x16x64_i8 v[22:25], v[144:147], v[220:223], v[22:25]
	v_mfma_i32_16x16x64_i8 v[14:17], v[152:155], v[220:223], v[14:17]
	s_setprio 0
	s_setprio 1
	v_mfma_i32_16x16x64_i8 v[50:53], v[156:159], v[188:191], v[50:53]
	v_mfma_i32_16x16x64_i8 v[42:45], v[174:177], v[188:191], v[42:45]
	v_mfma_i32_16x16x64_i8 v[34:37], v[156:159], v[196:199], v[34:37]
	v_mfma_i32_16x16x64_i8 v[26:29], v[174:177], v[196:199], v[26:29]
	v_mfma_i32_16x16x64_i8 v[18:21], v[156:159], v[208:211], v[18:21]
	v_mfma_i32_16x16x64_i8 v[10:13], v[174:177], v[208:211], v[10:13]
	v_mfma_i32_16x16x64_i8 v[6:9], v[156:159], v[216:219], v[6:9]
	v_mfma_i32_16x16x64_i8 v[2:5], v[174:177], v[216:219], v[2:5]
	v_mfma_i32_16x16x64_i8 v[50:53], v[170:173], v[192:195], v[50:53]
	v_mfma_i32_16x16x64_i8 v[42:45], v[184:187], v[192:195], v[42:45]
	v_mfma_i32_16x16x64_i8 v[34:37], v[170:173], v[204:207], v[34:37]
	v_mfma_i32_16x16x64_i8 v[26:29], v[184:187], v[204:207], v[26:29]
	v_mfma_i32_16x16x64_i8 v[18:21], v[170:173], v[212:215], v[18:21]
	v_mfma_i32_16x16x64_i8 v[10:13], v[184:187], v[212:215], v[10:13]
	v_mfma_i32_16x16x64_i8 v[6:9], v[170:173], v[220:223], v[6:9]
	v_mfma_i32_16x16x64_i8 v[2:5], v[184:187], v[220:223], v[2:5]
	s_setprio 0
	s_barrier
	v_add_u32_e32 v143, 0x18000, v141
	ds_read_b128 v[134:137], v143
	ds_read_b128 v[144:147], v143 offset:1024
	ds_read_b128 v[148:151], v143 offset:2048
	ds_read_b128 v[152:155], v143 offset:3072
	v_add_u32_e32 v143, 0x1c000, v141
	ds_read_b128 v[156:159], v143
	ds_read_b128 v[170:173], v143 offset:1024
	ds_read_b128 v[174:177], v143 offset:2048
	ds_read_b128 v[184:187], v143 offset:3072
	ds_read_b128 v[188:191], v142 offset:32768
	ds_read_b128 v[192:195], v142 offset:33792
	ds_read_b128 v[196:199], v142 offset:34816
	ds_read_b128 v[204:207], v142 offset:35840
	ds_read_b128 v[208:211], v142 offset:36864
	ds_read_b128 v[212:215], v142 offset:37888
	ds_read_b128 v[216:219], v142 offset:38912
	ds_read_b128 v[220:223], v142 offset:39936
	s_add_u32 s72, s30, 0x80000
	s_addc_u32 s73, s31, 0
	s_mov_b32 m0, s51
	s_nop 0
	global_load_lds_dwordx4 v1, s[72:73]
	s_add_u32 s72, s30, 0xc0000
	s_addc_u32 s73, s31, 0
	s_mov_b32 m0, s52
	s_nop 0
	global_load_lds_dwordx4 v1, s[72:73]
	s_waitcnt vmcnt(8)
	s_waitcnt lgkmcnt(0)
	s_barrier
	s_setprio 1
	s_waitcnt lgkmcnt(7)
	v_mfma_i32_16x16x64_i8 v[126:129], v[134:137], v[188:191], v[126:129]
	v_mfma_i32_16x16x64_i8 v[122:125], v[148:151], v[188:191], v[122:125]
	s_waitcnt lgkmcnt(5)
	v_mfma_i32_16x16x64_i8 v[118:121], v[134:137], v[196:199], v[118:121]
	v_mfma_i32_16x16x64_i8 v[110:113], v[148:151], v[196:199], v[110:113]
	s_waitcnt lgkmcnt(3)
	v_mfma_i32_16x16x64_i8 v[102:105], v[134:137], v[208:211], v[102:105]
	v_mfma_i32_16x16x64_i8 v[94:97], v[148:151], v[208:211], v[94:97]
	s_waitcnt lgkmcnt(1)
	v_mfma_i32_16x16x64_i8 v[86:89], v[134:137], v[216:219], v[86:89]
	v_mfma_i32_16x16x64_i8 v[78:81], v[148:151], v[216:219], v[78:81]
	v_mfma_i32_16x16x64_i8 v[126:129], v[144:147], v[192:195], v[126:129]
	v_mfma_i32_16x16x64_i8 v[122:125], v[152:155], v[192:195], v[122:125]
	v_mfma_i32_16x16x64_i8 v[118:121], v[144:147], v[204:207], v[118:121]
	v_mfma_i32_16x16x64_i8 v[110:113], v[152:155], v[204:207], v[110:113]
	v_mfma_i32_16x16x64_i8 v[102:105], v[144:147], v[212:215], v[102:105]
	v_mfma_i32_16x16x64_i8 v[94:97], v[152:155], v[212:215], v[94:97]
	s_waitcnt lgkmcnt(0)
	v_mfma_i32_16x16x64_i8 v[86:89], v[144:147], v[220:223], v[86:89]
	v_mfma_i32_16x16x64_i8 v[78:81], v[152:155], v[220:223], v[78:81]
	s_setprio 0
	s_setprio 1
	v_mfma_i32_16x16x64_i8 v[114:117], v[156:159], v[188:191], v[114:117]
	v_mfma_i32_16x16x64_i8 v[106:109], v[174:177], v[188:191], v[106:109]
	v_mfma_i32_16x16x64_i8 v[98:101], v[156:159], v[196:199], v[98:101]
	v_mfma_i32_16x16x64_i8 v[90:93], v[174:177], v[196:199], v[90:93]
	v_mfma_i32_16x16x64_i8 v[82:85], v[156:159], v[208:211], v[82:85]
	v_mfma_i32_16x16x64_i8 v[74:77], v[174:177], v[208:211], v[74:77]
	v_mfma_i32_16x16x64_i8 v[70:73], v[156:159], v[216:219], v[70:73]
	v_mfma_i32_16x16x64_i8 v[66:69], v[174:177], v[216:219], v[66:69]
	v_mfma_i32_16x16x64_i8 v[114:117], v[170:173], v[192:195], v[114:117]
	v_mfma_i32_16x16x64_i8 v[106:109], v[184:187], v[192:195], v[106:109]
	v_mfma_i32_16x16x64_i8 v[98:101], v[170:173], v[204:207], v[98:101]
	v_mfma_i32_16x16x64_i8 v[90:93], v[184:187], v[204:207], v[90:93]
	v_mfma_i32_16x16x64_i8 v[82:85], v[170:173], v[212:215], v[82:85]
	v_mfma_i32_16x16x64_i8 v[74:77], v[184:187], v[212:215], v[74:77]
	v_mfma_i32_16x16x64_i8 v[70:73], v[170:173], v[220:223], v[70:73]
	v_mfma_i32_16x16x64_i8 v[66:69], v[184:187], v[220:223], v[66:69]
	s_setprio 0
	s_add_u32 s72, s36, 0x80
	s_addc_u32 s73, s37, 0
	s_barrier
; #define PG8_STAGE(bufoff, gbase, X) do { _Pragma("unroll") for (int _i = 0; _i < 2; ++_i) { \
;         const char* gp_ = (const char*)(gbase) + (_i ? rs##X : (size_t)0); const unsigned la_ = (unsigned)(size_t)(lds + (bufoff) + ldsw + _i * 8192); \
;         asm volatile("s_mov_b32 m0, %2\n\ts_nop 0\n\tglobal_load_lds_dwordx4 %0, %1" :: "v"(voff##X), "s"(gp_), "s"(la_) : "memory", "m0"); } } while (0)
; #define PG8_LDA(dst, b, h) do { _Pragma("unroll") for (int m = 0; m < 4; ++m) _Pragma("unroll") for (int k = 0; k < 2; ++k) dst[m][k] = *(const LAS bf16x8*)(lds + PG8_SA(b, h) + aoff + m * 2048 + k * 1024); } while (0)
; #define PG8_WAIT_V(n) asm volatile("s_waitcnt vmcnt(" #n ")" ::: "memory")
; #define PG8_WAIT_L(n) asm volatile("s_waitcnt lgkmcnt(" #n ")" ::: "memory")
; #define PG8_BAR __builtin_amdgcn_s_barrier()
; #define PG8_SCHED __builtin_amdgcn_sched_barrier(0)
; template <class Epi>
; __device__ __forceinline__ void gemm_phase(LAS unsigned char* lds, const Gemm g_in, const StaticOrder& S, const Epi& E) {
;     ...
;             PG8_LDA(At, 1, 1); PG8_STAGE(PG8_SB(1, 0), b3, B); PG8_STAGE(PG8_SB(1, 1), b3 + hsB, B); PG8_STAGE(PG8_SA(1, 0), a3, A);
;             PG8_WAIT_V(8); PG8_WAIT_L(0); PG8_BAR; PG8_MMA(1, 0, At, B0); PG8_MMA(1, 1, At, B1); PG8_BAR; PG8_SCHED;
;         }
;     __device__ __forceinline__ void operator()(const f32x4 (&acc)[2][2][4][2], const Unit& u, int wr, int wc, int fr, int fq) const {
;     ...
;                 for (int bj = 0; bj < 2; ++bj) { f32x4 v0 = acc[ai][bj][m][0], v1 = acc[ai][bj][m][1];
;                     if (I8_) { v0 = __builtin_convertvector(__builtin_bit_cast(i32x4, v0), f32x4) * I8_DEQ; v1 = __builtin_convertvector(__builtin_bit_cast(i32x4, v1), f32x4) * I8_DEQ; }
	ds_read_b128 v[188:191], v142 offset:49152
	ds_read_b128 v[192:195], v142 offset:50176
	ds_read_b128 v[196:199], v142 offset:51200
	ds_read_b128 v[204:207], v142 offset:52224
	ds_read_b128 v[208:211], v142 offset:53248
	ds_read_b128 v[212:215], v142 offset:54272
	ds_read_b128 v[216:219], v142 offset:55296
	ds_read_b128 v[220:223], v142 offset:56320
	s_mov_b32 m0, s56
	s_nop 0
	global_load_lds_dwordx4 v138, s[72:73]
	s_add_u32 s72, s36, 0x40080
	s_addc_u32 s73, s37, 0
	s_mov_b32 m0, s57
	s_nop 0
	global_load_lds_dwordx4 v138, s[72:73]
	s_add_u32 s72, s36, 0x80080
	s_addc_u32 s73, s37, 0
	s_mov_b32 m0, s60
	s_nop 0
	global_load_lds_dwordx4 v138, s[72:73]
	s_add_u32 s36, s36, 0xc0080
	s_addc_u32 s37, s37, 0
	s_mov_b32 m0, s61
	s_nop 0
	global_load_lds_dwordx4 v138, s[36:37]
	s_add_u32 s30, s30, 0x40080
	s_mov_b32 m0, s58
	s_nop 0
	global_load_lds_dwordx4 v1, s[34:35]
	s_addc_u32 s31, s31, 0
	s_mov_b32 m0, s59
	s_nop 0
	global_load_lds_dwordx4 v1, s[30:31]
	s_waitcnt vmcnt(8)
	s_waitcnt lgkmcnt(0)
	s_barrier
	s_setprio 1
	s_waitcnt lgkmcnt(7)
	v_mfma_i32_16x16x64_i8 v[62:65], v[134:137], v[188:191], v[62:65]
	v_mfma_i32_16x16x64_i8 v[58:61], v[148:151], v[188:191], v[58:61]
	s_waitcnt lgkmcnt(5)
	v_mfma_i32_16x16x64_i8 v[54:57], v[134:137], v[196:199], v[54:57]
	v_mfma_i32_16x16x64_i8 v[46:49], v[148:151], v[196:199], v[46:49]
	s_waitcnt lgkmcnt(3)
	v_mfma_i32_16x16x64_i8 v[38:41], v[134:137], v[208:211], v[38:41]
	v_mfma_i32_16x16x64_i8 v[30:33], v[148:151], v[208:211], v[30:33]
	s_waitcnt lgkmcnt(1)
	v_mfma_i32_16x16x64_i8 v[22:25], v[134:137], v[216:219], v[22:25]
	v_mfma_i32_16x16x64_i8 v[14:17], v[148:151], v[216:219], v[14:17]
	v_mfma_i32_16x16x64_i8 v[62:65], v[144:147], v[192:195], v[62:65]
	v_mfma_i32_16x16x64_i8 v[58:61], v[152:155], v[192:195], v[58:61]
	v_mfma_i32_16x16x64_i8 v[54:57], v[144:147], v[204:207], v[54:57]
	v_mfma_i32_16x16x64_i8 v[46:49], v[152:155], v[204:207], v[46:49]
	v_mfma_i32_16x16x64_i8 v[38:41], v[144:147], v[212:215], v[38:41]
	v_mfma_i32_16x16x64_i8 v[30:33], v[152:155], v[212:215], v[30:33]
	s_waitcnt lgkmcnt(0)
	v_mfma_i32_16x16x64_i8 v[22:25], v[144:147], v[220:223], v[22:25]
	v_mfma_i32_16x16x64_i8 v[14:17], v[152:155], v[220:223], v[14:17]
	s_setprio 0
	s_setprio 1
	v_mfma_i32_16x16x64_i8 v[50:53], v[156:159], v[188:191], v[50:53]
	v_mfma_i32_16x16x64_i8 v[42:45], v[174:177], v[188:191], v[42:45]
	v_mfma_i32_16x16x64_i8 v[34:37], v[156:159], v[196:199], v[34:37]
	v_mfma_i32_16x16x64_i8 v[26:29], v[174:177], v[196:199], v[26:29]
	v_mfma_i32_16x16x64_i8 v[18:21], v[156:159], v[208:211], v[18:21]
	v_mfma_i32_16x16x64_i8 v[10:13], v[174:177], v[208:211], v[10:13]
	v_mfma_i32_16x16x64_i8 v[6:9], v[156:159], v[216:219], v[6:9]
	v_mfma_i32_16x16x64_i8 v[2:5], v[174:177], v[216:219], v[2:5]
	v_mfma_i32_16x16x64_i8 v[50:53], v[170:173], v[192:195], v[50:53]
	v_mfma_i32_16x16x64_i8 v[42:45], v[184:187], v[192:195], v[42:45]
	v_mfma_i32_16x16x64_i8 v[34:37], v[170:173], v[204:207], v[34:37]
	v_mfma_i32_16x16x64_i8 v[26:29], v[184:187], v[204:207], v[26:29]
	v_mfma_i32_16x16x64_i8 v[18:21], v[170:173], v[212:215], v[18:21]
	v_mfma_i32_16x16x64_i8 v[10:13], v[184:187], v[212:215], v[10:13]
	v_mfma_i32_16x16x64_i8 v[6:9], v[170:173], v[220:223], v[6:9]
	v_mfma_i32_16x16x64_i8 v[2:5], v[184:187], v[220:223], v[2:5]
	s_setprio 0
	s_add_u32 s68, s68, 0x100
	s_addc_u32 s69, s69, 0
	s_add_u32 s28, s28, 0x100
	s_addc_u32 s29, s29, 0
	s_cmp_ge_i32 s70, s41
	s_mov_b32 s30, s70
	s_barrier
	s_cbranch_scc0 .LBB0_406
	v_cvt_f32_i32_e32 v129, v129
	v_cvt_f32_i32_e32 v128, v128
	v_cvt_f32_i32_e32 v135, v123
	v_cvt_f32_i32_e32 v134, v122
	v_cvt_f32_i32_e32 v109, v109
	v_pk_mul_f32 v[122:123], v[128:129], s[8:9] op_sel_hi:[1,0]
	v_cvt_f32_i32_e32 v108, v108
	v_pk_mul_f32 v[128:129], v[134:135], s[8:9] op_sel_hi:[1,0]
	v_cvt_f32_i32_e32 v135, v115
	v_cvt_f32_i32_e32 v134, v114
	v_cvt_f32_i32_e32 v115, v117
	v_cvt_f32_i32_e32 v114, v116
	v_cvt_f32_i32_e32 v113, v113
	v_pk_mul_f32 v[116:117], v[134:135], s[8:9] op_sel_hi:[1,0]
	v_pk_mul_f32 v[134:135], v[108:109], s[8:9] op_sel_hi:[1,0]
	v_cvt_f32_i32_e32 v109, v119
	v_cvt_f32_i32_e32 v108, v118
	v_cvt_f32_i32_e32 v119, v111
	v_cvt_f32_i32_e32 v112, v112
	v_cvt_f32_i32_e32 v118, v110
	v_cvt_f32_i32_e32 v93, v93
	v_cvt_f32_i32_e32 v92, v92
	v_pk_mul_f32 v[110:111], v[112:113], s[8:9] op_sel_hi:[1,0]
	v_pk_mul_f32 v[112:113], v[118:119], s[8:9] op_sel_hi:[1,0]
	v_cvt_f32_i32_e32 v119, v99
	v_cvt_f32_i32_e32 v118, v98
	v_cvt_f32_i32_e32 v99, v101
	v_cvt_f32_i32_e32 v98, v100
	v_cvt_f32_i32_e32 v97, v97
	v_pk_mul_f32 v[100:101], v[118:119], s[8:9] op_sel_hi:[1,0]
	v_pk_mul_f32 v[118:119], v[92:93], s[8:9] op_sel_hi:[1,0]
	v_cvt_f32_i32_e32 v93, v103
	v_cvt_f32_i32_e32 v92, v102
	v_cvt_f32_i32_e32 v103, v95
	v_cvt_f32_i32_e32 v96, v96
	v_cvt_f32_i32_e32 v102, v94
	v_cvt_f32_i32_e32 v77, v77
	v_cvt_f32_i32_e32 v76, v76
	v_pk_mul_f32 v[94:95], v[96:97], s[8:9] op_sel_hi:[1,0]
	v_pk_mul_f32 v[96:97], v[102:103], s[8:9] op_sel_hi:[1,0]
	v_cvt_f32_i32_e32 v103, v83
	v_cvt_f32_i32_e32 v102, v82
	v_cvt_f32_i32_e32 v83, v85
	v_cvt_f32_i32_e32 v82, v84
	v_cvt_f32_i32_e32 v81, v81
	v_pk_mul_f32 v[84:85], v[102:103], s[8:9] op_sel_hi:[1,0]
	v_pk_mul_f32 v[102:103], v[76:77], s[8:9] op_sel_hi:[1,0]
	v_cvt_f32_i32_e32 v77, v87
	v_cvt_f32_i32_e32 v76, v86
	v_cvt_f32_i32_e32 v87, v79
	v_cvt_f32_i32_e32 v80, v80
	v_cvt_f32_i32_e32 v86, v78
	v_cvt_f32_i32_e32 v73, v73
	v_cvt_f32_i32_e32 v72, v72
;     __device__ __forceinline__ void operator()(const f32x4 (&acc)[2][2][4][2], const Unit& u, int wr, int wc, int fr, int fq) const {
;     ...
;                 for (int bj = 0; bj < 2; ++bj) { f32x4 v0 = acc[ai][bj][m][0], v1 = acc[ai][bj][m][1];
;                     if (I8_) { v0 = __builtin_convertvector(__builtin_bit_cast(i32x4, v0), f32x4) * I8_DEQ; v1 = __builtin_convertvector(__builtin_bit_cast(i32x4, v1), f32x4) * I8_DEQ; }
	v_pk_mul_f32 v[78:79], v[80:81], s[8:9] op_sel_hi:[1,0]
	v_pk_mul_f32 v[80:81], v[86:87], s[8:9] op_sel_hi:[1,0]
	v_cvt_f32_i32_e32 v87, v67
	v_cvt_f32_i32_e32 v86, v66
	v_pk_mul_f32 v[66:67], v[72:73], s[8:9] op_sel_hi:[1,0]
	v_cvt_f32_i32_e32 v65, v65
	v_cvt_f32_i32_e32 v64, v64
	v_pk_mul_f32 v[72:73], v[86:87], s[8:9] op_sel_hi:[1,0]
	v_cvt_f32_i32_e32 v87, v59
	v_cvt_f32_i32_e32 v86, v58
	v_pk_mul_f32 v[58:59], v[64:65], s[8:9] op_sel_hi:[1,0]
	v_cvt_f32_i32_e32 v45, v45
	v_cvt_f32_i32_e32 v44, v44
	v_pk_mul_f32 v[64:65], v[86:87], s[8:9] op_sel_hi:[1,0]
	v_cvt_f32_i32_e32 v87, v51
	v_cvt_f32_i32_e32 v86, v50
	v_cvt_f32_i32_e32 v51, v53
	v_cvt_f32_i32_e32 v50, v52
	v_cvt_f32_i32_e32 v49, v49
	v_pk_mul_f32 v[52:53], v[86:87], s[8:9] op_sel_hi:[1,0]
	v_pk_mul_f32 v[86:87], v[44:45], s[8:9] op_sel_hi:[1,0]
	v_cvt_f32_i32_e32 v45, v55
	v_cvt_f32_i32_e32 v44, v54
	v_cvt_f32_i32_e32 v55, v47
	v_cvt_f32_i32_e32 v48, v48
	v_cvt_f32_i32_e32 v54, v46
	v_cvt_f32_i32_e32 v29, v29
	v_cvt_f32_i32_e32 v28, v28
	v_pk_mul_f32 v[46:47], v[48:49], s[8:9] op_sel_hi:[1,0]
	v_pk_mul_f32 v[48:49], v[54:55], s[8:9] op_sel_hi:[1,0]
	v_cvt_f32_i32_e32 v55, v35
	v_cvt_f32_i32_e32 v54, v34
	v_cvt_f32_i32_e32 v127, v127
	v_cvt_f32_i32_e32 v126, v126
	v_cvt_f32_i32_e32 v137, v125
	v_cvt_f32_i32_e32 v136, v124
	v_cvt_f32_i32_e32 v107, v107
	v_cvt_f32_i32_e32 v106, v106
	v_cvt_f32_i32_e32 v91, v91
	v_cvt_f32_i32_e32 v90, v90
	v_cvt_f32_i32_e32 v75, v75
	v_cvt_f32_i32_e32 v74, v74
	v_cvt_f32_i32_e32 v35, v37
	v_cvt_f32_i32_e32 v34, v36
	v_pk_mul_f32 v[36:37], v[54:55], s[8:9] op_sel_hi:[1,0]
	v_pk_mul_f32 v[54:55], v[28:29], s[8:9] op_sel_hi:[1,0]
	v_cvt_f32_i32_e32 v29, v39
	v_cvt_f32_i32_e32 v28, v38
	v_cvt_f32_i32_e32 v39, v31
	v_cvt_f32_i32_e32 v33, v33
	v_cvt_f32_i32_e32 v32, v32
	v_cvt_f32_i32_e32 v38, v30
	v_pk_mul_f32 v[124:125], v[126:127], s[8:9] op_sel_hi:[1,0]
	v_pk_mul_f32 v[126:127], v[136:137], s[8:9] op_sel_hi:[1,0]
	v_pk_mul_f32 v[136:137], v[106:107], s[8:9] op_sel_hi:[1,0]
	v_cvt_f32_i32_e32 v107, v121
	v_cvt_f32_i32_e32 v106, v120
	v_pk_mul_f32 v[120:121], v[90:91], s[8:9] op_sel_hi:[1,0]
	v_cvt_f32_i32_e32 v91, v105
	v_cvt_f32_i32_e32 v90, v104
	v_pk_mul_f32 v[104:105], v[74:75], s[8:9] op_sel_hi:[1,0]
	v_cvt_f32_i32_e32 v75, v89
	v_cvt_f32_i32_e32 v74, v88
	v_cvt_f32_i32_e32 v71, v71
	v_cvt_f32_i32_e32 v70, v70
	v_cvt_f32_i32_e32 v89, v69
	v_cvt_f32_i32_e32 v88, v68
	v_pk_mul_f32 v[30:31], v[32:33], s[8:9] op_sel_hi:[1,0]
	v_pk_mul_f32 v[32:33], v[38:39], s[8:9] op_sel_hi:[1,0]
	v_cvt_f32_i32_e32 v39, v19
	v_cvt_f32_i32_e32 v38, v18
	v_cvt_f32_i32_e32 v13, v13
	v_cvt_f32_i32_e32 v12, v12
	v_pk_mul_f32 v[68:69], v[70:71], s[8:9] op_sel_hi:[1,0]
	v_pk_mul_f32 v[70:71], v[88:89], s[8:9] op_sel_hi:[1,0]
	v_cvt_f32_i32_e32 v63, v63
	v_cvt_f32_i32_e32 v62, v62
	v_cvt_f32_i32_e32 v89, v61
	v_cvt_f32_i32_e32 v88, v60
	v_cvt_f32_i32_e32 v43, v43
	v_cvt_f32_i32_e32 v42, v42
	v_cvt_f32_i32_e32 v27, v27
	v_cvt_f32_i32_e32 v26, v26
	v_cvt_f32_i32_e32 v19, v21
	v_cvt_f32_i32_e32 v18, v20
	v_cvt_f32_i32_e32 v11, v11
	v_cvt_f32_i32_e32 v10, v10
	v_pk_mul_f32 v[20:21], v[38:39], s[8:9] op_sel_hi:[1,0]
	v_pk_mul_f32 v[38:39], v[12:13], s[8:9] op_sel_hi:[1,0]
	v_cvt_f32_i32_e32 v13, v23
	v_cvt_f32_i32_e32 v12, v22
	v_cvt_f32_i32_e32 v23, v15
	v_cvt_f32_i32_e32 v17, v17
	v_cvt_f32_i32_e32 v16, v16
	v_cvt_f32_i32_e32 v22, v14
	v_pk_mul_f32 v[60:61], v[62:63], s[8:9] op_sel_hi:[1,0]
	v_pk_mul_f32 v[62:63], v[88:89], s[8:9] op_sel_hi:[1,0]
	v_pk_mul_f32 v[88:89], v[42:43], s[8:9] op_sel_hi:[1,0]
	v_cvt_f32_i32_e32 v43, v57
	v_cvt_f32_i32_e32 v42, v56
	v_pk_mul_f32 v[56:57], v[26:27], s[8:9] op_sel_hi:[1,0]
	v_cvt_f32_i32_e32 v27, v41
	v_cvt_f32_i32_e32 v26, v40
	v_pk_mul_f32 v[40:41], v[10:11], s[8:9] op_sel_hi:[1,0]
	v_cvt_f32_i32_e32 v11, v25
	v_cvt_f32_i32_e32 v10, v24
	v_pk_mul_f32 v[14:15], v[16:17], s[8:9] op_sel_hi:[1,0]
	v_pk_mul_f32 v[16:17], v[22:23], s[8:9] op_sel_hi:[1,0]
	v_cvt_f32_i32_e32 v7, v7
	v_cvt_f32_i32_e32 v6, v6
	v_cvt_f32_i32_e32 v9, v9
	v_cvt_f32_i32_e32 v8, v8
	v_cvt_f32_i32_e32 v23, v3
	v_cvt_f32_i32_e32 v25, v5
	v_cvt_f32_i32_e32 v24, v4
	v_cvt_f32_i32_e32 v22, v2
	v_pk_mul_f32 v[114:115], v[114:115], s[8:9] op_sel_hi:[1,0]
	v_pk_mul_f32 v[106:107], v[106:107], s[8:9] op_sel_hi:[1,0]
	v_pk_mul_f32 v[108:109], v[108:109], s[8:9] op_sel_hi:[1,0]
	v_pk_mul_f32 v[98:99], v[98:99], s[8:9] op_sel_hi:[1,0]
	v_pk_mul_f32 v[90:91], v[90:91], s[8:9] op_sel_hi:[1,0]
	v_pk_mul_f32 v[92:93], v[92:93], s[8:9] op_sel_hi:[1,0]
	v_pk_mul_f32 v[82:83], v[82:83], s[8:9] op_sel_hi:[1,0]
	v_pk_mul_f32 v[74:75], v[74:75], s[8:9] op_sel_hi:[1,0]
	v_pk_mul_f32 v[76:77], v[76:77], s[8:9] op_sel_hi:[1,0]
	v_pk_mul_f32 v[50:51], v[50:51], s[8:9] op_sel_hi:[1,0]
	v_pk_mul_f32 v[42:43], v[42:43], s[8:9] op_sel_hi:[1,0]
	v_pk_mul_f32 v[44:45], v[44:45], s[8:9] op_sel_hi:[1,0]
	v_pk_mul_f32 v[34:35], v[34:35], s[8:9] op_sel_hi:[1,0]
	v_pk_mul_f32 v[26:27], v[26:27], s[8:9] op_sel_hi:[1,0]
	v_pk_mul_f32 v[28:29], v[28:29], s[8:9] op_sel_hi:[1,0]
	v_pk_mul_f32 v[18:19], v[18:19], s[8:9] op_sel_hi:[1,0]
	v_pk_mul_f32 v[10:11], v[10:11], s[8:9] op_sel_hi:[1,0]
	v_pk_mul_f32 v[12:13], v[12:13], s[8:9] op_sel_hi:[1,0]
	v_pk_mul_f32 v[2:3], v[8:9], s[8:9] op_sel_hi:[1,0]
	v_pk_mul_f32 v[4:5], v[6:7], s[8:9] op_sel_hi:[1,0]
	v_pk_mul_f32 v[6:7], v[24:25], s[8:9] op_sel_hi:[1,0]
	v_pk_mul_f32 v[8:9], v[22:23], s[8:9] op_sel_hi:[1,0]
	s_and_b64 vcc, exec, s[4:5]
	s_cbranch_vccz .LBB0_409

; #define PG8_STAGE(bufoff, gbase, X) do { _Pragma("unroll") for (int _i = 0; _i < 2; ++_i) { \
;         const char* gp_ = (const char*)(gbase) + (_i ? rs##X : (size_t)0); const unsigned la_ = (unsigned)(size_t)(lds + (bufoff) + ldsw + _i * 8192); \
;         asm volatile("s_mov_b32 m0, %2\n\ts_nop 0\n\tglobal_load_lds_dwordx4 %0, %1" :: "v"(voff##X), "s"(gp_), "s"(la_) : "memory", "m0"); } } while (0)
; #define PG8_LDA(dst, b, h) do { _Pragma("unroll") for (int m = 0; m < 4; ++m) _Pragma("unroll") for (int k = 0; k < 2; ++k) dst[m][k] = *(const LAS bf16x8*)(lds + PG8_SA(b, h) + aoff + m * 2048 + k * 1024); } while (0)
; #define PG8_LDB(dst, b, h) do { _Pragma("unroll") for (int n = 0; n < 2; ++n) _Pragma("unroll") for (int k = 0; k < 2; ++k) dst[n][k] = *(const LAS bf16x8*)(lds + PG8_SB(b, h) + boff + n * 2048 + k * 1024); } while (0)
; #define PG8_WAIT_V(n) asm volatile("s_waitcnt vmcnt(" #n ")" ::: "memory")
; #define PG8_WAIT_L(n) asm volatile("s_waitcnt lgkmcnt(" #n ")" ::: "memory")
; #define PG8_BAR __builtin_amdgcn_s_barrier()
; #define PG8_SCHED __builtin_amdgcn_sched_barrier(0)
; template <class Epi>
; __device__ __forceinline__ void gemm_phase(LAS unsigned char* lds, const Gemm g_in, const StaticOrder& S, const Epi& E) {
;     ...
;             const bool last = (t == nt - 2);
;             const char* a1 = cA + (size_t)(t + 1) * kstep;
;             const char* a2 = last ? nA : cA + (size_t)(t + 2) * kstep; const char* b2 = last ? nB : cB + (size_t)(t + 2) * kstep;
;             const char* a3 = a2 + kstep; const char* b3 = b2 + kstep;
;             PG8_LDB(B0, 0, 0); PG8_LDB(B1, 0, 1); PG8_SCHED; PG8_LDA(At, 0, 0); PG8_STAGE(PG8_SA(1, 1), a1 + hsA, A);
;             PG8_WAIT_V(8); PG8_WAIT_L(0); PG8_BAR; PG8_MMA(0, 0, At, B0); PG8_MMA(0, 1, At, B1); PG8_BAR; PG8_SCHED;
;             PG8_LDA(At, 0, 1); PG8_STAGE(PG8_SB(0, 0), b2, B); PG8_STAGE(PG8_SB(0, 1), b2 + hsB, B); PG8_STAGE(PG8_SA(0, 0), a2, A);
.LBB0_751:
	ds_read_b128 v[130:133], v157
	ds_read_b128 v[134:137], v157 offset:1024
	ds_read_b128 v[142:145], v157 offset:2048
	ds_read_b128 v[146:149], v157 offset:3072
	ds_read_b128 v[168:171], v158
	ds_read_b128 v[172:175], v158 offset:1024
	ds_read_b128 v[184:187], v158 offset:2048
	ds_read_b128 v[188:191], v158 offset:3072
	s_add_i32 s62, s24, 2
	s_add_u32 s26, s22, 0xfffa0080
	s_addc_u32 s25, s23, -1
	s_cmp_eq_u32 s55, s24
	s_cselect_b32 s24, s11, s26
	s_cselect_b32 s25, s1, s25
	s_cselect_b32 s28, s59, s60
	s_cselect_b32 s29, s58, s61
	s_add_u32 s26, s24, 0x80
	s_addc_u32 s27, s25, 0
	ds_read_b128 v[192:195], v159
	ds_read_b128 v[196:199], v159 offset:1024
	ds_read_b128 v[204:207], v159 offset:2048
	ds_read_b128 v[208:211], v159 offset:3072
	ds_read_b128 v[212:215], v159 offset:4096
	ds_read_b128 v[216:219], v159 offset:5120
	ds_read_b128 v[220:223], v159 offset:6144
	ds_read_b128 v[224:227], v159 offset:7168
	s_add_u32 s64, s22, 0xfffe0000
	s_addc_u32 s65, s23, -1
	s_mov_b32 m0, s56
	s_nop 0
	global_load_lds_dwordx4 v1, s[64:65]
	s_nop 0
	s_mov_b32 m0, s57
	s_nop 0
	global_load_lds_dwordx4 v1, s[22:23]
	s_waitcnt vmcnt(8)
	s_waitcnt lgkmcnt(0)
	s_barrier
	s_setprio 1
	s_waitcnt lgkmcnt(7)
	v_mfma_f32_16x16x32_bf16 v[126:129], v[130:133], v[192:195], v[126:129]
	v_mfma_f32_16x16x32_bf16 v[122:125], v[142:145], v[192:195], v[122:125]
	s_waitcnt lgkmcnt(5)
	v_mfma_f32_16x16x32_bf16 v[118:121], v[130:133], v[204:207], v[118:121]
	v_mfma_f32_16x16x32_bf16 v[114:117], v[142:145], v[204:207], v[114:117]
	s_waitcnt lgkmcnt(3)
	v_mfma_f32_16x16x32_bf16 v[110:113], v[130:133], v[212:215], v[110:113]
	v_mfma_f32_16x16x32_bf16 v[106:109], v[142:145], v[212:215], v[106:109]
	s_waitcnt lgkmcnt(1)
	v_mfma_f32_16x16x32_bf16 v[102:105], v[130:133], v[220:223], v[102:105]
	v_mfma_f32_16x16x32_bf16 v[94:97], v[142:145], v[220:223], v[94:97]
	v_mfma_f32_16x16x32_bf16 v[126:129], v[134:137], v[196:199], v[126:129]
	v_mfma_f32_16x16x32_bf16 v[122:125], v[146:149], v[196:199], v[122:125]
	v_mfma_f32_16x16x32_bf16 v[118:121], v[134:137], v[208:211], v[118:121]
	v_mfma_f32_16x16x32_bf16 v[114:117], v[146:149], v[208:211], v[114:117]
	v_mfma_f32_16x16x32_bf16 v[110:113], v[134:137], v[216:219], v[110:113]
	v_mfma_f32_16x16x32_bf16 v[106:109], v[146:149], v[216:219], v[106:109]
	s_waitcnt lgkmcnt(0)
	v_mfma_f32_16x16x32_bf16 v[102:105], v[134:137], v[224:227], v[102:105]
	v_mfma_f32_16x16x32_bf16 v[94:97], v[146:149], v[224:227], v[94:97]
	s_setprio 0
	s_setprio 1
	v_mfma_f32_16x16x32_bf16 v[62:65], v[168:171], v[192:195], v[62:65]
	v_mfma_f32_16x16x32_bf16 v[58:61], v[184:187], v[192:195], v[58:61]
	v_mfma_f32_16x16x32_bf16 v[54:57], v[168:171], v[204:207], v[54:57]
	v_mfma_f32_16x16x32_bf16 v[50:53], v[184:187], v[204:207], v[50:53]
	v_mfma_f32_16x16x32_bf16 v[46:49], v[168:171], v[212:215], v[46:49]
	v_mfma_f32_16x16x32_bf16 v[42:45], v[184:187], v[212:215], v[42:45]
	v_mfma_f32_16x16x32_bf16 v[38:41], v[168:171], v[220:223], v[38:41]
	v_mfma_f32_16x16x32_bf16 v[34:37], v[184:187], v[220:223], v[34:37]
	v_mfma_f32_16x16x32_bf16 v[62:65], v[172:175], v[196:199], v[62:65]
	v_mfma_f32_16x16x32_bf16 v[58:61], v[188:191], v[196:199], v[58:61]
	v_mfma_f32_16x16x32_bf16 v[54:57], v[172:175], v[208:211], v[54:57]
	v_mfma_f32_16x16x32_bf16 v[50:53], v[188:191], v[208:211], v[50:53]
	v_mfma_f32_16x16x32_bf16 v[46:49], v[172:175], v[216:219], v[46:49]
	v_mfma_f32_16x16x32_bf16 v[42:45], v[188:191], v[216:219], v[42:45]
	v_mfma_f32_16x16x32_bf16 v[38:41], v[172:175], v[224:227], v[38:41]
	v_mfma_f32_16x16x32_bf16 v[34:37], v[188:191], v[224:227], v[34:37]
	s_setprio 0
	s_add_u32 s64, s28, 0x8000
	s_barrier
	ds_read_b128 v[192:195], v159 offset:16384
	ds_read_b128 v[196:199], v159 offset:17408
	ds_read_b128 v[204:207], v159 offset:18432
	ds_read_b128 v[208:211], v159 offset:19456
	ds_read_b128 v[212:215], v159 offset:20480
	ds_read_b128 v[216:219], v159 offset:21504
	ds_read_b128 v[220:223], v159 offset:22528
	ds_read_b128 v[224:227], v159 offset:23552
	s_mov_b32 m0, s42
	s_nop 0
	global_load_lds_dwordx4 v154, s[28:29]
	s_addc_u32 s65, s29, 0
	s_mov_b32 m0, s43
	s_nop 0
	global_load_lds_dwordx4 v154, s[64:65]
	s_add_u32 s64, s28, 0x10000
	s_addc_u32 s65, s29, 0
	s_mov_b32 m0, s44
	s_nop 0
	global_load_lds_dwordx4 v154, s[64:65]
	s_add_u32 s64, s28, 0x18000
	s_addc_u32 s65, s29, 0
	s_mov_b32 m0, s45
	s_nop 0
	global_load_lds_dwordx4 v154, s[64:65]
	s_add_u32 s64, s24, 0x20000
	s_mov_b32 m0, s41
	s_nop 0
	global_load_lds_dwordx4 v1, s[24:25]
	s_addc_u32 s65, s25, 0
	s_mov_b32 m0, s46
	s_nop 0
	global_load_lds_dwordx4 v1, s[64:65]
	s_waitcnt vmcnt(8)
	s_waitcnt lgkmcnt(0)
	s_barrier
; #define PG8_STAGE(bufoff, gbase, X) do { _Pragma("unroll") for (int _i = 0; _i < 2; ++_i) { \
;         const char* gp_ = (const char*)(gbase) + (_i ? rs##X : (size_t)0); const unsigned la_ = (unsigned)(size_t)(lds + (bufoff) + ldsw + _i * 8192); \
;         asm volatile("s_mov_b32 m0, %2\n\ts_nop 0\n\tglobal_load_lds_dwordx4 %0, %1" :: "v"(voff##X), "s"(gp_), "s"(la_) : "memory", "m0"); } } while (0)
; #define PG8_LDA(dst, b, h) do { _Pragma("unroll") for (int m = 0; m < 4; ++m) _Pragma("unroll") for (int k = 0; k < 2; ++k) dst[m][k] = *(const LAS bf16x8*)(lds + PG8_SA(b, h) + aoff + m * 2048 + k * 1024); } while (0)
; #define PG8_LDB(dst, b, h) do { _Pragma("unroll") for (int n = 0; n < 2; ++n) _Pragma("unroll") for (int k = 0; k < 2; ++k) dst[n][k] = *(const LAS bf16x8*)(lds + PG8_SB(b, h) + boff + n * 2048 + k * 1024); } while (0)
; #define PG8_WAIT_V(n) asm volatile("s_waitcnt vmcnt(" #n ")" ::: "memory")
; #define PG8_WAIT_L(n) asm volatile("s_waitcnt lgkmcnt(" #n ")" ::: "memory")
; #define PG8_BAR __builtin_amdgcn_s_barrier()
; #define PG8_SCHED __builtin_amdgcn_sched_barrier(0)
; template <class Epi>
; __device__ __forceinline__ void gemm_phase(LAS unsigned char* lds, const Gemm g_in, const StaticOrder& S, const Epi& E) {
;     ...
;             PG8_WAIT_V(8); PG8_WAIT_L(0); PG8_BAR; PG8_MMA(1, 0, At, B0); PG8_MMA(1, 1, At, B1); PG8_BAR; PG8_SCHED;
;             PG8_LDB(B0, 1, 0); PG8_LDB(B1, 1, 1); PG8_SCHED; PG8_LDA(At, 1, 0); PG8_STAGE(PG8_SA(0, 1), a2 + hsA, A);
;             PG8_WAIT_V(8); PG8_WAIT_L(0); PG8_BAR; PG8_MMA(0, 0, At, B0); PG8_MMA(0, 1, At, B1); PG8_BAR; PG8_SCHED;
	s_setprio 1
	s_waitcnt lgkmcnt(7)
	v_mfma_f32_16x16x32_bf16 v[98:101], v[130:133], v[192:195], v[98:101]
	v_mfma_f32_16x16x32_bf16 v[90:93], v[142:145], v[192:195], v[90:93]
	s_waitcnt lgkmcnt(5)
	v_mfma_f32_16x16x32_bf16 v[86:89], v[130:133], v[204:207], v[86:89]
	v_mfma_f32_16x16x32_bf16 v[82:85], v[142:145], v[204:207], v[82:85]
	s_waitcnt lgkmcnt(3)
	v_mfma_f32_16x16x32_bf16 v[78:81], v[130:133], v[212:215], v[78:81]
	v_mfma_f32_16x16x32_bf16 v[74:77], v[142:145], v[212:215], v[74:77]
	s_waitcnt lgkmcnt(1)
	v_mfma_f32_16x16x32_bf16 v[70:73], v[130:133], v[220:223], v[70:73]
	v_mfma_f32_16x16x32_bf16 v[66:69], v[142:145], v[220:223], v[66:69]
	v_mfma_f32_16x16x32_bf16 v[98:101], v[134:137], v[196:199], v[98:101]
	v_mfma_f32_16x16x32_bf16 v[90:93], v[146:149], v[196:199], v[90:93]
	v_mfma_f32_16x16x32_bf16 v[86:89], v[134:137], v[208:211], v[86:89]
	v_mfma_f32_16x16x32_bf16 v[82:85], v[146:149], v[208:211], v[82:85]
	v_mfma_f32_16x16x32_bf16 v[78:81], v[134:137], v[216:219], v[78:81]
	v_mfma_f32_16x16x32_bf16 v[74:77], v[146:149], v[216:219], v[74:77]
	s_waitcnt lgkmcnt(0)
	v_mfma_f32_16x16x32_bf16 v[70:73], v[134:137], v[224:227], v[70:73]
	v_mfma_f32_16x16x32_bf16 v[66:69], v[146:149], v[224:227], v[66:69]
	s_setprio 0
	s_setprio 1
	v_mfma_f32_16x16x32_bf16 v[30:33], v[168:171], v[192:195], v[30:33]
	v_mfma_f32_16x16x32_bf16 v[26:29], v[184:187], v[192:195], v[26:29]
	v_mfma_f32_16x16x32_bf16 v[22:25], v[168:171], v[204:207], v[22:25]
	v_mfma_f32_16x16x32_bf16 v[18:21], v[184:187], v[204:207], v[18:21]
	v_mfma_f32_16x16x32_bf16 v[14:17], v[168:171], v[212:215], v[14:17]
	v_mfma_f32_16x16x32_bf16 v[10:13], v[184:187], v[212:215], v[10:13]
	v_mfma_f32_16x16x32_bf16 v[6:9], v[168:171], v[220:223], v[6:9]
	v_mfma_f32_16x16x32_bf16 v[2:5], v[184:187], v[220:223], v[2:5]
	v_mfma_f32_16x16x32_bf16 v[30:33], v[172:175], v[196:199], v[30:33]
	v_mfma_f32_16x16x32_bf16 v[26:29], v[188:191], v[196:199], v[26:29]
	v_mfma_f32_16x16x32_bf16 v[22:25], v[172:175], v[208:211], v[22:25]
	v_mfma_f32_16x16x32_bf16 v[18:21], v[188:191], v[208:211], v[18:21]
	v_mfma_f32_16x16x32_bf16 v[14:17], v[172:175], v[216:219], v[14:17]
	v_mfma_f32_16x16x32_bf16 v[10:13], v[188:191], v[216:219], v[10:13]
	v_mfma_f32_16x16x32_bf16 v[6:9], v[172:175], v[224:227], v[6:9]
	v_mfma_f32_16x16x32_bf16 v[2:5], v[188:191], v[224:227], v[2:5]
	s_setprio 0
	s_barrier
	ds_read_b128 v[130:133], v160
	ds_read_b128 v[134:137], v160 offset:1024
	ds_read_b128 v[142:145], v160 offset:2048
	ds_read_b128 v[146:149], v160 offset:3072
	ds_read_b128 v[168:171], v161
	ds_read_b128 v[172:175], v161 offset:1024
	ds_read_b128 v[184:187], v161 offset:2048
	ds_read_b128 v[188:191], v161 offset:3072
	ds_read_b128 v[192:195], v159 offset:32768
	ds_read_b128 v[196:199], v159 offset:33792
	ds_read_b128 v[204:207], v159 offset:34816
	ds_read_b128 v[208:211], v159 offset:35840
	ds_read_b128 v[212:215], v159 offset:36864
	ds_read_b128 v[216:219], v159 offset:37888
	ds_read_b128 v[220:223], v159 offset:38912
	ds_read_b128 v[224:227], v159 offset:39936
	s_add_u32 s64, s24, 0x40000
	s_addc_u32 s65, s25, 0
	s_mov_b32 m0, s47
	s_nop 0
	global_load_lds_dwordx4 v1, s[64:65]
	s_add_u32 s64, s24, 0x60000
	s_addc_u32 s65, s25, 0
	s_mov_b32 m0, s48
	s_nop 0
	global_load_lds_dwordx4 v1, s[64:65]
	s_waitcnt vmcnt(8)
	s_waitcnt lgkmcnt(0)
	s_barrier
	s_setprio 1
	s_waitcnt lgkmcnt(7)
	v_mfma_f32_16x16x32_bf16 v[126:129], v[130:133], v[192:195], v[126:129]
	v_mfma_f32_16x16x32_bf16 v[122:125], v[142:145], v[192:195], v[122:125]
	s_waitcnt lgkmcnt(5)
	v_mfma_f32_16x16x32_bf16 v[118:121], v[130:133], v[204:207], v[118:121]
	v_mfma_f32_16x16x32_bf16 v[114:117], v[142:145], v[204:207], v[114:117]
	s_waitcnt lgkmcnt(3)
	v_mfma_f32_16x16x32_bf16 v[110:113], v[130:133], v[212:215], v[110:113]
	v_mfma_f32_16x16x32_bf16 v[106:109], v[142:145], v[212:215], v[106:109]
	s_waitcnt lgkmcnt(1)
	v_mfma_f32_16x16x32_bf16 v[102:105], v[130:133], v[220:223], v[102:105]
	v_mfma_f32_16x16x32_bf16 v[94:97], v[142:145], v[220:223], v[94:97]
	v_mfma_f32_16x16x32_bf16 v[126:129], v[134:137], v[196:199], v[126:129]
	v_mfma_f32_16x16x32_bf16 v[122:125], v[146:149], v[196:199], v[122:125]
	v_mfma_f32_16x16x32_bf16 v[118:121], v[134:137], v[208:211], v[118:121]
	v_mfma_f32_16x16x32_bf16 v[114:117], v[146:149], v[208:211], v[114:117]
	v_mfma_f32_16x16x32_bf16 v[110:113], v[134:137], v[216:219], v[110:113]
	v_mfma_f32_16x16x32_bf16 v[106:109], v[146:149], v[216:219], v[106:109]
	s_waitcnt lgkmcnt(0)
	v_mfma_f32_16x16x32_bf16 v[102:105], v[134:137], v[224:227], v[102:105]
	v_mfma_f32_16x16x32_bf16 v[94:97], v[146:149], v[224:227], v[94:97]
	s_setprio 0
	s_setprio 1
	v_mfma_f32_16x16x32_bf16 v[62:65], v[168:171], v[192:195], v[62:65]
	v_mfma_f32_16x16x32_bf16 v[58:61], v[184:187], v[192:195], v[58:61]
	v_mfma_f32_16x16x32_bf16 v[54:57], v[168:171], v[204:207], v[54:57]
	v_mfma_f32_16x16x32_bf16 v[50:53], v[184:187], v[204:207], v[50:53]
	v_mfma_f32_16x16x32_bf16 v[46:49], v[168:171], v[212:215], v[46:49]
	v_mfma_f32_16x16x32_bf16 v[42:45], v[184:187], v[212:215], v[42:45]
	v_mfma_f32_16x16x32_bf16 v[38:41], v[168:171], v[220:223], v[38:41]
	v_mfma_f32_16x16x32_bf16 v[34:37], v[184:187], v[220:223], v[34:37]
	v_mfma_f32_16x16x32_bf16 v[62:65], v[172:175], v[196:199], v[62:65]
	v_mfma_f32_16x16x32_bf16 v[58:61], v[188:191], v[196:199], v[58:61]
	v_mfma_f32_16x16x32_bf16 v[54:57], v[172:175], v[208:211], v[54:57]
	v_mfma_f32_16x16x32_bf16 v[50:53], v[188:191], v[208:211], v[50:53]
	v_mfma_f32_16x16x32_bf16 v[46:49], v[172:175], v[216:219], v[46:49]
	v_mfma_f32_16x16x32_bf16 v[42:45], v[188:191], v[216:219], v[42:45]
	v_mfma_f32_16x16x32_bf16 v[38:41], v[172:175], v[224:227], v[38:41]
	v_mfma_f32_16x16x32_bf16 v[34:37], v[188:191], v[224:227], v[34:37]
	s_setprio 0
	s_add_u32 s64, s28, 0x80
	s_addc_u32 s65, s29, 0
	s_barrier
; #define PG8_STAGE(bufoff, gbase, X) do { _Pragma("unroll") for (int _i = 0; _i < 2; ++_i) { \
;         const char* gp_ = (const char*)(gbase) + (_i ? rs##X : (size_t)0); const unsigned la_ = (unsigned)(size_t)(lds + (bufoff) + ldsw + _i * 8192); \
;         asm volatile("s_mov_b32 m0, %2\n\ts_nop 0\n\tglobal_load_lds_dwordx4 %0, %1" :: "v"(voff##X), "s"(gp_), "s"(la_) : "memory", "m0"); } } while (0)
; #define PG8_LDA(dst, b, h) do { _Pragma("unroll") for (int m = 0; m < 4; ++m) _Pragma("unroll") for (int k = 0; k < 2; ++k) dst[m][k] = *(const LAS bf16x8*)(lds + PG8_SA(b, h) + aoff + m * 2048 + k * 1024); } while (0)
; #define PG8_WAIT_V(n) asm volatile("s_waitcnt vmcnt(" #n ")" ::: "memory")
; #define PG8_WAIT_L(n) asm volatile("s_waitcnt lgkmcnt(" #n ")" ::: "memory")
; #define PG8_BAR __builtin_amdgcn_s_barrier()
; #define PG8_SCHED __builtin_amdgcn_sched_barrier(0)
; template <class Epi>
; __device__ __forceinline__ void gemm_phase(LAS unsigned char* lds, const Gemm g_in, const StaticOrder& S, const Epi& E) {
;     ...
;         for (int t = 0; t < nt; t += 2) {
;     ...
;             PG8_LDA(At, 1, 1); PG8_STAGE(PG8_SB(1, 0), b3, B); PG8_STAGE(PG8_SB(1, 1), b3 + hsB, B); PG8_STAGE(PG8_SA(1, 0), a3, A);
;             PG8_WAIT_V(8); PG8_WAIT_L(0); PG8_BAR; PG8_MMA(1, 0, At, B0); PG8_MMA(1, 1, At, B1); PG8_BAR; PG8_SCHED;
;         }
	ds_read_b128 v[192:195], v159 offset:49152
	ds_read_b128 v[196:199], v159 offset:50176
	ds_read_b128 v[204:207], v159 offset:51200
	ds_read_b128 v[208:211], v159 offset:52224
	ds_read_b128 v[212:215], v159 offset:53248
	ds_read_b128 v[216:219], v159 offset:54272
	ds_read_b128 v[220:223], v159 offset:55296
	ds_read_b128 v[224:227], v159 offset:56320
	s_mov_b32 m0, s49
	s_nop 0
	global_load_lds_dwordx4 v154, s[64:65]
	s_add_u32 s64, s28, 0x8080
	s_addc_u32 s65, s29, 0
	s_mov_b32 m0, s50
	s_nop 0
	global_load_lds_dwordx4 v154, s[64:65]
	s_add_u32 s64, s28, 0x10080
	s_addc_u32 s65, s29, 0
	s_mov_b32 m0, s53
	s_nop 0
	global_load_lds_dwordx4 v154, s[64:65]
	s_add_u32 s28, s28, 0x18080
	s_addc_u32 s29, s29, 0
	s_mov_b32 m0, s54
	s_nop 0
	global_load_lds_dwordx4 v154, s[28:29]
	s_add_u32 s24, s24, 0x20080
	s_mov_b32 m0, s51
	s_nop 0
	global_load_lds_dwordx4 v1, s[26:27]
	s_addc_u32 s25, s25, 0
	s_mov_b32 m0, s52
	s_nop 0
	global_load_lds_dwordx4 v1, s[24:25]
	s_waitcnt vmcnt(8)
	s_waitcnt lgkmcnt(0)
	s_barrier
	s_setprio 1
	s_waitcnt lgkmcnt(7)
	v_mfma_f32_16x16x32_bf16 v[98:101], v[130:133], v[192:195], v[98:101]
	v_mfma_f32_16x16x32_bf16 v[90:93], v[142:145], v[192:195], v[90:93]
	s_waitcnt lgkmcnt(5)
	v_mfma_f32_16x16x32_bf16 v[86:89], v[130:133], v[204:207], v[86:89]
	v_mfma_f32_16x16x32_bf16 v[82:85], v[142:145], v[204:207], v[82:85]
	s_waitcnt lgkmcnt(3)
	v_mfma_f32_16x16x32_bf16 v[78:81], v[130:133], v[212:215], v[78:81]
	v_mfma_f32_16x16x32_bf16 v[74:77], v[142:145], v[212:215], v[74:77]
	s_waitcnt lgkmcnt(1)
	v_mfma_f32_16x16x32_bf16 v[70:73], v[130:133], v[220:223], v[70:73]
	v_mfma_f32_16x16x32_bf16 v[66:69], v[142:145], v[220:223], v[66:69]
	v_mfma_f32_16x16x32_bf16 v[98:101], v[134:137], v[196:199], v[98:101]
	v_mfma_f32_16x16x32_bf16 v[90:93], v[146:149], v[196:199], v[90:93]
	v_mfma_f32_16x16x32_bf16 v[86:89], v[134:137], v[208:211], v[86:89]
	v_mfma_f32_16x16x32_bf16 v[82:85], v[146:149], v[208:211], v[82:85]
	v_mfma_f32_16x16x32_bf16 v[78:81], v[134:137], v[216:219], v[78:81]
	v_mfma_f32_16x16x32_bf16 v[74:77], v[146:149], v[216:219], v[74:77]
	s_waitcnt lgkmcnt(0)
	v_mfma_f32_16x16x32_bf16 v[70:73], v[134:137], v[224:227], v[70:73]
	v_mfma_f32_16x16x32_bf16 v[66:69], v[146:149], v[224:227], v[66:69]
	s_setprio 0
	s_setprio 1
	v_mfma_f32_16x16x32_bf16 v[30:33], v[168:171], v[192:195], v[30:33]
	v_mfma_f32_16x16x32_bf16 v[26:29], v[184:187], v[192:195], v[26:29]
	v_mfma_f32_16x16x32_bf16 v[22:25], v[168:171], v[204:207], v[22:25]
	v_mfma_f32_16x16x32_bf16 v[18:21], v[184:187], v[204:207], v[18:21]
	v_mfma_f32_16x16x32_bf16 v[14:17], v[168:171], v[212:215], v[14:17]
	v_mfma_f32_16x16x32_bf16 v[10:13], v[184:187], v[212:215], v[10:13]
	v_mfma_f32_16x16x32_bf16 v[6:9], v[168:171], v[220:223], v[6:9]
	v_mfma_f32_16x16x32_bf16 v[2:5], v[184:187], v[220:223], v[2:5]
	v_mfma_f32_16x16x32_bf16 v[30:33], v[172:175], v[196:199], v[30:33]
	v_mfma_f32_16x16x32_bf16 v[26:29], v[188:191], v[196:199], v[26:29]
	v_mfma_f32_16x16x32_bf16 v[22:25], v[172:175], v[208:211], v[22:25]
	v_mfma_f32_16x16x32_bf16 v[18:21], v[188:191], v[208:211], v[18:21]
	v_mfma_f32_16x16x32_bf16 v[14:17], v[172:175], v[216:219], v[14:17]
	v_mfma_f32_16x16x32_bf16 v[10:13], v[188:191], v[216:219], v[10:13]
	v_mfma_f32_16x16x32_bf16 v[6:9], v[172:175], v[224:227], v[6:9]
	v_mfma_f32_16x16x32_bf16 v[2:5], v[188:191], v[224:227], v[2:5]
	s_setprio 0
	s_add_u32 s60, s60, 0x100
	s_addc_u32 s61, s61, 0
	s_add_u32 s22, s22, 0x100
	s_addc_u32 s23, s23, 0
	s_cmp_ge_i32 s62, s37
	s_mov_b32 s24, s62
	s_barrier
	s_cbranch_scc0 .LBB0_751
	s_and_b64 vcc, exec, s[14:15]
	s_cbranch_vccz .LBB0_754

; #define PG8_STAGE(bufoff, gbase, X) do { _Pragma("unroll") for (int _i = 0; _i < 2; ++_i) { \
;         const char* gp_ = (const char*)(gbase) + (_i ? rs##X : (size_t)0); const unsigned la_ = (unsigned)(size_t)(lds + (bufoff) + ldsw + _i * 8192); \
;         asm volatile("s_mov_b32 m0, %2\n\ts_nop 0\n\tglobal_load_lds_dwordx4 %0, %1" :: "v"(voff##X), "s"(gp_), "s"(la_) : "memory", "m0"); } } while (0)
; #define PG8_LDA(dst, b, h) do { _Pragma("unroll") for (int m = 0; m < 4; ++m) _Pragma("unroll") for (int k = 0; k < 2; ++k) dst[m][k] = *(const LAS bf16x8*)(lds + PG8_SA(b, h) + aoff + m * 2048 + k * 1024); } while (0)
; #define PG8_LDB(dst, b, h) do { _Pragma("unroll") for (int n = 0; n < 2; ++n) _Pragma("unroll") for (int k = 0; k < 2; ++k) dst[n][k] = *(const LAS bf16x8*)(lds + PG8_SB(b, h) + boff + n * 2048 + k * 1024); } while (0)
; #define PG8_WAIT_V(n) asm volatile("s_waitcnt vmcnt(" #n ")" ::: "memory")
; #define PG8_WAIT_L(n) asm volatile("s_waitcnt lgkmcnt(" #n ")" ::: "memory")
; #define PG8_BAR __builtin_amdgcn_s_barrier()
; #define PG8_SCHED __builtin_amdgcn_sched_barrier(0)
; template <class Epi>
; __device__ __forceinline__ void gemm_phase(LAS unsigned char* lds, const Gemm g_in, const StaticOrder& S, const Epi& E) {
;     ...
;             const bool last = (t == nt - 2);
;             const char* a1 = cA + (size_t)(t + 1) * kstep;
;             const char* a2 = last ? nA : cA + (size_t)(t + 2) * kstep; const char* b2 = last ? nB : cB + (size_t)(t + 2) * kstep;
;             const char* a3 = a2 + kstep; const char* b3 = b2 + kstep;
;             PG8_LDB(B0, 0, 0); PG8_LDB(B1, 0, 1); PG8_SCHED; PG8_LDA(At, 0, 0); PG8_STAGE(PG8_SA(1, 1), a1 + hsA, A);
;             PG8_WAIT_V(8); PG8_WAIT_L(0); PG8_BAR; PG8_MMA(0, 0, At, B0); PG8_MMA(0, 1, At, B1); PG8_BAR; PG8_SCHED;
;             PG8_LDA(At, 0, 1); PG8_STAGE(PG8_SB(0, 0), b2, B); PG8_STAGE(PG8_SB(0, 1), b2 + hsB, B); PG8_STAGE(PG8_SA(0, 0), a2, A);
.LBB0_769:
	ds_read_b128 v[130:133], v147
	ds_read_b128 v[134:137], v147 offset:1024
	ds_read_b128 v[154:157], v147 offset:2048
	ds_read_b128 v[158:161], v147 offset:3072
	ds_read_b128 v[168:171], v148
	ds_read_b128 v[172:175], v148 offset:1024
	ds_read_b128 v[184:187], v148 offset:2048
	ds_read_b128 v[188:191], v148 offset:3072
	s_add_i32 s64, s10, 2
	s_add_u32 s28, s6, 0xfffa0080
	s_addc_u32 s11, s7, -1
	s_cmp_eq_u32 s57, s10
	s_cselect_b32 s10, s23, s28
	s_cselect_b32 s11, s21, s11
	s_cselect_b32 s30, s61, s62
	s_cselect_b32 s31, s60, s63
	s_add_u32 s28, s10, 0x80
	s_addc_u32 s29, s11, 0
	ds_read_b128 v[192:195], v149
	ds_read_b128 v[196:199], v149 offset:1024
	ds_read_b128 v[204:207], v149 offset:2048
	ds_read_b128 v[208:211], v149 offset:3072
	ds_read_b128 v[212:215], v149 offset:4096
	ds_read_b128 v[216:219], v149 offset:5120
	ds_read_b128 v[220:223], v149 offset:6144
	ds_read_b128 v[224:227], v149 offset:7168
	s_add_u32 s66, s6, 0xfffe0000
	s_addc_u32 s67, s7, -1
	s_mov_b32 m0, s58
	s_nop 0
	global_load_lds_dwordx4 v1, s[66:67]
	s_nop 0
	s_mov_b32 m0, s59
	s_nop 0
	global_load_lds_dwordx4 v1, s[6:7]
	s_waitcnt vmcnt(8)
	s_waitcnt lgkmcnt(0)
	s_barrier
	s_setprio 1
	s_waitcnt lgkmcnt(7)
	v_mfma_f32_16x16x32_bf16 v[126:129], v[130:133], v[192:195], v[126:129]
	v_mfma_f32_16x16x32_bf16 v[122:125], v[154:157], v[192:195], v[122:125]
	s_waitcnt lgkmcnt(5)
	v_mfma_f32_16x16x32_bf16 v[118:121], v[130:133], v[204:207], v[118:121]
	v_mfma_f32_16x16x32_bf16 v[114:117], v[154:157], v[204:207], v[114:117]
	s_waitcnt lgkmcnt(3)
	v_mfma_f32_16x16x32_bf16 v[110:113], v[130:133], v[212:215], v[110:113]
	v_mfma_f32_16x16x32_bf16 v[106:109], v[154:157], v[212:215], v[106:109]
	s_waitcnt lgkmcnt(1)
	v_mfma_f32_16x16x32_bf16 v[102:105], v[130:133], v[220:223], v[102:105]
	v_mfma_f32_16x16x32_bf16 v[98:101], v[154:157], v[220:223], v[98:101]
	v_mfma_f32_16x16x32_bf16 v[126:129], v[134:137], v[196:199], v[126:129]
	v_mfma_f32_16x16x32_bf16 v[122:125], v[158:161], v[196:199], v[122:125]
	v_mfma_f32_16x16x32_bf16 v[118:121], v[134:137], v[208:211], v[118:121]
	v_mfma_f32_16x16x32_bf16 v[114:117], v[158:161], v[208:211], v[114:117]
	v_mfma_f32_16x16x32_bf16 v[110:113], v[134:137], v[216:219], v[110:113]
	v_mfma_f32_16x16x32_bf16 v[106:109], v[158:161], v[216:219], v[106:109]
	s_waitcnt lgkmcnt(0)
	v_mfma_f32_16x16x32_bf16 v[102:105], v[134:137], v[224:227], v[102:105]
	v_mfma_f32_16x16x32_bf16 v[98:101], v[158:161], v[224:227], v[98:101]
	s_setprio 0
	s_setprio 1
	v_mfma_f32_16x16x32_bf16 v[62:65], v[168:171], v[192:195], v[62:65]
	v_mfma_f32_16x16x32_bf16 v[58:61], v[184:187], v[192:195], v[58:61]
	v_mfma_f32_16x16x32_bf16 v[54:57], v[168:171], v[204:207], v[54:57]
	v_mfma_f32_16x16x32_bf16 v[50:53], v[184:187], v[204:207], v[50:53]
	v_mfma_f32_16x16x32_bf16 v[46:49], v[168:171], v[212:215], v[46:49]
	v_mfma_f32_16x16x32_bf16 v[42:45], v[184:187], v[212:215], v[42:45]
	v_mfma_f32_16x16x32_bf16 v[38:41], v[168:171], v[220:223], v[38:41]
	v_mfma_f32_16x16x32_bf16 v[34:37], v[184:187], v[220:223], v[34:37]
	v_mfma_f32_16x16x32_bf16 v[62:65], v[172:175], v[196:199], v[62:65]
	v_mfma_f32_16x16x32_bf16 v[58:61], v[188:191], v[196:199], v[58:61]
	v_mfma_f32_16x16x32_bf16 v[54:57], v[172:175], v[208:211], v[54:57]
	v_mfma_f32_16x16x32_bf16 v[50:53], v[188:191], v[208:211], v[50:53]
	v_mfma_f32_16x16x32_bf16 v[46:49], v[172:175], v[216:219], v[46:49]
	v_mfma_f32_16x16x32_bf16 v[42:45], v[188:191], v[216:219], v[42:45]
	v_mfma_f32_16x16x32_bf16 v[38:41], v[172:175], v[224:227], v[38:41]
	v_mfma_f32_16x16x32_bf16 v[34:37], v[188:191], v[224:227], v[34:37]
	s_setprio 0
	s_add_u32 s66, s30, 0x8000
	s_barrier
	ds_read_b128 v[192:195], v149 offset:16384
	ds_read_b128 v[196:199], v149 offset:17408
	ds_read_b128 v[204:207], v149 offset:18432
	ds_read_b128 v[208:211], v149 offset:19456
	ds_read_b128 v[212:215], v149 offset:20480
	ds_read_b128 v[216:219], v149 offset:21504
	ds_read_b128 v[220:223], v149 offset:22528
	ds_read_b128 v[224:227], v149 offset:23552
	s_mov_b32 m0, s44
	s_nop 0
	global_load_lds_dwordx4 v144, s[30:31]
	s_addc_u32 s67, s31, 0
	s_mov_b32 m0, s45
	s_nop 0
	global_load_lds_dwordx4 v144, s[66:67]
	s_add_u32 s66, s30, 0x10000
	s_addc_u32 s67, s31, 0
	s_mov_b32 m0, s46
	s_nop 0
	global_load_lds_dwordx4 v144, s[66:67]
	s_add_u32 s66, s30, 0x18000
	s_addc_u32 s67, s31, 0
	s_mov_b32 m0, s47
	s_nop 0
	global_load_lds_dwordx4 v144, s[66:67]
	s_add_u32 s66, s10, 0x20000
	s_mov_b32 m0, s43
	s_nop 0
	global_load_lds_dwordx4 v1, s[10:11]
	s_addc_u32 s67, s11, 0
	s_mov_b32 m0, s48
	s_nop 0
	global_load_lds_dwordx4 v1, s[66:67]
	s_waitcnt vmcnt(8)
	s_waitcnt lgkmcnt(0)
	s_barrier
; #define PG8_STAGE(bufoff, gbase, X) do { _Pragma("unroll") for (int _i = 0; _i < 2; ++_i) { \
;         const char* gp_ = (const char*)(gbase) + (_i ? rs##X : (size_t)0); const unsigned la_ = (unsigned)(size_t)(lds + (bufoff) + ldsw + _i * 8192); \
;         asm volatile("s_mov_b32 m0, %2\n\ts_nop 0\n\tglobal_load_lds_dwordx4 %0, %1" :: "v"(voff##X), "s"(gp_), "s"(la_) : "memory", "m0"); } } while (0)
; #define PG8_LDA(dst, b, h) do { _Pragma("unroll") for (int m = 0; m < 4; ++m) _Pragma("unroll") for (int k = 0; k < 2; ++k) dst[m][k] = *(const LAS bf16x8*)(lds + PG8_SA(b, h) + aoff + m * 2048 + k * 1024); } while (0)
; #define PG8_LDB(dst, b, h) do { _Pragma("unroll") for (int n = 0; n < 2; ++n) _Pragma("unroll") for (int k = 0; k < 2; ++k) dst[n][k] = *(const LAS bf16x8*)(lds + PG8_SB(b, h) + boff + n * 2048 + k * 1024); } while (0)
; #define PG8_WAIT_V(n) asm volatile("s_waitcnt vmcnt(" #n ")" ::: "memory")
; #define PG8_WAIT_L(n) asm volatile("s_waitcnt lgkmcnt(" #n ")" ::: "memory")
; #define PG8_BAR __builtin_amdgcn_s_barrier()
; #define PG8_SCHED __builtin_amdgcn_sched_barrier(0)
; template <class Epi>
; __device__ __forceinline__ void gemm_phase(LAS unsigned char* lds, const Gemm g_in, const StaticOrder& S, const Epi& E) {
;     ...
;             PG8_WAIT_V(8); PG8_WAIT_L(0); PG8_BAR; PG8_MMA(1, 0, At, B0); PG8_MMA(1, 1, At, B1); PG8_BAR; PG8_SCHED;
;             PG8_LDB(B0, 1, 0); PG8_LDB(B1, 1, 1); PG8_SCHED; PG8_LDA(At, 1, 0); PG8_STAGE(PG8_SA(0, 1), a2 + hsA, A);
;             PG8_WAIT_V(8); PG8_WAIT_L(0); PG8_BAR; PG8_MMA(0, 0, At, B0); PG8_MMA(0, 1, At, B1); PG8_BAR; PG8_SCHED;
	s_setprio 1
	s_waitcnt lgkmcnt(7)
	v_mfma_f32_16x16x32_bf16 v[94:97], v[130:133], v[192:195], v[94:97]
	v_mfma_f32_16x16x32_bf16 v[90:93], v[154:157], v[192:195], v[90:93]
	s_waitcnt lgkmcnt(5)
	v_mfma_f32_16x16x32_bf16 v[86:89], v[130:133], v[204:207], v[86:89]
	v_mfma_f32_16x16x32_bf16 v[82:85], v[154:157], v[204:207], v[82:85]
	s_waitcnt lgkmcnt(3)
	v_mfma_f32_16x16x32_bf16 v[78:81], v[130:133], v[212:215], v[78:81]
	v_mfma_f32_16x16x32_bf16 v[74:77], v[154:157], v[212:215], v[74:77]
	s_waitcnt lgkmcnt(1)
	v_mfma_f32_16x16x32_bf16 v[70:73], v[130:133], v[220:223], v[70:73]
	v_mfma_f32_16x16x32_bf16 v[66:69], v[154:157], v[220:223], v[66:69]
	v_mfma_f32_16x16x32_bf16 v[94:97], v[134:137], v[196:199], v[94:97]
	v_mfma_f32_16x16x32_bf16 v[90:93], v[158:161], v[196:199], v[90:93]
	v_mfma_f32_16x16x32_bf16 v[86:89], v[134:137], v[208:211], v[86:89]
	v_mfma_f32_16x16x32_bf16 v[82:85], v[158:161], v[208:211], v[82:85]
	v_mfma_f32_16x16x32_bf16 v[78:81], v[134:137], v[216:219], v[78:81]
	v_mfma_f32_16x16x32_bf16 v[74:77], v[158:161], v[216:219], v[74:77]
	s_waitcnt lgkmcnt(0)
	v_mfma_f32_16x16x32_bf16 v[70:73], v[134:137], v[224:227], v[70:73]
	v_mfma_f32_16x16x32_bf16 v[66:69], v[158:161], v[224:227], v[66:69]
	s_setprio 0
	s_setprio 1
	v_mfma_f32_16x16x32_bf16 v[30:33], v[168:171], v[192:195], v[30:33]
	v_mfma_f32_16x16x32_bf16 v[26:29], v[184:187], v[192:195], v[26:29]
	v_mfma_f32_16x16x32_bf16 v[22:25], v[168:171], v[204:207], v[22:25]
	v_mfma_f32_16x16x32_bf16 v[18:21], v[184:187], v[204:207], v[18:21]
	v_mfma_f32_16x16x32_bf16 v[14:17], v[168:171], v[212:215], v[14:17]
	v_mfma_f32_16x16x32_bf16 v[10:13], v[184:187], v[212:215], v[10:13]
	v_mfma_f32_16x16x32_bf16 v[6:9], v[168:171], v[220:223], v[6:9]
	v_mfma_f32_16x16x32_bf16 v[2:5], v[184:187], v[220:223], v[2:5]
	v_mfma_f32_16x16x32_bf16 v[30:33], v[172:175], v[196:199], v[30:33]
	v_mfma_f32_16x16x32_bf16 v[26:29], v[188:191], v[196:199], v[26:29]
	v_mfma_f32_16x16x32_bf16 v[22:25], v[172:175], v[208:211], v[22:25]
	v_mfma_f32_16x16x32_bf16 v[18:21], v[188:191], v[208:211], v[18:21]
	v_mfma_f32_16x16x32_bf16 v[14:17], v[172:175], v[216:219], v[14:17]
	v_mfma_f32_16x16x32_bf16 v[10:13], v[188:191], v[216:219], v[10:13]
	v_mfma_f32_16x16x32_bf16 v[6:9], v[172:175], v[224:227], v[6:9]
	v_mfma_f32_16x16x32_bf16 v[2:5], v[188:191], v[224:227], v[2:5]
	s_setprio 0
	s_barrier
	ds_read_b128 v[130:133], v150
	ds_read_b128 v[134:137], v150 offset:1024
	ds_read_b128 v[154:157], v150 offset:2048
	ds_read_b128 v[158:161], v150 offset:3072
	ds_read_b128 v[168:171], v151
	ds_read_b128 v[172:175], v151 offset:1024
	ds_read_b128 v[184:187], v151 offset:2048
	ds_read_b128 v[188:191], v151 offset:3072
	ds_read_b128 v[192:195], v149 offset:32768
	ds_read_b128 v[196:199], v149 offset:33792
	ds_read_b128 v[204:207], v149 offset:34816
	ds_read_b128 v[208:211], v149 offset:35840
	ds_read_b128 v[212:215], v149 offset:36864
	ds_read_b128 v[216:219], v149 offset:37888
	ds_read_b128 v[220:223], v149 offset:38912
	ds_read_b128 v[224:227], v149 offset:39936
	s_add_u32 s66, s10, 0x40000
	s_addc_u32 s67, s11, 0
	s_mov_b32 m0, s49
	s_nop 0
	global_load_lds_dwordx4 v1, s[66:67]
	s_add_u32 s66, s10, 0x60000
	s_addc_u32 s67, s11, 0
	s_mov_b32 m0, s50
	s_nop 0
	global_load_lds_dwordx4 v1, s[66:67]
	s_waitcnt vmcnt(8)
	s_waitcnt lgkmcnt(0)
	s_barrier
	s_setprio 1
	s_waitcnt lgkmcnt(7)
	v_mfma_f32_16x16x32_bf16 v[126:129], v[130:133], v[192:195], v[126:129]
	v_mfma_f32_16x16x32_bf16 v[122:125], v[154:157], v[192:195], v[122:125]
	s_waitcnt lgkmcnt(5)
	v_mfma_f32_16x16x32_bf16 v[118:121], v[130:133], v[204:207], v[118:121]
	v_mfma_f32_16x16x32_bf16 v[114:117], v[154:157], v[204:207], v[114:117]
	s_waitcnt lgkmcnt(3)
	v_mfma_f32_16x16x32_bf16 v[110:113], v[130:133], v[212:215], v[110:113]
	v_mfma_f32_16x16x32_bf16 v[106:109], v[154:157], v[212:215], v[106:109]
	s_waitcnt lgkmcnt(1)
	v_mfma_f32_16x16x32_bf16 v[102:105], v[130:133], v[220:223], v[102:105]
	v_mfma_f32_16x16x32_bf16 v[98:101], v[154:157], v[220:223], v[98:101]
	v_mfma_f32_16x16x32_bf16 v[126:129], v[134:137], v[196:199], v[126:129]
	v_mfma_f32_16x16x32_bf16 v[122:125], v[158:161], v[196:199], v[122:125]
	v_mfma_f32_16x16x32_bf16 v[118:121], v[134:137], v[208:211], v[118:121]
	v_mfma_f32_16x16x32_bf16 v[114:117], v[158:161], v[208:211], v[114:117]
	v_mfma_f32_16x16x32_bf16 v[110:113], v[134:137], v[216:219], v[110:113]
	v_mfma_f32_16x16x32_bf16 v[106:109], v[158:161], v[216:219], v[106:109]
	s_waitcnt lgkmcnt(0)
	v_mfma_f32_16x16x32_bf16 v[102:105], v[134:137], v[224:227], v[102:105]
	v_mfma_f32_16x16x32_bf16 v[98:101], v[158:161], v[224:227], v[98:101]
	s_setprio 0
	s_setprio 1
	v_mfma_f32_16x16x32_bf16 v[62:65], v[168:171], v[192:195], v[62:65]
	v_mfma_f32_16x16x32_bf16 v[58:61], v[184:187], v[192:195], v[58:61]
	v_mfma_f32_16x16x32_bf16 v[54:57], v[168:171], v[204:207], v[54:57]
	v_mfma_f32_16x16x32_bf16 v[50:53], v[184:187], v[204:207], v[50:53]
	v_mfma_f32_16x16x32_bf16 v[46:49], v[168:171], v[212:215], v[46:49]
	v_mfma_f32_16x16x32_bf16 v[42:45], v[184:187], v[212:215], v[42:45]
	v_mfma_f32_16x16x32_bf16 v[38:41], v[168:171], v[220:223], v[38:41]
	v_mfma_f32_16x16x32_bf16 v[34:37], v[184:187], v[220:223], v[34:37]
	v_mfma_f32_16x16x32_bf16 v[62:65], v[172:175], v[196:199], v[62:65]
	v_mfma_f32_16x16x32_bf16 v[58:61], v[188:191], v[196:199], v[58:61]
	v_mfma_f32_16x16x32_bf16 v[54:57], v[172:175], v[208:211], v[54:57]
	v_mfma_f32_16x16x32_bf16 v[50:53], v[188:191], v[208:211], v[50:53]
	v_mfma_f32_16x16x32_bf16 v[46:49], v[172:175], v[216:219], v[46:49]
	v_mfma_f32_16x16x32_bf16 v[42:45], v[188:191], v[216:219], v[42:45]
	v_mfma_f32_16x16x32_bf16 v[38:41], v[172:175], v[224:227], v[38:41]
	v_mfma_f32_16x16x32_bf16 v[34:37], v[188:191], v[224:227], v[34:37]
	s_setprio 0
	s_add_u32 s66, s30, 0x80
	s_addc_u32 s67, s31, 0
	s_barrier
; #define PG8_STAGE(bufoff, gbase, X) do { _Pragma("unroll") for (int _i = 0; _i < 2; ++_i) { \
;         const char* gp_ = (const char*)(gbase) + (_i ? rs##X : (size_t)0); const unsigned la_ = (unsigned)(size_t)(lds + (bufoff) + ldsw + _i * 8192); \
;         asm volatile("s_mov_b32 m0, %2\n\ts_nop 0\n\tglobal_load_lds_dwordx4 %0, %1" :: "v"(voff##X), "s"(gp_), "s"(la_) : "memory", "m0"); } } while (0)
; #define PG8_LDA(dst, b, h) do { _Pragma("unroll") for (int m = 0; m < 4; ++m) _Pragma("unroll") for (int k = 0; k < 2; ++k) dst[m][k] = *(const LAS bf16x8*)(lds + PG8_SA(b, h) + aoff + m * 2048 + k * 1024); } while (0)
; #define PG8_WAIT_V(n) asm volatile("s_waitcnt vmcnt(" #n ")" ::: "memory")
; #define PG8_WAIT_L(n) asm volatile("s_waitcnt lgkmcnt(" #n ")" ::: "memory")
; #define PG8_BAR __builtin_amdgcn_s_barrier()
; #define PG8_SCHED __builtin_amdgcn_sched_barrier(0)
; template <class Epi>
; __device__ __forceinline__ void gemm_phase(LAS unsigned char* lds, const Gemm g_in, const StaticOrder& S, const Epi& E) {
;     ...
;         for (int t = 0; t < nt; t += 2) {
;     ...
;             PG8_LDA(At, 1, 1); PG8_STAGE(PG8_SB(1, 0), b3, B); PG8_STAGE(PG8_SB(1, 1), b3 + hsB, B); PG8_STAGE(PG8_SA(1, 0), a3, A);
;             PG8_WAIT_V(8); PG8_WAIT_L(0); PG8_BAR; PG8_MMA(1, 0, At, B0); PG8_MMA(1, 1, At, B1); PG8_BAR; PG8_SCHED;
;         }
	ds_read_b128 v[192:195], v149 offset:49152
	ds_read_b128 v[196:199], v149 offset:50176
	ds_read_b128 v[204:207], v149 offset:51200
	ds_read_b128 v[208:211], v149 offset:52224
	ds_read_b128 v[212:215], v149 offset:53248
	ds_read_b128 v[216:219], v149 offset:54272
	ds_read_b128 v[220:223], v149 offset:55296
	ds_read_b128 v[224:227], v149 offset:56320
	s_mov_b32 m0, s51
	s_nop 0
	global_load_lds_dwordx4 v144, s[66:67]
	s_add_u32 s66, s30, 0x8080
	s_addc_u32 s67, s31, 0
	s_mov_b32 m0, s52
	s_nop 0
	global_load_lds_dwordx4 v144, s[66:67]
	s_add_u32 s66, s30, 0x10080
	s_addc_u32 s67, s31, 0
	s_mov_b32 m0, s55
	s_nop 0
	global_load_lds_dwordx4 v144, s[66:67]
	s_add_u32 s30, s30, 0x18080
	s_addc_u32 s31, s31, 0
	s_mov_b32 m0, s56
	s_nop 0
	global_load_lds_dwordx4 v144, s[30:31]
	s_add_u32 s10, s10, 0x20080
	s_mov_b32 m0, s53
	s_nop 0
	global_load_lds_dwordx4 v1, s[28:29]
	s_addc_u32 s11, s11, 0
	s_mov_b32 m0, s54
	s_nop 0
	global_load_lds_dwordx4 v1, s[10:11]
	s_waitcnt vmcnt(8)
	s_waitcnt lgkmcnt(0)
	s_barrier
	s_setprio 1
	s_waitcnt lgkmcnt(7)
	v_mfma_f32_16x16x32_bf16 v[94:97], v[130:133], v[192:195], v[94:97]
	v_mfma_f32_16x16x32_bf16 v[90:93], v[154:157], v[192:195], v[90:93]
	s_waitcnt lgkmcnt(5)
	v_mfma_f32_16x16x32_bf16 v[86:89], v[130:133], v[204:207], v[86:89]
	v_mfma_f32_16x16x32_bf16 v[82:85], v[154:157], v[204:207], v[82:85]
	s_waitcnt lgkmcnt(3)
	v_mfma_f32_16x16x32_bf16 v[78:81], v[130:133], v[212:215], v[78:81]
	v_mfma_f32_16x16x32_bf16 v[74:77], v[154:157], v[212:215], v[74:77]
	s_waitcnt lgkmcnt(1)
	v_mfma_f32_16x16x32_bf16 v[70:73], v[130:133], v[220:223], v[70:73]
	v_mfma_f32_16x16x32_bf16 v[66:69], v[154:157], v[220:223], v[66:69]
	v_mfma_f32_16x16x32_bf16 v[94:97], v[134:137], v[196:199], v[94:97]
	v_mfma_f32_16x16x32_bf16 v[90:93], v[158:161], v[196:199], v[90:93]
	v_mfma_f32_16x16x32_bf16 v[86:89], v[134:137], v[208:211], v[86:89]
	v_mfma_f32_16x16x32_bf16 v[82:85], v[158:161], v[208:211], v[82:85]
	v_mfma_f32_16x16x32_bf16 v[78:81], v[134:137], v[216:219], v[78:81]
	v_mfma_f32_16x16x32_bf16 v[74:77], v[158:161], v[216:219], v[74:77]
	s_waitcnt lgkmcnt(0)
	v_mfma_f32_16x16x32_bf16 v[70:73], v[134:137], v[224:227], v[70:73]
	v_mfma_f32_16x16x32_bf16 v[66:69], v[158:161], v[224:227], v[66:69]
	s_setprio 0
	s_setprio 1
	v_mfma_f32_16x16x32_bf16 v[30:33], v[168:171], v[192:195], v[30:33]
	v_mfma_f32_16x16x32_bf16 v[26:29], v[184:187], v[192:195], v[26:29]
	v_mfma_f32_16x16x32_bf16 v[22:25], v[168:171], v[204:207], v[22:25]
	v_mfma_f32_16x16x32_bf16 v[18:21], v[184:187], v[204:207], v[18:21]
	v_mfma_f32_16x16x32_bf16 v[14:17], v[168:171], v[212:215], v[14:17]
	v_mfma_f32_16x16x32_bf16 v[10:13], v[184:187], v[212:215], v[10:13]
	v_mfma_f32_16x16x32_bf16 v[6:9], v[168:171], v[220:223], v[6:9]
	v_mfma_f32_16x16x32_bf16 v[2:5], v[184:187], v[220:223], v[2:5]
	v_mfma_f32_16x16x32_bf16 v[30:33], v[172:175], v[196:199], v[30:33]
	v_mfma_f32_16x16x32_bf16 v[26:29], v[188:191], v[196:199], v[26:29]
	v_mfma_f32_16x16x32_bf16 v[22:25], v[172:175], v[208:211], v[22:25]
	v_mfma_f32_16x16x32_bf16 v[18:21], v[188:191], v[208:211], v[18:21]
	v_mfma_f32_16x16x32_bf16 v[14:17], v[172:175], v[216:219], v[14:17]
	v_mfma_f32_16x16x32_bf16 v[10:13], v[188:191], v[216:219], v[10:13]
	v_mfma_f32_16x16x32_bf16 v[6:9], v[172:175], v[224:227], v[6:9]
	v_mfma_f32_16x16x32_bf16 v[2:5], v[188:191], v[224:227], v[2:5]
	s_setprio 0
	s_add_u32 s62, s62, 0x100
	s_addc_u32 s63, s63, 0
	s_add_u32 s6, s6, 0x100
	s_addc_u32 s7, s7, 0
	s_cmp_ge_i32 s64, s39
	s_mov_b32 s10, s64
	s_barrier
	s_cbranch_scc0 .LBB0_769
	s_and_b64 vcc, exec, s[16:17]
	s_cbranch_vccz .LBB0_772

; #define PG8_STAGE(bufoff, gbase, X) do { _Pragma("unroll") for (int _i = 0; _i < 2; ++_i) { \
;         const char* gp_ = (const char*)(gbase) + (_i ? rs##X : (size_t)0); const unsigned la_ = (unsigned)(size_t)(lds + (bufoff) + ldsw + _i * 8192); \
;         asm volatile("s_mov_b32 m0, %2\n\ts_nop 0\n\tglobal_load_lds_dwordx4 %0, %1" :: "v"(voff##X), "s"(gp_), "s"(la_) : "memory", "m0"); } } while (0)
; #define PG8_LDA(dst, b, h) do { _Pragma("unroll") for (int m = 0; m < 4; ++m) _Pragma("unroll") for (int k = 0; k < 2; ++k) dst[m][k] = *(const LAS bf16x8*)(lds + PG8_SA(b, h) + aoff + m * 2048 + k * 1024); } while (0)
; #define PG8_LDB(dst, b, h) do { _Pragma("unroll") for (int n = 0; n < 2; ++n) _Pragma("unroll") for (int k = 0; k < 2; ++k) dst[n][k] = *(const LAS bf16x8*)(lds + PG8_SB(b, h) + boff + n * 2048 + k * 1024); } while (0)
; #define PG8_WAIT_V(n) asm volatile("s_waitcnt vmcnt(" #n ")" ::: "memory")
; #define PG8_WAIT_L(n) asm volatile("s_waitcnt lgkmcnt(" #n ")" ::: "memory")
; #define PG8_BAR __builtin_amdgcn_s_barrier()
; #define PG8_SCHED __builtin_amdgcn_sched_barrier(0)
; template <class Epi>
; __device__ __forceinline__ void gemm_phase(LAS unsigned char* lds, const Gemm g_in, const StaticOrder& S, const Epi& E) {
;     ...
;             const bool last = (t == nt - 2);
;             const char* a1 = cA + (size_t)(t + 1) * kstep;
;             const char* a2 = last ? nA : cA + (size_t)(t + 2) * kstep; const char* b2 = last ? nB : cB + (size_t)(t + 2) * kstep;
;             const char* a3 = a2 + kstep; const char* b3 = b2 + kstep;
;             PG8_LDB(B0, 0, 0); PG8_LDB(B1, 0, 1); PG8_SCHED; PG8_LDA(At, 0, 0); PG8_STAGE(PG8_SA(1, 1), a1 + hsA, A);
;             PG8_WAIT_V(8); PG8_WAIT_L(0); PG8_BAR; PG8_MMA(0, 0, At, B0); PG8_MMA(0, 1, At, B1); PG8_BAR; PG8_SCHED;
;             PG8_LDA(At, 0, 1); PG8_STAGE(PG8_SB(0, 0), b2, B); PG8_STAGE(PG8_SB(0, 1), b2 + hsB, B); PG8_STAGE(PG8_SA(0, 0), a2, A);
.LBB0_787:
	ds_read_b128 v[142:145], v137
	ds_read_b128 v[146:149], v137 offset:1024
	ds_read_b128 v[154:157], v137 offset:2048
	ds_read_b128 v[158:161], v137 offset:3072
	ds_read_b128 v[168:171], v138
	ds_read_b128 v[172:175], v138 offset:1024
	ds_read_b128 v[184:187], v138 offset:2048
	ds_read_b128 v[188:191], v138 offset:3072
	s_add_i32 s63, s26, 2
	s_add_u32 s28, s24, 0xfffa0080
	s_addc_u32 s27, s25, -1
	s_cmp_eq_u32 s55, s26
	s_cselect_b32 s26, s17, s28
	s_cselect_b32 s27, s15, s27
	s_cselect_b32 s30, s60, s61
	s_cselect_b32 s31, s59, s62
	s_add_u32 s28, s26, 0x80
	s_addc_u32 s29, s27, 0
	ds_read_b128 v[192:195], v139
	ds_read_b128 v[196:199], v139 offset:1024
	ds_read_b128 v[204:207], v139 offset:2048
	ds_read_b128 v[208:211], v139 offset:3072
	ds_read_b128 v[212:215], v139 offset:4096
	ds_read_b128 v[216:219], v139 offset:5120
	ds_read_b128 v[220:223], v139 offset:6144
	ds_read_b128 v[224:227], v139 offset:7168
	s_add_u32 s64, s24, 0xfffe0000
	s_addc_u32 s65, s25, -1
	s_mov_b32 m0, s56
	s_nop 0
	global_load_lds_dwordx4 v1, s[64:65]
	s_nop 0
	s_mov_b32 m0, s57
	s_nop 0
	global_load_lds_dwordx4 v1, s[24:25]
	s_waitcnt vmcnt(8)
	s_waitcnt lgkmcnt(0)
	s_barrier
	s_setprio 1
	s_waitcnt lgkmcnt(7)
	v_mfma_f32_16x16x32_bf16 v[126:129], v[142:145], v[192:195], v[126:129]
	v_mfma_f32_16x16x32_bf16 v[122:125], v[154:157], v[192:195], v[122:125]
	s_waitcnt lgkmcnt(5)
	v_mfma_f32_16x16x32_bf16 v[110:113], v[142:145], v[204:207], v[110:113]
	v_mfma_f32_16x16x32_bf16 v[106:109], v[154:157], v[204:207], v[106:109]
	s_waitcnt lgkmcnt(3)
	v_mfma_f32_16x16x32_bf16 v[94:97], v[142:145], v[212:215], v[94:97]
	v_mfma_f32_16x16x32_bf16 v[90:93], v[154:157], v[212:215], v[90:93]
	s_waitcnt lgkmcnt(1)
	v_mfma_f32_16x16x32_bf16 v[78:81], v[142:145], v[220:223], v[78:81]
	v_mfma_f32_16x16x32_bf16 v[74:77], v[154:157], v[220:223], v[74:77]
	v_mfma_f32_16x16x32_bf16 v[126:129], v[146:149], v[196:199], v[126:129]
	v_mfma_f32_16x16x32_bf16 v[122:125], v[158:161], v[196:199], v[122:125]
	v_mfma_f32_16x16x32_bf16 v[110:113], v[146:149], v[208:211], v[110:113]
	v_mfma_f32_16x16x32_bf16 v[106:109], v[158:161], v[208:211], v[106:109]
	v_mfma_f32_16x16x32_bf16 v[94:97], v[146:149], v[216:219], v[94:97]
	v_mfma_f32_16x16x32_bf16 v[90:93], v[158:161], v[216:219], v[90:93]
	s_waitcnt lgkmcnt(0)
	v_mfma_f32_16x16x32_bf16 v[78:81], v[146:149], v[224:227], v[78:81]
	v_mfma_f32_16x16x32_bf16 v[74:77], v[158:161], v[224:227], v[74:77]
	s_setprio 0
	s_setprio 1
	v_mfma_f32_16x16x32_bf16 v[118:121], v[168:171], v[192:195], v[118:121]
	v_mfma_f32_16x16x32_bf16 v[114:117], v[184:187], v[192:195], v[114:117]
	v_mfma_f32_16x16x32_bf16 v[102:105], v[168:171], v[204:207], v[102:105]
	v_mfma_f32_16x16x32_bf16 v[98:101], v[184:187], v[204:207], v[98:101]
	v_mfma_f32_16x16x32_bf16 v[86:89], v[168:171], v[212:215], v[86:89]
	v_mfma_f32_16x16x32_bf16 v[82:85], v[184:187], v[212:215], v[82:85]
	v_mfma_f32_16x16x32_bf16 v[70:73], v[168:171], v[220:223], v[70:73]
	v_mfma_f32_16x16x32_bf16 v[66:69], v[184:187], v[220:223], v[66:69]
	v_mfma_f32_16x16x32_bf16 v[118:121], v[172:175], v[196:199], v[118:121]
	v_mfma_f32_16x16x32_bf16 v[114:117], v[188:191], v[196:199], v[114:117]
	v_mfma_f32_16x16x32_bf16 v[102:105], v[172:175], v[208:211], v[102:105]
	v_mfma_f32_16x16x32_bf16 v[98:101], v[188:191], v[208:211], v[98:101]
	v_mfma_f32_16x16x32_bf16 v[86:89], v[172:175], v[216:219], v[86:89]
	v_mfma_f32_16x16x32_bf16 v[82:85], v[188:191], v[216:219], v[82:85]
	v_mfma_f32_16x16x32_bf16 v[70:73], v[172:175], v[224:227], v[70:73]
	v_mfma_f32_16x16x32_bf16 v[66:69], v[188:191], v[224:227], v[66:69]
	s_setprio 0
	s_add_u32 s64, s30, 0x10000
	s_barrier
	ds_read_b128 v[192:195], v139 offset:16384
	ds_read_b128 v[196:199], v139 offset:17408
	ds_read_b128 v[204:207], v139 offset:18432
	ds_read_b128 v[208:211], v139 offset:19456
	ds_read_b128 v[212:215], v139 offset:20480
	ds_read_b128 v[216:219], v139 offset:21504
	ds_read_b128 v[220:223], v139 offset:22528
	ds_read_b128 v[224:227], v139 offset:23552
	s_mov_b32 m0, s42
	s_nop 0
	global_load_lds_dwordx4 v134, s[30:31]
	s_addc_u32 s65, s31, 0
	s_mov_b32 m0, s43
	s_nop 0
	global_load_lds_dwordx4 v134, s[64:65]
	s_add_u32 s64, s30, 0x20000
	s_addc_u32 s65, s31, 0
	s_mov_b32 m0, s44
	s_nop 0
	global_load_lds_dwordx4 v134, s[64:65]
	s_add_u32 s64, s30, 0x30000
	s_addc_u32 s65, s31, 0
	s_mov_b32 m0, s45
	s_nop 0
	global_load_lds_dwordx4 v134, s[64:65]
	s_add_u32 s64, s26, 0x20000
	s_mov_b32 m0, s13
	s_nop 0
	global_load_lds_dwordx4 v1, s[26:27]
	s_addc_u32 s65, s27, 0
	s_mov_b32 m0, s46
	s_nop 0
	global_load_lds_dwordx4 v1, s[64:65]
	s_waitcnt vmcnt(8)
	s_waitcnt lgkmcnt(0)
	s_barrier
; #define PG8_STAGE(bufoff, gbase, X) do { _Pragma("unroll") for (int _i = 0; _i < 2; ++_i) { \
;         const char* gp_ = (const char*)(gbase) + (_i ? rs##X : (size_t)0); const unsigned la_ = (unsigned)(size_t)(lds + (bufoff) + ldsw + _i * 8192); \
;         asm volatile("s_mov_b32 m0, %2\n\ts_nop 0\n\tglobal_load_lds_dwordx4 %0, %1" :: "v"(voff##X), "s"(gp_), "s"(la_) : "memory", "m0"); } } while (0)
; #define PG8_LDA(dst, b, h) do { _Pragma("unroll") for (int m = 0; m < 4; ++m) _Pragma("unroll") for (int k = 0; k < 2; ++k) dst[m][k] = *(const LAS bf16x8*)(lds + PG8_SA(b, h) + aoff + m * 2048 + k * 1024); } while (0)
; #define PG8_LDB(dst, b, h) do { _Pragma("unroll") for (int n = 0; n < 2; ++n) _Pragma("unroll") for (int k = 0; k < 2; ++k) dst[n][k] = *(const LAS bf16x8*)(lds + PG8_SB(b, h) + boff + n * 2048 + k * 1024); } while (0)
; #define PG8_WAIT_V(n) asm volatile("s_waitcnt vmcnt(" #n ")" ::: "memory")
; #define PG8_WAIT_L(n) asm volatile("s_waitcnt lgkmcnt(" #n ")" ::: "memory")
; #define PG8_BAR __builtin_amdgcn_s_barrier()
; #define PG8_SCHED __builtin_amdgcn_sched_barrier(0)
; template <class Epi>
; __device__ __forceinline__ void gemm_phase(LAS unsigned char* lds, const Gemm g_in, const StaticOrder& S, const Epi& E) {
;     ...
;             PG8_WAIT_V(8); PG8_WAIT_L(0); PG8_BAR; PG8_MMA(1, 0, At, B0); PG8_MMA(1, 1, At, B1); PG8_BAR; PG8_SCHED;
;             PG8_LDB(B0, 1, 0); PG8_LDB(B1, 1, 1); PG8_SCHED; PG8_LDA(At, 1, 0); PG8_STAGE(PG8_SA(0, 1), a2 + hsA, A);
;             PG8_WAIT_V(8); PG8_WAIT_L(0); PG8_BAR; PG8_MMA(0, 0, At, B0); PG8_MMA(0, 1, At, B1); PG8_BAR; PG8_SCHED;
	s_setprio 1
	s_waitcnt lgkmcnt(7)
	v_mfma_f32_16x16x32_bf16 v[62:65], v[142:145], v[192:195], v[62:65]
	v_mfma_f32_16x16x32_bf16 v[58:61], v[154:157], v[192:195], v[58:61]
	s_waitcnt lgkmcnt(5)
	v_mfma_f32_16x16x32_bf16 v[46:49], v[142:145], v[204:207], v[46:49]
	v_mfma_f32_16x16x32_bf16 v[42:45], v[154:157], v[204:207], v[42:45]
	s_waitcnt lgkmcnt(3)
	v_mfma_f32_16x16x32_bf16 v[30:33], v[142:145], v[212:215], v[30:33]
	v_mfma_f32_16x16x32_bf16 v[26:29], v[154:157], v[212:215], v[26:29]
	s_waitcnt lgkmcnt(1)
	v_mfma_f32_16x16x32_bf16 v[14:17], v[142:145], v[220:223], v[14:17]
	v_mfma_f32_16x16x32_bf16 v[10:13], v[154:157], v[220:223], v[10:13]
	v_mfma_f32_16x16x32_bf16 v[62:65], v[146:149], v[196:199], v[62:65]
	v_mfma_f32_16x16x32_bf16 v[58:61], v[158:161], v[196:199], v[58:61]
	v_mfma_f32_16x16x32_bf16 v[46:49], v[146:149], v[208:211], v[46:49]
	v_mfma_f32_16x16x32_bf16 v[42:45], v[158:161], v[208:211], v[42:45]
	v_mfma_f32_16x16x32_bf16 v[30:33], v[146:149], v[216:219], v[30:33]
	v_mfma_f32_16x16x32_bf16 v[26:29], v[158:161], v[216:219], v[26:29]
	s_waitcnt lgkmcnt(0)
	v_mfma_f32_16x16x32_bf16 v[14:17], v[146:149], v[224:227], v[14:17]
	v_mfma_f32_16x16x32_bf16 v[10:13], v[158:161], v[224:227], v[10:13]
	s_setprio 0
	s_setprio 1
	v_mfma_f32_16x16x32_bf16 v[54:57], v[168:171], v[192:195], v[54:57]
	v_mfma_f32_16x16x32_bf16 v[50:53], v[184:187], v[192:195], v[50:53]
	v_mfma_f32_16x16x32_bf16 v[38:41], v[168:171], v[204:207], v[38:41]
	v_mfma_f32_16x16x32_bf16 v[34:37], v[184:187], v[204:207], v[34:37]
	v_mfma_f32_16x16x32_bf16 v[22:25], v[168:171], v[212:215], v[22:25]
	v_mfma_f32_16x16x32_bf16 v[18:21], v[184:187], v[212:215], v[18:21]
	v_mfma_f32_16x16x32_bf16 v[6:9], v[168:171], v[220:223], v[6:9]
	v_mfma_f32_16x16x32_bf16 v[2:5], v[184:187], v[220:223], v[2:5]
	v_mfma_f32_16x16x32_bf16 v[54:57], v[172:175], v[196:199], v[54:57]
	v_mfma_f32_16x16x32_bf16 v[50:53], v[188:191], v[196:199], v[50:53]
	v_mfma_f32_16x16x32_bf16 v[38:41], v[172:175], v[208:211], v[38:41]
	v_mfma_f32_16x16x32_bf16 v[34:37], v[188:191], v[208:211], v[34:37]
	v_mfma_f32_16x16x32_bf16 v[22:25], v[172:175], v[216:219], v[22:25]
	v_mfma_f32_16x16x32_bf16 v[18:21], v[188:191], v[216:219], v[18:21]
	v_mfma_f32_16x16x32_bf16 v[6:9], v[172:175], v[224:227], v[6:9]
	v_mfma_f32_16x16x32_bf16 v[2:5], v[188:191], v[224:227], v[2:5]
	s_setprio 0
	s_barrier
	ds_read_b128 v[142:145], v140
	ds_read_b128 v[146:149], v140 offset:1024
	ds_read_b128 v[154:157], v140 offset:2048
	ds_read_b128 v[158:161], v140 offset:3072
	ds_read_b128 v[168:171], v141
	ds_read_b128 v[172:175], v141 offset:1024
	ds_read_b128 v[184:187], v141 offset:2048
	ds_read_b128 v[188:191], v141 offset:3072
	ds_read_b128 v[192:195], v139 offset:32768
	ds_read_b128 v[196:199], v139 offset:33792
	ds_read_b128 v[204:207], v139 offset:34816
	ds_read_b128 v[208:211], v139 offset:35840
	ds_read_b128 v[212:215], v139 offset:36864
	ds_read_b128 v[216:219], v139 offset:37888
	ds_read_b128 v[220:223], v139 offset:38912
	ds_read_b128 v[224:227], v139 offset:39936
	s_add_u32 s64, s26, 0x40000
	s_addc_u32 s65, s27, 0
	s_mov_b32 m0, s47
	s_nop 0
	global_load_lds_dwordx4 v1, s[64:65]
	s_add_u32 s64, s26, 0x60000
	s_addc_u32 s65, s27, 0
	s_mov_b32 m0, s48
	s_nop 0
	global_load_lds_dwordx4 v1, s[64:65]
	s_waitcnt vmcnt(8)
	s_waitcnt lgkmcnt(0)
	s_barrier
	s_setprio 1
	s_waitcnt lgkmcnt(7)
	v_mfma_f32_16x16x32_bf16 v[126:129], v[142:145], v[192:195], v[126:129]
	v_mfma_f32_16x16x32_bf16 v[122:125], v[154:157], v[192:195], v[122:125]
	s_waitcnt lgkmcnt(5)
	v_mfma_f32_16x16x32_bf16 v[110:113], v[142:145], v[204:207], v[110:113]
	v_mfma_f32_16x16x32_bf16 v[106:109], v[154:157], v[204:207], v[106:109]
	s_waitcnt lgkmcnt(3)
	v_mfma_f32_16x16x32_bf16 v[94:97], v[142:145], v[212:215], v[94:97]
	v_mfma_f32_16x16x32_bf16 v[90:93], v[154:157], v[212:215], v[90:93]
	s_waitcnt lgkmcnt(1)
	v_mfma_f32_16x16x32_bf16 v[78:81], v[142:145], v[220:223], v[78:81]
	v_mfma_f32_16x16x32_bf16 v[74:77], v[154:157], v[220:223], v[74:77]
	v_mfma_f32_16x16x32_bf16 v[126:129], v[146:149], v[196:199], v[126:129]
	v_mfma_f32_16x16x32_bf16 v[122:125], v[158:161], v[196:199], v[122:125]
	v_mfma_f32_16x16x32_bf16 v[110:113], v[146:149], v[208:211], v[110:113]
	v_mfma_f32_16x16x32_bf16 v[106:109], v[158:161], v[208:211], v[106:109]
	v_mfma_f32_16x16x32_bf16 v[94:97], v[146:149], v[216:219], v[94:97]
	v_mfma_f32_16x16x32_bf16 v[90:93], v[158:161], v[216:219], v[90:93]
	s_waitcnt lgkmcnt(0)
	v_mfma_f32_16x16x32_bf16 v[78:81], v[146:149], v[224:227], v[78:81]
	v_mfma_f32_16x16x32_bf16 v[74:77], v[158:161], v[224:227], v[74:77]
	s_setprio 0
	s_setprio 1
	v_mfma_f32_16x16x32_bf16 v[118:121], v[168:171], v[192:195], v[118:121]
	v_mfma_f32_16x16x32_bf16 v[114:117], v[184:187], v[192:195], v[114:117]
	v_mfma_f32_16x16x32_bf16 v[102:105], v[168:171], v[204:207], v[102:105]
	v_mfma_f32_16x16x32_bf16 v[98:101], v[184:187], v[204:207], v[98:101]
	v_mfma_f32_16x16x32_bf16 v[86:89], v[168:171], v[212:215], v[86:89]
	v_mfma_f32_16x16x32_bf16 v[82:85], v[184:187], v[212:215], v[82:85]
	v_mfma_f32_16x16x32_bf16 v[70:73], v[168:171], v[220:223], v[70:73]
	v_mfma_f32_16x16x32_bf16 v[66:69], v[184:187], v[220:223], v[66:69]
	v_mfma_f32_16x16x32_bf16 v[118:121], v[172:175], v[196:199], v[118:121]
	v_mfma_f32_16x16x32_bf16 v[114:117], v[188:191], v[196:199], v[114:117]
	v_mfma_f32_16x16x32_bf16 v[102:105], v[172:175], v[208:211], v[102:105]
	v_mfma_f32_16x16x32_bf16 v[98:101], v[188:191], v[208:211], v[98:101]
	v_mfma_f32_16x16x32_bf16 v[86:89], v[172:175], v[216:219], v[86:89]
	v_mfma_f32_16x16x32_bf16 v[82:85], v[188:191], v[216:219], v[82:85]
	v_mfma_f32_16x16x32_bf16 v[70:73], v[172:175], v[224:227], v[70:73]
	v_mfma_f32_16x16x32_bf16 v[66:69], v[188:191], v[224:227], v[66:69]
	s_setprio 0
	s_add_u32 s64, s30, 0x80
	s_addc_u32 s65, s31, 0
	s_barrier
; #define PG8_STAGE(bufoff, gbase, X) do { _Pragma("unroll") for (int _i = 0; _i < 2; ++_i) { \
;         const char* gp_ = (const char*)(gbase) + (_i ? rs##X : (size_t)0); const unsigned la_ = (unsigned)(size_t)(lds + (bufoff) + ldsw + _i * 8192); \
;         asm volatile("s_mov_b32 m0, %2\n\ts_nop 0\n\tglobal_load_lds_dwordx4 %0, %1" :: "v"(voff##X), "s"(gp_), "s"(la_) : "memory", "m0"); } } while (0)
; #define PG8_LDA(dst, b, h) do { _Pragma("unroll") for (int m = 0; m < 4; ++m) _Pragma("unroll") for (int k = 0; k < 2; ++k) dst[m][k] = *(const LAS bf16x8*)(lds + PG8_SA(b, h) + aoff + m * 2048 + k * 1024); } while (0)
; #define PG8_WAIT_V(n) asm volatile("s_waitcnt vmcnt(" #n ")" ::: "memory")
; #define PG8_WAIT_L(n) asm volatile("s_waitcnt lgkmcnt(" #n ")" ::: "memory")
; #define PG8_BAR __builtin_amdgcn_s_barrier()
; #define PG8_SCHED __builtin_amdgcn_sched_barrier(0)
; template <class Epi>
; __device__ __forceinline__ void gemm_phase(LAS unsigned char* lds, const Gemm g_in, const StaticOrder& S, const Epi& E) {
;     ...
;         for (int t = 0; t < nt; t += 2) {
;     ...
;             PG8_LDA(At, 1, 1); PG8_STAGE(PG8_SB(1, 0), b3, B); PG8_STAGE(PG8_SB(1, 1), b3 + hsB, B); PG8_STAGE(PG8_SA(1, 0), a3, A);
;             PG8_WAIT_V(8); PG8_WAIT_L(0); PG8_BAR; PG8_MMA(1, 0, At, B0); PG8_MMA(1, 1, At, B1); PG8_BAR; PG8_SCHED;
;         }
	ds_read_b128 v[192:195], v139 offset:49152
	ds_read_b128 v[196:199], v139 offset:50176
	ds_read_b128 v[204:207], v139 offset:51200
	ds_read_b128 v[208:211], v139 offset:52224
	ds_read_b128 v[212:215], v139 offset:53248
	ds_read_b128 v[216:219], v139 offset:54272
	ds_read_b128 v[220:223], v139 offset:55296
	ds_read_b128 v[224:227], v139 offset:56320
	s_mov_b32 m0, s49
	s_nop 0
	global_load_lds_dwordx4 v134, s[64:65]
	s_add_u32 s64, s30, 0x10080
	s_addc_u32 s65, s31, 0
	s_mov_b32 m0, s50
	s_nop 0
	global_load_lds_dwordx4 v134, s[64:65]
	s_add_u32 s64, s30, 0x20080
	s_addc_u32 s65, s31, 0
	s_mov_b32 m0, s53
	s_nop 0
	global_load_lds_dwordx4 v134, s[64:65]
	s_add_u32 s30, s30, 0x30080
	s_addc_u32 s31, s31, 0
	s_mov_b32 m0, s54
	s_nop 0
	global_load_lds_dwordx4 v134, s[30:31]
	s_add_u32 s26, s26, 0x20080
	s_mov_b32 m0, s51
	s_nop 0
	global_load_lds_dwordx4 v1, s[28:29]
	s_addc_u32 s27, s27, 0
	s_mov_b32 m0, s52
	s_nop 0
	global_load_lds_dwordx4 v1, s[26:27]
	s_waitcnt vmcnt(8)
	s_waitcnt lgkmcnt(0)
	s_barrier
	s_setprio 1
	s_waitcnt lgkmcnt(7)
	v_mfma_f32_16x16x32_bf16 v[62:65], v[142:145], v[192:195], v[62:65]
	v_mfma_f32_16x16x32_bf16 v[58:61], v[154:157], v[192:195], v[58:61]
	s_waitcnt lgkmcnt(5)
	v_mfma_f32_16x16x32_bf16 v[46:49], v[142:145], v[204:207], v[46:49]
	v_mfma_f32_16x16x32_bf16 v[42:45], v[154:157], v[204:207], v[42:45]
	s_waitcnt lgkmcnt(3)
	v_mfma_f32_16x16x32_bf16 v[30:33], v[142:145], v[212:215], v[30:33]
	v_mfma_f32_16x16x32_bf16 v[26:29], v[154:157], v[212:215], v[26:29]
	s_waitcnt lgkmcnt(1)
	v_mfma_f32_16x16x32_bf16 v[14:17], v[142:145], v[220:223], v[14:17]
	v_mfma_f32_16x16x32_bf16 v[10:13], v[154:157], v[220:223], v[10:13]
	v_mfma_f32_16x16x32_bf16 v[62:65], v[146:149], v[196:199], v[62:65]
	v_mfma_f32_16x16x32_bf16 v[58:61], v[158:161], v[196:199], v[58:61]
	v_mfma_f32_16x16x32_bf16 v[46:49], v[146:149], v[208:211], v[46:49]
	v_mfma_f32_16x16x32_bf16 v[42:45], v[158:161], v[208:211], v[42:45]
	v_mfma_f32_16x16x32_bf16 v[30:33], v[146:149], v[216:219], v[30:33]
	v_mfma_f32_16x16x32_bf16 v[26:29], v[158:161], v[216:219], v[26:29]
	s_waitcnt lgkmcnt(0)
	v_mfma_f32_16x16x32_bf16 v[14:17], v[146:149], v[224:227], v[14:17]
	v_mfma_f32_16x16x32_bf16 v[10:13], v[158:161], v[224:227], v[10:13]
	s_setprio 0
	s_setprio 1
	v_mfma_f32_16x16x32_bf16 v[54:57], v[168:171], v[192:195], v[54:57]
	v_mfma_f32_16x16x32_bf16 v[50:53], v[184:187], v[192:195], v[50:53]
	v_mfma_f32_16x16x32_bf16 v[38:41], v[168:171], v[204:207], v[38:41]
	v_mfma_f32_16x16x32_bf16 v[34:37], v[184:187], v[204:207], v[34:37]
	v_mfma_f32_16x16x32_bf16 v[22:25], v[168:171], v[212:215], v[22:25]
	v_mfma_f32_16x16x32_bf16 v[18:21], v[184:187], v[212:215], v[18:21]
	v_mfma_f32_16x16x32_bf16 v[6:9], v[168:171], v[220:223], v[6:9]
	v_mfma_f32_16x16x32_bf16 v[2:5], v[184:187], v[220:223], v[2:5]
	v_mfma_f32_16x16x32_bf16 v[54:57], v[172:175], v[196:199], v[54:57]
	v_mfma_f32_16x16x32_bf16 v[50:53], v[188:191], v[196:199], v[50:53]
	v_mfma_f32_16x16x32_bf16 v[38:41], v[172:175], v[208:211], v[38:41]
	v_mfma_f32_16x16x32_bf16 v[34:37], v[188:191], v[208:211], v[34:37]
	v_mfma_f32_16x16x32_bf16 v[22:25], v[172:175], v[216:219], v[22:25]
	v_mfma_f32_16x16x32_bf16 v[18:21], v[188:191], v[216:219], v[18:21]
	v_mfma_f32_16x16x32_bf16 v[6:9], v[172:175], v[224:227], v[6:9]
	v_mfma_f32_16x16x32_bf16 v[2:5], v[188:191], v[224:227], v[2:5]
	s_setprio 0
	s_add_u32 s61, s61, 0x100
	s_addc_u32 s62, s62, 0
	s_add_u32 s24, s24, 0x100
	s_addc_u32 s25, s25, 0
	s_cmp_ge_i32 s63, s38
	s_mov_b32 s26, s63
	s_barrier
	s_cbranch_scc0 .LBB0_787
	s_and_b64 vcc, exec, s[10:11]
	s_cbranch_vccz .LBB0_790

; #define PG8_STAGE(bufoff, gbase, X) do { _Pragma("unroll") for (int _i = 0; _i < 2; ++_i) { \
;         const char* gp_ = (const char*)(gbase) + (_i ? rs##X : (size_t)0); const unsigned la_ = (unsigned)(size_t)(lds + (bufoff) + ldsw + _i * 8192); \
;         asm volatile("s_mov_b32 m0, %2\n\ts_nop 0\n\tglobal_load_lds_dwordx4 %0, %1" :: "v"(voff##X), "s"(gp_), "s"(la_) : "memory", "m0"); } } while (0)
; #define PG8_LDA(dst, b, h) do { _Pragma("unroll") for (int m = 0; m < 4; ++m) _Pragma("unroll") for (int k = 0; k < 2; ++k) dst[m][k] = *(const LAS bf16x8*)(lds + PG8_SA(b, h) + aoff + m * 2048 + k * 1024); } while (0)
; #define PG8_LDB(dst, b, h) do { _Pragma("unroll") for (int n = 0; n < 2; ++n) _Pragma("unroll") for (int k = 0; k < 2; ++k) dst[n][k] = *(const LAS bf16x8*)(lds + PG8_SB(b, h) + boff + n * 2048 + k * 1024); } while (0)
; #define PG8_WAIT_V(n) asm volatile("s_waitcnt vmcnt(" #n ")" ::: "memory")
; #define PG8_WAIT_L(n) asm volatile("s_waitcnt lgkmcnt(" #n ")" ::: "memory")
; #define PG8_BAR __builtin_amdgcn_s_barrier()
; #define PG8_SCHED __builtin_amdgcn_sched_barrier(0)
; template <class Epi>
; __device__ __forceinline__ void gemm_phase(LAS unsigned char* lds, const Gemm g_in, const StaticOrder& S, const Epi& E) {
;     ...
;             const bool last = (t == nt - 2);
;             const char* a1 = cA + (size_t)(t + 1) * kstep;
;             const char* a2 = last ? nA : cA + (size_t)(t + 2) * kstep; const char* b2 = last ? nB : cB + (size_t)(t + 2) * kstep;
;             const char* a3 = a2 + kstep; const char* b3 = b2 + kstep;
;             PG8_LDB(B0, 0, 0); PG8_LDB(B1, 0, 1); PG8_SCHED; PG8_LDA(At, 0, 0); PG8_STAGE(PG8_SA(1, 1), a1 + hsA, A);
;             PG8_WAIT_V(8); PG8_WAIT_L(0); PG8_BAR; PG8_MMA(0, 0, At, B0); PG8_MMA(0, 1, At, B1); PG8_BAR; PG8_SCHED;
;             PG8_LDA(At, 0, 1); PG8_STAGE(PG8_SB(0, 0), b2, B); PG8_STAGE(PG8_SB(0, 1), b2 + hsB, B); PG8_STAGE(PG8_SA(0, 0), a2, A);
.LBB0_1254:
	ds_read_b128 v[130:133], v169
	ds_read_b128 v[134:137], v169 offset:1024
	ds_read_b128 v[138:141], v169 offset:2048
	ds_read_b128 v[142:145], v169 offset:3072
	ds_read_b128 v[146:149], v170
	ds_read_b128 v[154:157], v170 offset:1024
	ds_read_b128 v[158:161], v170 offset:2048
	ds_read_b128 v[162:165], v170 offset:3072
	s_add_i32 s62, s28, 2
	s_add_u32 s30, s26, 0xfff40080
	s_addc_u32 s29, s27, -1
	s_cmp_eq_u32 s55, s28
	s_cselect_b32 s28, s21, s30
	s_cselect_b32 s29, s19, s29
	s_cselect_b32 s34, s59, s60
	s_cselect_b32 s35, s58, s61
	s_add_u32 s30, s28, 0x80
	s_addc_u32 s31, s29, 0
	ds_read_b128 v[174:177], v171
	ds_read_b128 v[184:187], v171 offset:1024
	ds_read_b128 v[188:191], v171 offset:2048
	ds_read_b128 v[192:195], v171 offset:3072
	ds_read_b128 v[196:199], v171 offset:4096
	ds_read_b128 v[204:207], v171 offset:5120
	ds_read_b128 v[208:211], v171 offset:6144
	ds_read_b128 v[212:215], v171 offset:7168
	s_add_u32 s64, s26, 0xfffc0000
	s_addc_u32 s65, s27, -1
	s_mov_b32 m0, s56
	s_nop 0
	global_load_lds_dwordx4 v1, s[64:65]
	s_nop 0
	s_mov_b32 m0, s57
	s_nop 0
	global_load_lds_dwordx4 v1, s[26:27]
	s_waitcnt vmcnt(8)
	s_waitcnt lgkmcnt(0)
	s_barrier
	s_setprio 1
	s_waitcnt lgkmcnt(7)
	v_mfma_f32_16x16x32_bf16 v[126:129], v[130:133], v[174:177], v[126:129]
	v_mfma_f32_16x16x32_bf16 v[122:125], v[138:141], v[174:177], v[122:125]
	s_waitcnt lgkmcnt(5)
	v_mfma_f32_16x16x32_bf16 v[110:113], v[130:133], v[188:191], v[110:113]
	v_mfma_f32_16x16x32_bf16 v[106:109], v[138:141], v[188:191], v[106:109]
	s_waitcnt lgkmcnt(3)
	v_mfma_f32_16x16x32_bf16 v[94:97], v[130:133], v[196:199], v[94:97]
	v_mfma_f32_16x16x32_bf16 v[90:93], v[138:141], v[196:199], v[90:93]
	s_waitcnt lgkmcnt(1)
	v_mfma_f32_16x16x32_bf16 v[78:81], v[130:133], v[208:211], v[78:81]
	v_mfma_f32_16x16x32_bf16 v[74:77], v[138:141], v[208:211], v[74:77]
	v_mfma_f32_16x16x32_bf16 v[126:129], v[134:137], v[184:187], v[126:129]
	v_mfma_f32_16x16x32_bf16 v[122:125], v[142:145], v[184:187], v[122:125]
	v_mfma_f32_16x16x32_bf16 v[110:113], v[134:137], v[192:195], v[110:113]
	v_mfma_f32_16x16x32_bf16 v[106:109], v[142:145], v[192:195], v[106:109]
	v_mfma_f32_16x16x32_bf16 v[94:97], v[134:137], v[204:207], v[94:97]
	v_mfma_f32_16x16x32_bf16 v[90:93], v[142:145], v[204:207], v[90:93]
	s_waitcnt lgkmcnt(0)
	v_mfma_f32_16x16x32_bf16 v[78:81], v[134:137], v[212:215], v[78:81]
	v_mfma_f32_16x16x32_bf16 v[74:77], v[142:145], v[212:215], v[74:77]
	s_setprio 0
	s_setprio 1
	v_mfma_f32_16x16x32_bf16 v[118:121], v[146:149], v[174:177], v[118:121]
	v_mfma_f32_16x16x32_bf16 v[114:117], v[158:161], v[174:177], v[114:117]
	v_mfma_f32_16x16x32_bf16 v[102:105], v[146:149], v[188:191], v[102:105]
	v_mfma_f32_16x16x32_bf16 v[98:101], v[158:161], v[188:191], v[98:101]
	v_mfma_f32_16x16x32_bf16 v[86:89], v[146:149], v[196:199], v[86:89]
	v_mfma_f32_16x16x32_bf16 v[82:85], v[158:161], v[196:199], v[82:85]
	v_mfma_f32_16x16x32_bf16 v[70:73], v[146:149], v[208:211], v[70:73]
	v_mfma_f32_16x16x32_bf16 v[66:69], v[158:161], v[208:211], v[66:69]
	v_mfma_f32_16x16x32_bf16 v[118:121], v[154:157], v[184:187], v[118:121]
	v_mfma_f32_16x16x32_bf16 v[114:117], v[162:165], v[184:187], v[114:117]
	v_mfma_f32_16x16x32_bf16 v[102:105], v[154:157], v[192:195], v[102:105]
	v_mfma_f32_16x16x32_bf16 v[98:101], v[162:165], v[192:195], v[98:101]
	v_mfma_f32_16x16x32_bf16 v[86:89], v[154:157], v[204:207], v[86:89]
	v_mfma_f32_16x16x32_bf16 v[82:85], v[162:165], v[204:207], v[82:85]
	v_mfma_f32_16x16x32_bf16 v[70:73], v[154:157], v[212:215], v[70:73]
	v_mfma_f32_16x16x32_bf16 v[66:69], v[162:165], v[212:215], v[66:69]
	s_setprio 0
	s_add_u32 s64, s34, 0x40000
	s_barrier
	ds_read_b128 v[174:177], v171 offset:16384
	ds_read_b128 v[184:187], v171 offset:17408
	ds_read_b128 v[188:191], v171 offset:18432
	ds_read_b128 v[192:195], v171 offset:19456
	ds_read_b128 v[196:199], v171 offset:20480
	ds_read_b128 v[204:207], v171 offset:21504
	ds_read_b128 v[208:211], v171 offset:22528
	ds_read_b128 v[212:215], v171 offset:23552
	s_mov_b32 m0, s42
	s_nop 0
	global_load_lds_dwordx4 v166, s[34:35]
	s_addc_u32 s65, s35, 0
	s_mov_b32 m0, s43
	s_nop 0
	global_load_lds_dwordx4 v166, s[64:65]
	s_add_u32 s64, s34, 0x80000
	s_addc_u32 s65, s35, 0
	s_mov_b32 m0, s44
	s_nop 0
	global_load_lds_dwordx4 v166, s[64:65]
	s_add_u32 s64, s34, 0xc0000
	s_addc_u32 s65, s35, 0
	s_mov_b32 m0, s45
	s_nop 0
	global_load_lds_dwordx4 v166, s[64:65]
	s_add_u32 s64, s28, 0x40000
	s_mov_b32 m0, s41
	s_nop 0
	global_load_lds_dwordx4 v1, s[28:29]
	s_addc_u32 s65, s29, 0
	s_mov_b32 m0, s46
	s_nop 0
	global_load_lds_dwordx4 v1, s[64:65]
	s_waitcnt vmcnt(8)
	s_waitcnt lgkmcnt(0)
	s_barrier
; #define PG8_STAGE(bufoff, gbase, X) do { _Pragma("unroll") for (int _i = 0; _i < 2; ++_i) { \
;         const char* gp_ = (const char*)(gbase) + (_i ? rs##X : (size_t)0); const unsigned la_ = (unsigned)(size_t)(lds + (bufoff) + ldsw + _i * 8192); \
;         asm volatile("s_mov_b32 m0, %2\n\ts_nop 0\n\tglobal_load_lds_dwordx4 %0, %1" :: "v"(voff##X), "s"(gp_), "s"(la_) : "memory", "m0"); } } while (0)
; #define PG8_LDA(dst, b, h) do { _Pragma("unroll") for (int m = 0; m < 4; ++m) _Pragma("unroll") for (int k = 0; k < 2; ++k) dst[m][k] = *(const LAS bf16x8*)(lds + PG8_SA(b, h) + aoff + m * 2048 + k * 1024); } while (0)
; #define PG8_LDB(dst, b, h) do { _Pragma("unroll") for (int n = 0; n < 2; ++n) _Pragma("unroll") for (int k = 0; k < 2; ++k) dst[n][k] = *(const LAS bf16x8*)(lds + PG8_SB(b, h) + boff + n * 2048 + k * 1024); } while (0)
; #define PG8_WAIT_V(n) asm volatile("s_waitcnt vmcnt(" #n ")" ::: "memory")
; #define PG8_WAIT_L(n) asm volatile("s_waitcnt lgkmcnt(" #n ")" ::: "memory")
; #define PG8_BAR __builtin_amdgcn_s_barrier()
; #define PG8_SCHED __builtin_amdgcn_sched_barrier(0)
; template <class Epi>
; __device__ __forceinline__ void gemm_phase(LAS unsigned char* lds, const Gemm g_in, const StaticOrder& S, const Epi& E) {
;     ...
;             PG8_WAIT_V(8); PG8_WAIT_L(0); PG8_BAR; PG8_MMA(1, 0, At, B0); PG8_MMA(1, 1, At, B1); PG8_BAR; PG8_SCHED;
;             PG8_LDB(B0, 1, 0); PG8_LDB(B1, 1, 1); PG8_SCHED; PG8_LDA(At, 1, 0); PG8_STAGE(PG8_SA(0, 1), a2 + hsA, A);
;             PG8_WAIT_V(8); PG8_WAIT_L(0); PG8_BAR; PG8_MMA(0, 0, At, B0); PG8_MMA(0, 1, At, B1); PG8_BAR; PG8_SCHED;
	s_setprio 1
	s_waitcnt lgkmcnt(7)
	v_mfma_f32_16x16x32_bf16 v[62:65], v[130:133], v[174:177], v[62:65]
	v_mfma_f32_16x16x32_bf16 v[58:61], v[138:141], v[174:177], v[58:61]
	s_waitcnt lgkmcnt(5)
	v_mfma_f32_16x16x32_bf16 v[46:49], v[130:133], v[188:191], v[46:49]
	v_mfma_f32_16x16x32_bf16 v[42:45], v[138:141], v[188:191], v[42:45]
	s_waitcnt lgkmcnt(3)
	v_mfma_f32_16x16x32_bf16 v[30:33], v[130:133], v[196:199], v[30:33]
	v_mfma_f32_16x16x32_bf16 v[26:29], v[138:141], v[196:199], v[26:29]
	s_waitcnt lgkmcnt(1)
	v_mfma_f32_16x16x32_bf16 v[14:17], v[130:133], v[208:211], v[14:17]
	v_mfma_f32_16x16x32_bf16 v[10:13], v[138:141], v[208:211], v[10:13]
	v_mfma_f32_16x16x32_bf16 v[62:65], v[134:137], v[184:187], v[62:65]
	v_mfma_f32_16x16x32_bf16 v[58:61], v[142:145], v[184:187], v[58:61]
	v_mfma_f32_16x16x32_bf16 v[46:49], v[134:137], v[192:195], v[46:49]
	v_mfma_f32_16x16x32_bf16 v[42:45], v[142:145], v[192:195], v[42:45]
	v_mfma_f32_16x16x32_bf16 v[30:33], v[134:137], v[204:207], v[30:33]
	v_mfma_f32_16x16x32_bf16 v[26:29], v[142:145], v[204:207], v[26:29]
	s_waitcnt lgkmcnt(0)
	v_mfma_f32_16x16x32_bf16 v[14:17], v[134:137], v[212:215], v[14:17]
	v_mfma_f32_16x16x32_bf16 v[10:13], v[142:145], v[212:215], v[10:13]
	s_setprio 0
	s_setprio 1
	v_mfma_f32_16x16x32_bf16 v[54:57], v[146:149], v[174:177], v[54:57]
	v_mfma_f32_16x16x32_bf16 v[50:53], v[158:161], v[174:177], v[50:53]
	v_mfma_f32_16x16x32_bf16 v[38:41], v[146:149], v[188:191], v[38:41]
	v_mfma_f32_16x16x32_bf16 v[34:37], v[158:161], v[188:191], v[34:37]
	v_mfma_f32_16x16x32_bf16 v[22:25], v[146:149], v[196:199], v[22:25]
	v_mfma_f32_16x16x32_bf16 v[18:21], v[158:161], v[196:199], v[18:21]
	v_mfma_f32_16x16x32_bf16 v[6:9], v[146:149], v[208:211], v[6:9]
	v_mfma_f32_16x16x32_bf16 v[2:5], v[158:161], v[208:211], v[2:5]
	v_mfma_f32_16x16x32_bf16 v[54:57], v[154:157], v[184:187], v[54:57]
	v_mfma_f32_16x16x32_bf16 v[50:53], v[162:165], v[184:187], v[50:53]
	v_mfma_f32_16x16x32_bf16 v[38:41], v[154:157], v[192:195], v[38:41]
	v_mfma_f32_16x16x32_bf16 v[34:37], v[162:165], v[192:195], v[34:37]
	v_mfma_f32_16x16x32_bf16 v[22:25], v[154:157], v[204:207], v[22:25]
	v_mfma_f32_16x16x32_bf16 v[18:21], v[162:165], v[204:207], v[18:21]
	v_mfma_f32_16x16x32_bf16 v[6:9], v[154:157], v[212:215], v[6:9]
	v_mfma_f32_16x16x32_bf16 v[2:5], v[162:165], v[212:215], v[2:5]
	s_setprio 0
	s_barrier
	ds_read_b128 v[130:133], v172
	ds_read_b128 v[134:137], v172 offset:1024
	ds_read_b128 v[138:141], v172 offset:2048
	ds_read_b128 v[142:145], v172 offset:3072
	ds_read_b128 v[146:149], v173
	ds_read_b128 v[154:157], v173 offset:1024
	ds_read_b128 v[158:161], v173 offset:2048
	ds_read_b128 v[162:165], v173 offset:3072
	ds_read_b128 v[174:177], v171 offset:32768
	ds_read_b128 v[184:187], v171 offset:33792
	ds_read_b128 v[188:191], v171 offset:34816
	ds_read_b128 v[192:195], v171 offset:35840
	ds_read_b128 v[196:199], v171 offset:36864
	ds_read_b128 v[204:207], v171 offset:37888
	ds_read_b128 v[208:211], v171 offset:38912
	ds_read_b128 v[212:215], v171 offset:39936
	s_add_u32 s64, s28, 0x80000
	s_addc_u32 s65, s29, 0
	s_mov_b32 m0, s47
	s_nop 0
	global_load_lds_dwordx4 v1, s[64:65]
	s_add_u32 s64, s28, 0xc0000
	s_addc_u32 s65, s29, 0
	s_mov_b32 m0, s48
	s_nop 0
	global_load_lds_dwordx4 v1, s[64:65]
	s_waitcnt vmcnt(8)
	s_waitcnt lgkmcnt(0)
	s_barrier
	s_setprio 1
	s_waitcnt lgkmcnt(7)
	v_mfma_f32_16x16x32_bf16 v[126:129], v[130:133], v[174:177], v[126:129]
	v_mfma_f32_16x16x32_bf16 v[122:125], v[138:141], v[174:177], v[122:125]
	s_waitcnt lgkmcnt(5)
	v_mfma_f32_16x16x32_bf16 v[110:113], v[130:133], v[188:191], v[110:113]
	v_mfma_f32_16x16x32_bf16 v[106:109], v[138:141], v[188:191], v[106:109]
	s_waitcnt lgkmcnt(3)
	v_mfma_f32_16x16x32_bf16 v[94:97], v[130:133], v[196:199], v[94:97]
	v_mfma_f32_16x16x32_bf16 v[90:93], v[138:141], v[196:199], v[90:93]
	s_waitcnt lgkmcnt(1)
	v_mfma_f32_16x16x32_bf16 v[78:81], v[130:133], v[208:211], v[78:81]
	v_mfma_f32_16x16x32_bf16 v[74:77], v[138:141], v[208:211], v[74:77]
	v_mfma_f32_16x16x32_bf16 v[126:129], v[134:137], v[184:187], v[126:129]
	v_mfma_f32_16x16x32_bf16 v[122:125], v[142:145], v[184:187], v[122:125]
	v_mfma_f32_16x16x32_bf16 v[110:113], v[134:137], v[192:195], v[110:113]
	v_mfma_f32_16x16x32_bf16 v[106:109], v[142:145], v[192:195], v[106:109]
	v_mfma_f32_16x16x32_bf16 v[94:97], v[134:137], v[204:207], v[94:97]
	v_mfma_f32_16x16x32_bf16 v[90:93], v[142:145], v[204:207], v[90:93]
	s_waitcnt lgkmcnt(0)
	v_mfma_f32_16x16x32_bf16 v[78:81], v[134:137], v[212:215], v[78:81]
	v_mfma_f32_16x16x32_bf16 v[74:77], v[142:145], v[212:215], v[74:77]
	s_setprio 0
	s_setprio 1
	v_mfma_f32_16x16x32_bf16 v[118:121], v[146:149], v[174:177], v[118:121]
	v_mfma_f32_16x16x32_bf16 v[114:117], v[158:161], v[174:177], v[114:117]
	v_mfma_f32_16x16x32_bf16 v[102:105], v[146:149], v[188:191], v[102:105]
	v_mfma_f32_16x16x32_bf16 v[98:101], v[158:161], v[188:191], v[98:101]
	v_mfma_f32_16x16x32_bf16 v[86:89], v[146:149], v[196:199], v[86:89]
	v_mfma_f32_16x16x32_bf16 v[82:85], v[158:161], v[196:199], v[82:85]
	v_mfma_f32_16x16x32_bf16 v[70:73], v[146:149], v[208:211], v[70:73]
	v_mfma_f32_16x16x32_bf16 v[66:69], v[158:161], v[208:211], v[66:69]
	v_mfma_f32_16x16x32_bf16 v[118:121], v[154:157], v[184:187], v[118:121]
	v_mfma_f32_16x16x32_bf16 v[114:117], v[162:165], v[184:187], v[114:117]
	v_mfma_f32_16x16x32_bf16 v[102:105], v[154:157], v[192:195], v[102:105]
	v_mfma_f32_16x16x32_bf16 v[98:101], v[162:165], v[192:195], v[98:101]
	v_mfma_f32_16x16x32_bf16 v[86:89], v[154:157], v[204:207], v[86:89]
	v_mfma_f32_16x16x32_bf16 v[82:85], v[162:165], v[204:207], v[82:85]
	v_mfma_f32_16x16x32_bf16 v[70:73], v[154:157], v[212:215], v[70:73]
	v_mfma_f32_16x16x32_bf16 v[66:69], v[162:165], v[212:215], v[66:69]
	s_setprio 0
	s_add_u32 s64, s34, 0x80
	s_addc_u32 s65, s35, 0
	s_barrier
; #define PG8_STAGE(bufoff, gbase, X) do { _Pragma("unroll") for (int _i = 0; _i < 2; ++_i) { \
;         const char* gp_ = (const char*)(gbase) + (_i ? rs##X : (size_t)0); const unsigned la_ = (unsigned)(size_t)(lds + (bufoff) + ldsw + _i * 8192); \
;         asm volatile("s_mov_b32 m0, %2\n\ts_nop 0\n\tglobal_load_lds_dwordx4 %0, %1" :: "v"(voff##X), "s"(gp_), "s"(la_) : "memory", "m0"); } } while (0)
; #define PG8_LDA(dst, b, h) do { _Pragma("unroll") for (int m = 0; m < 4; ++m) _Pragma("unroll") for (int k = 0; k < 2; ++k) dst[m][k] = *(const LAS bf16x8*)(lds + PG8_SA(b, h) + aoff + m * 2048 + k * 1024); } while (0)
; #define PG8_WAIT_V(n) asm volatile("s_waitcnt vmcnt(" #n ")" ::: "memory")
; #define PG8_WAIT_L(n) asm volatile("s_waitcnt lgkmcnt(" #n ")" ::: "memory")
; #define PG8_BAR __builtin_amdgcn_s_barrier()
; #define PG8_SCHED __builtin_amdgcn_sched_barrier(0)
; template <class Epi>
; __device__ __forceinline__ void gemm_phase(LAS unsigned char* lds, const Gemm g_in, const StaticOrder& S, const Epi& E) {
;     ...
;         for (int t = 0; t < nt; t += 2) {
;     ...
;             PG8_LDA(At, 1, 1); PG8_STAGE(PG8_SB(1, 0), b3, B); PG8_STAGE(PG8_SB(1, 1), b3 + hsB, B); PG8_STAGE(PG8_SA(1, 0), a3, A);
;             PG8_WAIT_V(8); PG8_WAIT_L(0); PG8_BAR; PG8_MMA(1, 0, At, B0); PG8_MMA(1, 1, At, B1); PG8_BAR; PG8_SCHED;
;         }
	ds_read_b128 v[174:177], v171 offset:49152
	ds_read_b128 v[184:187], v171 offset:50176
	ds_read_b128 v[188:191], v171 offset:51200
	ds_read_b128 v[192:195], v171 offset:52224
	ds_read_b128 v[196:199], v171 offset:53248
	ds_read_b128 v[204:207], v171 offset:54272
	ds_read_b128 v[208:211], v171 offset:55296
	ds_read_b128 v[212:215], v171 offset:56320
	s_mov_b32 m0, s49
	s_nop 0
	global_load_lds_dwordx4 v166, s[64:65]
	s_add_u32 s64, s34, 0x40080
	s_addc_u32 s65, s35, 0
	s_mov_b32 m0, s50
	s_nop 0
	global_load_lds_dwordx4 v166, s[64:65]
	s_add_u32 s64, s34, 0x80080
	s_addc_u32 s65, s35, 0
	s_mov_b32 m0, s53
	s_nop 0
	global_load_lds_dwordx4 v166, s[64:65]
	s_add_u32 s34, s34, 0xc0080
	s_addc_u32 s35, s35, 0
	s_mov_b32 m0, s54
	s_nop 0
	global_load_lds_dwordx4 v166, s[34:35]
	s_add_u32 s28, s28, 0x40080
	s_mov_b32 m0, s51
	s_nop 0
	global_load_lds_dwordx4 v1, s[30:31]
	s_addc_u32 s29, s29, 0
	s_mov_b32 m0, s52
	s_nop 0
	global_load_lds_dwordx4 v1, s[28:29]
	s_waitcnt vmcnt(8)
	s_waitcnt lgkmcnt(0)
	s_barrier
	s_setprio 1
	s_waitcnt lgkmcnt(7)
	v_mfma_f32_16x16x32_bf16 v[62:65], v[130:133], v[174:177], v[62:65]
	v_mfma_f32_16x16x32_bf16 v[58:61], v[138:141], v[174:177], v[58:61]
	s_waitcnt lgkmcnt(5)
	v_mfma_f32_16x16x32_bf16 v[46:49], v[130:133], v[188:191], v[46:49]
	v_mfma_f32_16x16x32_bf16 v[42:45], v[138:141], v[188:191], v[42:45]
	s_waitcnt lgkmcnt(3)
	v_mfma_f32_16x16x32_bf16 v[30:33], v[130:133], v[196:199], v[30:33]
	v_mfma_f32_16x16x32_bf16 v[26:29], v[138:141], v[196:199], v[26:29]
	s_waitcnt lgkmcnt(1)
	v_mfma_f32_16x16x32_bf16 v[14:17], v[130:133], v[208:211], v[14:17]
	v_mfma_f32_16x16x32_bf16 v[10:13], v[138:141], v[208:211], v[10:13]
	v_mfma_f32_16x16x32_bf16 v[62:65], v[134:137], v[184:187], v[62:65]
	v_mfma_f32_16x16x32_bf16 v[58:61], v[142:145], v[184:187], v[58:61]
	v_mfma_f32_16x16x32_bf16 v[46:49], v[134:137], v[192:195], v[46:49]
	v_mfma_f32_16x16x32_bf16 v[42:45], v[142:145], v[192:195], v[42:45]
	v_mfma_f32_16x16x32_bf16 v[30:33], v[134:137], v[204:207], v[30:33]
	v_mfma_f32_16x16x32_bf16 v[26:29], v[142:145], v[204:207], v[26:29]
	s_waitcnt lgkmcnt(0)
	v_mfma_f32_16x16x32_bf16 v[14:17], v[134:137], v[212:215], v[14:17]
	v_mfma_f32_16x16x32_bf16 v[10:13], v[142:145], v[212:215], v[10:13]
	s_setprio 0
	s_setprio 1
	v_mfma_f32_16x16x32_bf16 v[54:57], v[146:149], v[174:177], v[54:57]
	v_mfma_f32_16x16x32_bf16 v[50:53], v[158:161], v[174:177], v[50:53]
	v_mfma_f32_16x16x32_bf16 v[38:41], v[146:149], v[188:191], v[38:41]
	v_mfma_f32_16x16x32_bf16 v[34:37], v[158:161], v[188:191], v[34:37]
	v_mfma_f32_16x16x32_bf16 v[22:25], v[146:149], v[196:199], v[22:25]
	v_mfma_f32_16x16x32_bf16 v[18:21], v[158:161], v[196:199], v[18:21]
	v_mfma_f32_16x16x32_bf16 v[6:9], v[146:149], v[208:211], v[6:9]
	v_mfma_f32_16x16x32_bf16 v[2:5], v[158:161], v[208:211], v[2:5]
	v_mfma_f32_16x16x32_bf16 v[54:57], v[154:157], v[184:187], v[54:57]
	v_mfma_f32_16x16x32_bf16 v[50:53], v[162:165], v[184:187], v[50:53]
	v_mfma_f32_16x16x32_bf16 v[38:41], v[154:157], v[192:195], v[38:41]
	v_mfma_f32_16x16x32_bf16 v[34:37], v[162:165], v[192:195], v[34:37]
	v_mfma_f32_16x16x32_bf16 v[22:25], v[154:157], v[204:207], v[22:25]
	v_mfma_f32_16x16x32_bf16 v[18:21], v[162:165], v[204:207], v[18:21]
	v_mfma_f32_16x16x32_bf16 v[6:9], v[154:157], v[212:215], v[6:9]
	v_mfma_f32_16x16x32_bf16 v[2:5], v[162:165], v[212:215], v[2:5]
	s_setprio 0
	s_add_u32 s60, s60, 0x100
	s_addc_u32 s61, s61, 0
	s_add_u32 s26, s26, 0x100
	s_addc_u32 s27, s27, 0
	s_cmp_ge_i32 s62, s38
	s_mov_b32 s28, s62
	s_barrier
	s_cbranch_scc0 .LBB0_1254
	s_and_b64 vcc, exec, s[16:17]
	s_cbranch_vccz .LBB0_1257

; #define PG8_STAGE(bufoff, gbase, X) do { _Pragma("unroll") for (int _i = 0; _i < 2; ++_i) { \
;         const char* gp_ = (const char*)(gbase) + (_i ? rs##X : (size_t)0); const unsigned la_ = (unsigned)(size_t)(lds + (bufoff) + ldsw + _i * 8192); \
;         asm volatile("s_mov_b32 m0, %2\n\ts_nop 0\n\tglobal_load_lds_dwordx4 %0, %1" :: "v"(voff##X), "s"(gp_), "s"(la_) : "memory", "m0"); } } while (0)
; #define PG8_LDA(dst, b, h) do { _Pragma("unroll") for (int m = 0; m < 4; ++m) _Pragma("unroll") for (int k = 0; k < 2; ++k) dst[m][k] = *(const LAS bf16x8*)(lds + PG8_SA(b, h) + aoff + m * 2048 + k * 1024); } while (0)
; #define PG8_LDB(dst, b, h) do { _Pragma("unroll") for (int n = 0; n < 2; ++n) _Pragma("unroll") for (int k = 0; k < 2; ++k) dst[n][k] = *(const LAS bf16x8*)(lds + PG8_SB(b, h) + boff + n * 2048 + k * 1024); } while (0)
; #define PG8_WAIT_V(n) asm volatile("s_waitcnt vmcnt(" #n ")" ::: "memory")
; #define PG8_WAIT_L(n) asm volatile("s_waitcnt lgkmcnt(" #n ")" ::: "memory")
; #define PG8_BAR __builtin_amdgcn_s_barrier()
; #define PG8_SCHED __builtin_amdgcn_sched_barrier(0)
; template <class Epi>
; __device__ __forceinline__ void gemm_phase(LAS unsigned char* lds, const Gemm g_in, const StaticOrder& S, const Epi& E) {
;     ...
;             const bool last = (t == nt - 2);
;             const char* a1 = cA + (size_t)(t + 1) * kstep;
;             const char* a2 = last ? nA : cA + (size_t)(t + 2) * kstep; const char* b2 = last ? nB : cB + (size_t)(t + 2) * kstep;
;             const char* a3 = a2 + kstep; const char* b3 = b2 + kstep;
;             PG8_LDB(B0, 0, 0); PG8_LDB(B1, 0, 1); PG8_SCHED; PG8_LDA(At, 0, 0); PG8_STAGE(PG8_SA(1, 1), a1 + hsA, A);
;             PG8_WAIT_V(8); PG8_WAIT_L(0); PG8_BAR; PG8_MMA(0, 0, At, B0); PG8_MMA(0, 1, At, B1); PG8_BAR; PG8_SCHED;
;             PG8_LDA(At, 0, 1); PG8_STAGE(PG8_SB(0, 0), b2, B); PG8_STAGE(PG8_SB(0, 1), b2 + hsB, B); PG8_STAGE(PG8_SA(0, 0), a2, A);
.LBB0_1285:
	ds_read_b128 v[130:133], v205
	ds_read_b128 v[134:137], v205 offset:1024
	ds_read_b128 v[138:141], v205 offset:2048
	ds_read_b128 v[142:145], v205 offset:3072
	ds_read_b128 v[146:149], v206
	ds_read_b128 v[150:153], v206 offset:1024
	ds_read_b128 v[154:157], v206 offset:2048
	ds_read_b128 v[158:161], v206 offset:3072
	s_add_i32 s66, s34, 2
	s_add_u32 s36, s30, 0xfff40080
	s_addc_u32 s35, s31, -1
	s_cmp_eq_u32 s58, s34
	s_cselect_b32 s34, s25, s36
	s_cselect_b32 s35, s23, s35
	s_cselect_b32 s38, s63, s64
	s_cselect_b32 s39, s62, s65
	s_add_u32 s36, s34, 0x80
	s_addc_u32 s37, s35, 0
	ds_read_b128 v[162:165], v207
	ds_read_b128 v[166:169], v207 offset:1024
	ds_read_b128 v[170:173], v207 offset:2048
	ds_read_b128 v[174:177], v207 offset:3072
	ds_read_b128 v[188:191], v207 offset:4096
	ds_read_b128 v[192:195], v207 offset:5120
	ds_read_b128 v[196:199], v207 offset:6144
	ds_read_b128 v[212:215], v207 offset:7168
	s_add_u32 s68, s30, 0xfffc0000
	s_addc_u32 s69, s31, -1
	s_mov_b32 m0, s59
	s_nop 0
	global_load_lds_dwordx4 v1, s[68:69]
	s_nop 0
	s_mov_b32 m0, s60
	s_nop 0
	global_load_lds_dwordx4 v1, s[30:31]
	s_waitcnt vmcnt(8)
	s_waitcnt lgkmcnt(0)
	s_barrier
	s_setprio 1
	s_waitcnt lgkmcnt(7)
	v_mfma_f32_16x16x32_bf16 v[126:129], v[130:133], v[162:165], v[126:129]
	v_mfma_f32_16x16x32_bf16 v[122:125], v[138:141], v[162:165], v[122:125]
	s_waitcnt lgkmcnt(5)
	v_mfma_f32_16x16x32_bf16 v[110:113], v[130:133], v[170:173], v[110:113]
	v_mfma_f32_16x16x32_bf16 v[106:109], v[138:141], v[170:173], v[106:109]
	s_waitcnt lgkmcnt(3)
	v_mfma_f32_16x16x32_bf16 v[94:97], v[130:133], v[188:191], v[94:97]
	v_mfma_f32_16x16x32_bf16 v[90:93], v[138:141], v[188:191], v[90:93]
	s_waitcnt lgkmcnt(1)
	v_mfma_f32_16x16x32_bf16 v[78:81], v[130:133], v[196:199], v[78:81]
	v_mfma_f32_16x16x32_bf16 v[74:77], v[138:141], v[196:199], v[74:77]
	v_mfma_f32_16x16x32_bf16 v[126:129], v[134:137], v[166:169], v[126:129]
	v_mfma_f32_16x16x32_bf16 v[122:125], v[142:145], v[166:169], v[122:125]
	v_mfma_f32_16x16x32_bf16 v[110:113], v[134:137], v[174:177], v[110:113]
	v_mfma_f32_16x16x32_bf16 v[106:109], v[142:145], v[174:177], v[106:109]
	v_mfma_f32_16x16x32_bf16 v[94:97], v[134:137], v[192:195], v[94:97]
	v_mfma_f32_16x16x32_bf16 v[90:93], v[142:145], v[192:195], v[90:93]
	s_waitcnt lgkmcnt(0)
	v_mfma_f32_16x16x32_bf16 v[78:81], v[134:137], v[212:215], v[78:81]
	v_mfma_f32_16x16x32_bf16 v[74:77], v[142:145], v[212:215], v[74:77]
	s_setprio 0
	s_setprio 1
	v_mfma_f32_16x16x32_bf16 v[118:121], v[146:149], v[162:165], v[118:121]
	v_mfma_f32_16x16x32_bf16 v[114:117], v[154:157], v[162:165], v[114:117]
	v_mfma_f32_16x16x32_bf16 v[102:105], v[146:149], v[170:173], v[102:105]
	v_mfma_f32_16x16x32_bf16 v[98:101], v[154:157], v[170:173], v[98:101]
	v_mfma_f32_16x16x32_bf16 v[86:89], v[146:149], v[188:191], v[86:89]
	v_mfma_f32_16x16x32_bf16 v[82:85], v[154:157], v[188:191], v[82:85]
	v_mfma_f32_16x16x32_bf16 v[70:73], v[146:149], v[196:199], v[70:73]
	v_mfma_f32_16x16x32_bf16 v[66:69], v[154:157], v[196:199], v[66:69]
	v_mfma_f32_16x16x32_bf16 v[118:121], v[150:153], v[166:169], v[118:121]
	v_mfma_f32_16x16x32_bf16 v[114:117], v[158:161], v[166:169], v[114:117]
	v_mfma_f32_16x16x32_bf16 v[102:105], v[150:153], v[174:177], v[102:105]
	v_mfma_f32_16x16x32_bf16 v[98:101], v[158:161], v[174:177], v[98:101]
	v_mfma_f32_16x16x32_bf16 v[86:89], v[150:153], v[192:195], v[86:89]
	v_mfma_f32_16x16x32_bf16 v[82:85], v[158:161], v[192:195], v[82:85]
	v_mfma_f32_16x16x32_bf16 v[70:73], v[150:153], v[212:215], v[70:73]
	v_mfma_f32_16x16x32_bf16 v[66:69], v[158:161], v[212:215], v[66:69]
	s_setprio 0
	s_add_u32 s68, s38, 0x40000
	s_barrier
	ds_read_b128 v[162:165], v207 offset:16384
	ds_read_b128 v[166:169], v207 offset:17408
	ds_read_b128 v[170:173], v207 offset:18432
	ds_read_b128 v[174:177], v207 offset:19456
	ds_read_b128 v[188:191], v207 offset:20480
	ds_read_b128 v[192:195], v207 offset:21504
	ds_read_b128 v[196:199], v207 offset:22528
	ds_read_b128 v[212:215], v207 offset:23552
	s_mov_b32 m0, s45
	s_nop 0
	global_load_lds_dwordx4 v179, s[38:39]
	s_addc_u32 s69, s39, 0
	s_mov_b32 m0, s46
	s_nop 0
	global_load_lds_dwordx4 v179, s[68:69]
	s_add_u32 s68, s38, 0x80000
	s_addc_u32 s69, s39, 0
	s_mov_b32 m0, s47
	s_nop 0
	global_load_lds_dwordx4 v179, s[68:69]
	s_add_u32 s68, s38, 0xc0000
	s_addc_u32 s69, s39, 0
	s_mov_b32 m0, s48
	s_nop 0
	global_load_lds_dwordx4 v179, s[68:69]
	s_add_u32 s68, s34, 0x40000
	s_mov_b32 m0, s44
	s_nop 0
	global_load_lds_dwordx4 v1, s[34:35]
	s_addc_u32 s69, s35, 0
	s_mov_b32 m0, s49
	s_nop 0
	global_load_lds_dwordx4 v1, s[68:69]
	s_waitcnt vmcnt(8)
	s_waitcnt lgkmcnt(0)
	s_barrier
; #define PG8_STAGE(bufoff, gbase, X) do { _Pragma("unroll") for (int _i = 0; _i < 2; ++_i) { \
;         const char* gp_ = (const char*)(gbase) + (_i ? rs##X : (size_t)0); const unsigned la_ = (unsigned)(size_t)(lds + (bufoff) + ldsw + _i * 8192); \
;         asm volatile("s_mov_b32 m0, %2\n\ts_nop 0\n\tglobal_load_lds_dwordx4 %0, %1" :: "v"(voff##X), "s"(gp_), "s"(la_) : "memory", "m0"); } } while (0)
; #define PG8_LDA(dst, b, h) do { _Pragma("unroll") for (int m = 0; m < 4; ++m) _Pragma("unroll") for (int k = 0; k < 2; ++k) dst[m][k] = *(const LAS bf16x8*)(lds + PG8_SA(b, h) + aoff + m * 2048 + k * 1024); } while (0)
; #define PG8_LDB(dst, b, h) do { _Pragma("unroll") for (int n = 0; n < 2; ++n) _Pragma("unroll") for (int k = 0; k < 2; ++k) dst[n][k] = *(const LAS bf16x8*)(lds + PG8_SB(b, h) + boff + n * 2048 + k * 1024); } while (0)
; #define PG8_WAIT_V(n) asm volatile("s_waitcnt vmcnt(" #n ")" ::: "memory")
; #define PG8_WAIT_L(n) asm volatile("s_waitcnt lgkmcnt(" #n ")" ::: "memory")
; #define PG8_BAR __builtin_amdgcn_s_barrier()
; #define PG8_SCHED __builtin_amdgcn_sched_barrier(0)
; template <class Epi>
; __device__ __forceinline__ void gemm_phase(LAS unsigned char* lds, const Gemm g_in, const StaticOrder& S, const Epi& E) {
;     ...
;             PG8_WAIT_V(8); PG8_WAIT_L(0); PG8_BAR; PG8_MMA(1, 0, At, B0); PG8_MMA(1, 1, At, B1); PG8_BAR; PG8_SCHED;
;             PG8_LDB(B0, 1, 0); PG8_LDB(B1, 1, 1); PG8_SCHED; PG8_LDA(At, 1, 0); PG8_STAGE(PG8_SA(0, 1), a2 + hsA, A);
;             PG8_WAIT_V(8); PG8_WAIT_L(0); PG8_BAR; PG8_MMA(0, 0, At, B0); PG8_MMA(0, 1, At, B1); PG8_BAR; PG8_SCHED;
	s_setprio 1
	s_waitcnt lgkmcnt(7)
	v_mfma_f32_16x16x32_bf16 v[62:65], v[130:133], v[162:165], v[62:65]
	v_mfma_f32_16x16x32_bf16 v[58:61], v[138:141], v[162:165], v[58:61]
	s_waitcnt lgkmcnt(5)
	v_mfma_f32_16x16x32_bf16 v[46:49], v[130:133], v[170:173], v[46:49]
	v_mfma_f32_16x16x32_bf16 v[42:45], v[138:141], v[170:173], v[42:45]
	s_waitcnt lgkmcnt(3)
	v_mfma_f32_16x16x32_bf16 v[30:33], v[130:133], v[188:191], v[30:33]
	v_mfma_f32_16x16x32_bf16 v[26:29], v[138:141], v[188:191], v[26:29]
	s_waitcnt lgkmcnt(1)
	v_mfma_f32_16x16x32_bf16 v[14:17], v[130:133], v[196:199], v[14:17]
	v_mfma_f32_16x16x32_bf16 v[10:13], v[138:141], v[196:199], v[10:13]
	v_mfma_f32_16x16x32_bf16 v[62:65], v[134:137], v[166:169], v[62:65]
	v_mfma_f32_16x16x32_bf16 v[58:61], v[142:145], v[166:169], v[58:61]
	v_mfma_f32_16x16x32_bf16 v[46:49], v[134:137], v[174:177], v[46:49]
	v_mfma_f32_16x16x32_bf16 v[42:45], v[142:145], v[174:177], v[42:45]
	v_mfma_f32_16x16x32_bf16 v[30:33], v[134:137], v[192:195], v[30:33]
	v_mfma_f32_16x16x32_bf16 v[26:29], v[142:145], v[192:195], v[26:29]
	s_waitcnt lgkmcnt(0)
	v_mfma_f32_16x16x32_bf16 v[14:17], v[134:137], v[212:215], v[14:17]
	v_mfma_f32_16x16x32_bf16 v[10:13], v[142:145], v[212:215], v[10:13]
	s_setprio 0
	s_setprio 1
	v_mfma_f32_16x16x32_bf16 v[54:57], v[146:149], v[162:165], v[54:57]
	v_mfma_f32_16x16x32_bf16 v[50:53], v[154:157], v[162:165], v[50:53]
	v_mfma_f32_16x16x32_bf16 v[38:41], v[146:149], v[170:173], v[38:41]
	v_mfma_f32_16x16x32_bf16 v[34:37], v[154:157], v[170:173], v[34:37]
	v_mfma_f32_16x16x32_bf16 v[22:25], v[146:149], v[188:191], v[22:25]
	v_mfma_f32_16x16x32_bf16 v[18:21], v[154:157], v[188:191], v[18:21]
	v_mfma_f32_16x16x32_bf16 v[6:9], v[146:149], v[196:199], v[6:9]
	v_mfma_f32_16x16x32_bf16 v[2:5], v[154:157], v[196:199], v[2:5]
	v_mfma_f32_16x16x32_bf16 v[54:57], v[150:153], v[166:169], v[54:57]
	v_mfma_f32_16x16x32_bf16 v[50:53], v[158:161], v[166:169], v[50:53]
	v_mfma_f32_16x16x32_bf16 v[38:41], v[150:153], v[174:177], v[38:41]
	v_mfma_f32_16x16x32_bf16 v[34:37], v[158:161], v[174:177], v[34:37]
	v_mfma_f32_16x16x32_bf16 v[22:25], v[150:153], v[192:195], v[22:25]
	v_mfma_f32_16x16x32_bf16 v[18:21], v[158:161], v[192:195], v[18:21]
	v_mfma_f32_16x16x32_bf16 v[6:9], v[150:153], v[212:215], v[6:9]
	v_mfma_f32_16x16x32_bf16 v[2:5], v[158:161], v[212:215], v[2:5]
	s_setprio 0
	s_barrier
	ds_read_b128 v[130:133], v208
	ds_read_b128 v[134:137], v208 offset:1024
	ds_read_b128 v[138:141], v208 offset:2048
	ds_read_b128 v[142:145], v208 offset:3072
	ds_read_b128 v[146:149], v209
	ds_read_b128 v[150:153], v209 offset:1024
	ds_read_b128 v[154:157], v209 offset:2048
	ds_read_b128 v[158:161], v209 offset:3072
	ds_read_b128 v[162:165], v207 offset:32768
	ds_read_b128 v[166:169], v207 offset:33792
	ds_read_b128 v[170:173], v207 offset:34816
	ds_read_b128 v[174:177], v207 offset:35840
	ds_read_b128 v[188:191], v207 offset:36864
	ds_read_b128 v[192:195], v207 offset:37888
	ds_read_b128 v[196:199], v207 offset:38912
	ds_read_b128 v[212:215], v207 offset:39936
	s_add_u32 s68, s34, 0x80000
	s_addc_u32 s69, s35, 0
	s_mov_b32 m0, s50
	s_nop 0
	global_load_lds_dwordx4 v1, s[68:69]
	s_add_u32 s68, s34, 0xc0000
	s_addc_u32 s69, s35, 0
	s_mov_b32 m0, s51
	s_nop 0
	global_load_lds_dwordx4 v1, s[68:69]
	s_waitcnt vmcnt(8)
	s_waitcnt lgkmcnt(0)
	s_barrier
	s_setprio 1
	s_waitcnt lgkmcnt(7)
	v_mfma_f32_16x16x32_bf16 v[126:129], v[130:133], v[162:165], v[126:129]
	v_mfma_f32_16x16x32_bf16 v[122:125], v[138:141], v[162:165], v[122:125]
	s_waitcnt lgkmcnt(5)
	v_mfma_f32_16x16x32_bf16 v[110:113], v[130:133], v[170:173], v[110:113]
	v_mfma_f32_16x16x32_bf16 v[106:109], v[138:141], v[170:173], v[106:109]
	s_waitcnt lgkmcnt(3)
	v_mfma_f32_16x16x32_bf16 v[94:97], v[130:133], v[188:191], v[94:97]
	v_mfma_f32_16x16x32_bf16 v[90:93], v[138:141], v[188:191], v[90:93]
	s_waitcnt lgkmcnt(1)
	v_mfma_f32_16x16x32_bf16 v[78:81], v[130:133], v[196:199], v[78:81]
	v_mfma_f32_16x16x32_bf16 v[74:77], v[138:141], v[196:199], v[74:77]
	v_mfma_f32_16x16x32_bf16 v[126:129], v[134:137], v[166:169], v[126:129]
	v_mfma_f32_16x16x32_bf16 v[122:125], v[142:145], v[166:169], v[122:125]
	v_mfma_f32_16x16x32_bf16 v[110:113], v[134:137], v[174:177], v[110:113]
	v_mfma_f32_16x16x32_bf16 v[106:109], v[142:145], v[174:177], v[106:109]
	v_mfma_f32_16x16x32_bf16 v[94:97], v[134:137], v[192:195], v[94:97]
	v_mfma_f32_16x16x32_bf16 v[90:93], v[142:145], v[192:195], v[90:93]
	s_waitcnt lgkmcnt(0)
	v_mfma_f32_16x16x32_bf16 v[78:81], v[134:137], v[212:215], v[78:81]
	v_mfma_f32_16x16x32_bf16 v[74:77], v[142:145], v[212:215], v[74:77]
	s_setprio 0
	s_setprio 1
	v_mfma_f32_16x16x32_bf16 v[118:121], v[146:149], v[162:165], v[118:121]
	v_mfma_f32_16x16x32_bf16 v[114:117], v[154:157], v[162:165], v[114:117]
	v_mfma_f32_16x16x32_bf16 v[102:105], v[146:149], v[170:173], v[102:105]
	v_mfma_f32_16x16x32_bf16 v[98:101], v[154:157], v[170:173], v[98:101]
	v_mfma_f32_16x16x32_bf16 v[86:89], v[146:149], v[188:191], v[86:89]
	v_mfma_f32_16x16x32_bf16 v[82:85], v[154:157], v[188:191], v[82:85]
	v_mfma_f32_16x16x32_bf16 v[70:73], v[146:149], v[196:199], v[70:73]
	v_mfma_f32_16x16x32_bf16 v[66:69], v[154:157], v[196:199], v[66:69]
	v_mfma_f32_16x16x32_bf16 v[118:121], v[150:153], v[166:169], v[118:121]
	v_mfma_f32_16x16x32_bf16 v[114:117], v[158:161], v[166:169], v[114:117]
	v_mfma_f32_16x16x32_bf16 v[102:105], v[150:153], v[174:177], v[102:105]
	v_mfma_f32_16x16x32_bf16 v[98:101], v[158:161], v[174:177], v[98:101]
	v_mfma_f32_16x16x32_bf16 v[86:89], v[150:153], v[192:195], v[86:89]
	v_mfma_f32_16x16x32_bf16 v[82:85], v[158:161], v[192:195], v[82:85]
	v_mfma_f32_16x16x32_bf16 v[70:73], v[150:153], v[212:215], v[70:73]
	v_mfma_f32_16x16x32_bf16 v[66:69], v[158:161], v[212:215], v[66:69]
	s_setprio 0
	s_add_u32 s68, s38, 0x80
	s_addc_u32 s69, s39, 0
	s_barrier
; #define PG8_STAGE(bufoff, gbase, X) do { _Pragma("unroll") for (int _i = 0; _i < 2; ++_i) { \
;         const char* gp_ = (const char*)(gbase) + (_i ? rs##X : (size_t)0); const unsigned la_ = (unsigned)(size_t)(lds + (bufoff) + ldsw + _i * 8192); \
;         asm volatile("s_mov_b32 m0, %2\n\ts_nop 0\n\tglobal_load_lds_dwordx4 %0, %1" :: "v"(voff##X), "s"(gp_), "s"(la_) : "memory", "m0"); } } while (0)
; #define PG8_LDA(dst, b, h) do { _Pragma("unroll") for (int m = 0; m < 4; ++m) _Pragma("unroll") for (int k = 0; k < 2; ++k) dst[m][k] = *(const LAS bf16x8*)(lds + PG8_SA(b, h) + aoff + m * 2048 + k * 1024); } while (0)
; #define PG8_WAIT_V(n) asm volatile("s_waitcnt vmcnt(" #n ")" ::: "memory")
; #define PG8_WAIT_L(n) asm volatile("s_waitcnt lgkmcnt(" #n ")" ::: "memory")
; #define PG8_BAR __builtin_amdgcn_s_barrier()
; #define PG8_SCHED __builtin_amdgcn_sched_barrier(0)
; template <class Epi>
; __device__ __forceinline__ void gemm_phase(LAS unsigned char* lds, const Gemm g_in, const StaticOrder& S, const Epi& E) {
;     ...
;         for (int t = 0; t < nt; t += 2) {
;     ...
;             PG8_LDA(At, 1, 1); PG8_STAGE(PG8_SB(1, 0), b3, B); PG8_STAGE(PG8_SB(1, 1), b3 + hsB, B); PG8_STAGE(PG8_SA(1, 0), a3, A);
;             PG8_WAIT_V(8); PG8_WAIT_L(0); PG8_BAR; PG8_MMA(1, 0, At, B0); PG8_MMA(1, 1, At, B1); PG8_BAR; PG8_SCHED;
;         }
	ds_read_b128 v[162:165], v207 offset:49152
	ds_read_b128 v[166:169], v207 offset:50176
	ds_read_b128 v[170:173], v207 offset:51200
	ds_read_b128 v[174:177], v207 offset:52224
	ds_read_b128 v[188:191], v207 offset:53248
	ds_read_b128 v[192:195], v207 offset:54272
	ds_read_b128 v[196:199], v207 offset:55296
	ds_read_b128 v[212:215], v207 offset:56320
	s_mov_b32 m0, s52
	s_nop 0
	global_load_lds_dwordx4 v179, s[68:69]
	s_add_u32 s68, s38, 0x40080
	s_addc_u32 s69, s39, 0
	s_mov_b32 m0, s53
	s_nop 0
	global_load_lds_dwordx4 v179, s[68:69]
	s_add_u32 s68, s38, 0x80080
	s_addc_u32 s69, s39, 0
	s_mov_b32 m0, s56
	s_nop 0
	global_load_lds_dwordx4 v179, s[68:69]
	s_add_u32 s38, s38, 0xc0080
	s_addc_u32 s39, s39, 0
	s_mov_b32 m0, s57
	s_nop 0
	global_load_lds_dwordx4 v179, s[38:39]
	s_add_u32 s34, s34, 0x40080
	s_mov_b32 m0, s54
	s_nop 0
	global_load_lds_dwordx4 v1, s[36:37]
	s_addc_u32 s35, s35, 0
	s_mov_b32 m0, s55
	s_nop 0
	global_load_lds_dwordx4 v1, s[34:35]
	s_waitcnt vmcnt(8)
	s_waitcnt lgkmcnt(0)
	s_barrier
	s_setprio 1
	s_waitcnt lgkmcnt(7)
	v_mfma_f32_16x16x32_bf16 v[62:65], v[130:133], v[162:165], v[62:65]
	v_mfma_f32_16x16x32_bf16 v[58:61], v[138:141], v[162:165], v[58:61]
	s_waitcnt lgkmcnt(5)
	v_mfma_f32_16x16x32_bf16 v[46:49], v[130:133], v[170:173], v[46:49]
	v_mfma_f32_16x16x32_bf16 v[42:45], v[138:141], v[170:173], v[42:45]
	s_waitcnt lgkmcnt(3)
	v_mfma_f32_16x16x32_bf16 v[30:33], v[130:133], v[188:191], v[30:33]
	v_mfma_f32_16x16x32_bf16 v[26:29], v[138:141], v[188:191], v[26:29]
	s_waitcnt lgkmcnt(1)
	v_mfma_f32_16x16x32_bf16 v[14:17], v[130:133], v[196:199], v[14:17]
	v_mfma_f32_16x16x32_bf16 v[10:13], v[138:141], v[196:199], v[10:13]
	v_mfma_f32_16x16x32_bf16 v[62:65], v[134:137], v[166:169], v[62:65]
	v_mfma_f32_16x16x32_bf16 v[58:61], v[142:145], v[166:169], v[58:61]
	v_mfma_f32_16x16x32_bf16 v[46:49], v[134:137], v[174:177], v[46:49]
	v_mfma_f32_16x16x32_bf16 v[42:45], v[142:145], v[174:177], v[42:45]
	v_mfma_f32_16x16x32_bf16 v[30:33], v[134:137], v[192:195], v[30:33]
	v_mfma_f32_16x16x32_bf16 v[26:29], v[142:145], v[192:195], v[26:29]
	s_waitcnt lgkmcnt(0)
	v_mfma_f32_16x16x32_bf16 v[14:17], v[134:137], v[212:215], v[14:17]
	v_mfma_f32_16x16x32_bf16 v[10:13], v[142:145], v[212:215], v[10:13]
	s_setprio 0
	s_setprio 1
	v_mfma_f32_16x16x32_bf16 v[54:57], v[146:149], v[162:165], v[54:57]
	v_mfma_f32_16x16x32_bf16 v[50:53], v[154:157], v[162:165], v[50:53]
	v_mfma_f32_16x16x32_bf16 v[38:41], v[146:149], v[170:173], v[38:41]
	v_mfma_f32_16x16x32_bf16 v[34:37], v[154:157], v[170:173], v[34:37]
	v_mfma_f32_16x16x32_bf16 v[22:25], v[146:149], v[188:191], v[22:25]
	v_mfma_f32_16x16x32_bf16 v[18:21], v[154:157], v[188:191], v[18:21]
	v_mfma_f32_16x16x32_bf16 v[6:9], v[146:149], v[196:199], v[6:9]
	v_mfma_f32_16x16x32_bf16 v[2:5], v[154:157], v[196:199], v[2:5]
	v_mfma_f32_16x16x32_bf16 v[54:57], v[150:153], v[166:169], v[54:57]
	v_mfma_f32_16x16x32_bf16 v[50:53], v[158:161], v[166:169], v[50:53]
	v_mfma_f32_16x16x32_bf16 v[38:41], v[150:153], v[174:177], v[38:41]
	v_mfma_f32_16x16x32_bf16 v[34:37], v[158:161], v[174:177], v[34:37]
	v_mfma_f32_16x16x32_bf16 v[22:25], v[150:153], v[192:195], v[22:25]
	v_mfma_f32_16x16x32_bf16 v[18:21], v[158:161], v[192:195], v[18:21]
	v_mfma_f32_16x16x32_bf16 v[6:9], v[150:153], v[212:215], v[6:9]
	v_mfma_f32_16x16x32_bf16 v[2:5], v[158:161], v[212:215], v[2:5]
	s_setprio 0
	s_add_u32 s64, s64, 0x100
	s_addc_u32 s65, s65, 0
	s_add_u32 s30, s30, 0x100
	s_addc_u32 s31, s31, 0
	s_cmp_ge_i32 s66, s41
	s_mov_b32 s34, s66
	s_barrier
	s_cbranch_scc0 .LBB0_1285
	s_and_b64 vcc, exec, s[16:17]
	s_cbranch_vccz .LBB0_1288

; #define PG8_STAGE(bufoff, gbase, X) do { _Pragma("unroll") for (int _i = 0; _i < 2; ++_i) { \
;         const char* gp_ = (const char*)(gbase) + (_i ? rs##X : (size_t)0); const unsigned la_ = (unsigned)(size_t)(lds + (bufoff) + ldsw + _i * 8192); \
;         asm volatile("s_mov_b32 m0, %2\n\ts_nop 0\n\tglobal_load_lds_dwordx4 %0, %1" :: "v"(voff##X), "s"(gp_), "s"(la_) : "memory", "m0"); } } while (0)
; #define PG8_LDA(dst, b, h) do { _Pragma("unroll") for (int m = 0; m < 4; ++m) _Pragma("unroll") for (int k = 0; k < 2; ++k) dst[m][k] = *(const LAS bf16x8*)(lds + PG8_SA(b, h) + aoff + m * 2048 + k * 1024); } while (0)
; #define PG8_LDB(dst, b, h) do { _Pragma("unroll") for (int n = 0; n < 2; ++n) _Pragma("unroll") for (int k = 0; k < 2; ++k) dst[n][k] = *(const LAS bf16x8*)(lds + PG8_SB(b, h) + boff + n * 2048 + k * 1024); } while (0)
; #define PG8_WAIT_V(n) asm volatile("s_waitcnt vmcnt(" #n ")" ::: "memory")
; #define PG8_WAIT_L(n) asm volatile("s_waitcnt lgkmcnt(" #n ")" ::: "memory")
; #define PG8_BAR __builtin_amdgcn_s_barrier()
; #define PG8_SCHED __builtin_amdgcn_sched_barrier(0)
; template <class Epi>
; __device__ __forceinline__ void gemm_phase(LAS unsigned char* lds, const Gemm g_in, const StaticOrder& S, const Epi& E) {
;     ...
;             const bool last = (t == nt - 2);
;             const char* a1 = cA + (size_t)(t + 1) * kstep;
;             const char* a2 = last ? nA : cA + (size_t)(t + 2) * kstep; const char* b2 = last ? nB : cB + (size_t)(t + 2) * kstep;
;             const char* a3 = a2 + kstep; const char* b3 = b2 + kstep;
;             PG8_LDB(B0, 0, 0); PG8_LDB(B1, 0, 1); PG8_SCHED; PG8_LDA(At, 0, 0); PG8_STAGE(PG8_SA(1, 1), a1 + hsA, A);
;             PG8_WAIT_V(8); PG8_WAIT_L(0); PG8_BAR; PG8_MMA(0, 0, At, B0); PG8_MMA(0, 1, At, B1); PG8_BAR; PG8_SCHED;
;             PG8_LDA(At, 0, 1); PG8_STAGE(PG8_SB(0, 0), b2, B); PG8_STAGE(PG8_SB(0, 1), b2 + hsB, B); PG8_STAGE(PG8_SA(0, 0), a2, A);
.LBB0_1368:
	v_add_u32_e32 v147, 0x10000, v145
	ds_read_b128 v[134:137], v147
	ds_read_b128 v[138:141], v147 offset:1024
	ds_read_b128 v[148:151], v147 offset:2048
	ds_read_b128 v[152:155], v147 offset:3072
	v_add_u32_e32 v147, 0x14000, v145
	ds_read_b128 v[156:159], v147
	ds_read_b128 v[160:163], v147 offset:1024
	ds_read_b128 v[164:167], v147 offset:2048
	ds_read_b128 v[168:171], v147 offset:3072
	s_add_i32 s70, s40, 2
	s_add_u32 s42, s38, 0xfff40080
	s_addc_u32 s41, s39, -1
	s_cmp_eq_u32 s63, s40
	s_cselect_b32 s40, s31, s42
	s_cselect_b32 s41, s29, s41
	s_cselect_b32 s44, s67, s68
	s_cselect_b32 s45, s66, s69
	s_add_u32 s42, s40, 0x80
	s_addc_u32 s43, s41, 0
	ds_read_b128 v[172:175], v146
	ds_read_b128 v[184:187], v146 offset:1024
	ds_read_b128 v[188:191], v146 offset:2048
	ds_read_b128 v[192:195], v146 offset:3072
	ds_read_b128 v[196:199], v146 offset:4096
	ds_read_b128 v[204:207], v146 offset:5120
	ds_read_b128 v[208:211], v146 offset:6144
	ds_read_b128 v[212:215], v146 offset:7168
	s_add_u32 s72, s38, 0xfffc0000
	s_addc_u32 s73, s39, -1
	s_mov_b32 m0, s64
	s_nop 0
	global_load_lds_dwordx4 v1, s[72:73]
	s_nop 0
	s_mov_b32 m0, s65
	s_nop 0
	global_load_lds_dwordx4 v1, s[38:39]
	s_waitcnt vmcnt(8)
	s_waitcnt lgkmcnt(0)
	s_barrier
	s_setprio 1
	s_waitcnt lgkmcnt(7)
	v_mfma_i32_16x16x64_i8 v[126:129], v[134:137], v[172:175], v[126:129]
	v_mfma_i32_16x16x64_i8 v[122:125], v[148:151], v[172:175], v[122:125]
	s_waitcnt lgkmcnt(5)
	v_mfma_i32_16x16x64_i8 v[118:121], v[134:137], v[188:191], v[118:121]
	v_mfma_i32_16x16x64_i8 v[110:113], v[148:151], v[188:191], v[110:113]
	s_waitcnt lgkmcnt(3)
	v_mfma_i32_16x16x64_i8 v[102:105], v[134:137], v[196:199], v[102:105]
	v_mfma_i32_16x16x64_i8 v[94:97], v[148:151], v[196:199], v[94:97]
	s_waitcnt lgkmcnt(1)
	v_mfma_i32_16x16x64_i8 v[86:89], v[134:137], v[208:211], v[86:89]
	v_mfma_i32_16x16x64_i8 v[78:81], v[148:151], v[208:211], v[78:81]
	v_mfma_i32_16x16x64_i8 v[126:129], v[138:141], v[184:187], v[126:129]
	v_mfma_i32_16x16x64_i8 v[122:125], v[152:155], v[184:187], v[122:125]
	v_mfma_i32_16x16x64_i8 v[118:121], v[138:141], v[192:195], v[118:121]
	v_mfma_i32_16x16x64_i8 v[110:113], v[152:155], v[192:195], v[110:113]
	v_mfma_i32_16x16x64_i8 v[102:105], v[138:141], v[204:207], v[102:105]
	v_mfma_i32_16x16x64_i8 v[94:97], v[152:155], v[204:207], v[94:97]
	s_waitcnt lgkmcnt(0)
	v_mfma_i32_16x16x64_i8 v[86:89], v[138:141], v[212:215], v[86:89]
	v_mfma_i32_16x16x64_i8 v[78:81], v[152:155], v[212:215], v[78:81]
	s_setprio 0
	s_setprio 1
	v_mfma_i32_16x16x64_i8 v[114:117], v[156:159], v[172:175], v[114:117]
	v_mfma_i32_16x16x64_i8 v[106:109], v[164:167], v[172:175], v[106:109]
	v_mfma_i32_16x16x64_i8 v[98:101], v[156:159], v[188:191], v[98:101]
	v_mfma_i32_16x16x64_i8 v[90:93], v[164:167], v[188:191], v[90:93]
	v_mfma_i32_16x16x64_i8 v[82:85], v[156:159], v[196:199], v[82:85]
	v_mfma_i32_16x16x64_i8 v[74:77], v[164:167], v[196:199], v[74:77]
	v_mfma_i32_16x16x64_i8 v[70:73], v[156:159], v[208:211], v[70:73]
	v_mfma_i32_16x16x64_i8 v[66:69], v[164:167], v[208:211], v[66:69]
	v_mfma_i32_16x16x64_i8 v[114:117], v[160:163], v[184:187], v[114:117]
	v_mfma_i32_16x16x64_i8 v[106:109], v[168:171], v[184:187], v[106:109]
	v_mfma_i32_16x16x64_i8 v[98:101], v[160:163], v[192:195], v[98:101]
	v_mfma_i32_16x16x64_i8 v[90:93], v[168:171], v[192:195], v[90:93]
	v_mfma_i32_16x16x64_i8 v[82:85], v[160:163], v[204:207], v[82:85]
	v_mfma_i32_16x16x64_i8 v[74:77], v[168:171], v[204:207], v[74:77]
	v_mfma_i32_16x16x64_i8 v[70:73], v[160:163], v[212:215], v[70:73]
	v_mfma_i32_16x16x64_i8 v[66:69], v[168:171], v[212:215], v[66:69]
	s_setprio 0
	s_add_u32 s72, s44, 0x40000
	s_barrier
	ds_read_b128 v[172:175], v146 offset:16384
	ds_read_b128 v[184:187], v146 offset:17408
	ds_read_b128 v[188:191], v146 offset:18432
	ds_read_b128 v[192:195], v146 offset:19456
	ds_read_b128 v[196:199], v146 offset:20480
	ds_read_b128 v[204:207], v146 offset:21504
	ds_read_b128 v[208:211], v146 offset:22528
	ds_read_b128 v[212:215], v146 offset:23552
	s_mov_b32 m0, s50
	s_nop 0
	global_load_lds_dwordx4 v142, s[44:45]
	s_addc_u32 s73, s45, 0
	s_mov_b32 m0, s51
	s_nop 0
	global_load_lds_dwordx4 v142, s[72:73]
	s_add_u32 s72, s44, 0x80000
	s_addc_u32 s73, s45, 0
	s_mov_b32 m0, s52
	s_nop 0
	global_load_lds_dwordx4 v142, s[72:73]
	s_add_u32 s72, s44, 0xc0000
	s_addc_u32 s73, s45, 0
	s_mov_b32 m0, s53
	s_nop 0
	global_load_lds_dwordx4 v142, s[72:73]
	s_add_u32 s72, s40, 0x40000
	s_mov_b32 m0, s49
	s_nop 0
	global_load_lds_dwordx4 v1, s[40:41]
	s_addc_u32 s73, s41, 0
	s_mov_b32 m0, s54
	s_nop 0
	global_load_lds_dwordx4 v1, s[72:73]
	s_waitcnt vmcnt(8)
	s_waitcnt lgkmcnt(0)
	s_barrier
; #define PG8_STAGE(bufoff, gbase, X) do { _Pragma("unroll") for (int _i = 0; _i < 2; ++_i) { \
;         const char* gp_ = (const char*)(gbase) + (_i ? rs##X : (size_t)0); const unsigned la_ = (unsigned)(size_t)(lds + (bufoff) + ldsw + _i * 8192); \
;         asm volatile("s_mov_b32 m0, %2\n\ts_nop 0\n\tglobal_load_lds_dwordx4 %0, %1" :: "v"(voff##X), "s"(gp_), "s"(la_) : "memory", "m0"); } } while (0)
; #define PG8_LDA(dst, b, h) do { _Pragma("unroll") for (int m = 0; m < 4; ++m) _Pragma("unroll") for (int k = 0; k < 2; ++k) dst[m][k] = *(const LAS bf16x8*)(lds + PG8_SA(b, h) + aoff + m * 2048 + k * 1024); } while (0)
; #define PG8_LDB(dst, b, h) do { _Pragma("unroll") for (int n = 0; n < 2; ++n) _Pragma("unroll") for (int k = 0; k < 2; ++k) dst[n][k] = *(const LAS bf16x8*)(lds + PG8_SB(b, h) + boff + n * 2048 + k * 1024); } while (0)
; #define PG8_WAIT_V(n) asm volatile("s_waitcnt vmcnt(" #n ")" ::: "memory")
; #define PG8_WAIT_L(n) asm volatile("s_waitcnt lgkmcnt(" #n ")" ::: "memory")
; #define PG8_BAR __builtin_amdgcn_s_barrier()
; #define PG8_SCHED __builtin_amdgcn_sched_barrier(0)
; template <class Epi>
; __device__ __forceinline__ void gemm_phase(LAS unsigned char* lds, const Gemm g_in, const StaticOrder& S, const Epi& E) {
;     ...
;             PG8_WAIT_V(8); PG8_WAIT_L(0); PG8_BAR; PG8_MMA(1, 0, At, B0); PG8_MMA(1, 1, At, B1); PG8_BAR; PG8_SCHED;
;             PG8_LDB(B0, 1, 0); PG8_LDB(B1, 1, 1); PG8_SCHED; PG8_LDA(At, 1, 0); PG8_STAGE(PG8_SA(0, 1), a2 + hsA, A);
;             PG8_WAIT_V(8); PG8_WAIT_L(0); PG8_BAR; PG8_MMA(0, 0, At, B0); PG8_MMA(0, 1, At, B1); PG8_BAR; PG8_SCHED;
	s_setprio 1
	s_waitcnt lgkmcnt(7)
	v_mfma_i32_16x16x64_i8 v[62:65], v[134:137], v[172:175], v[62:65]
	v_mfma_i32_16x16x64_i8 v[58:61], v[148:151], v[172:175], v[58:61]
	s_waitcnt lgkmcnt(5)
	v_mfma_i32_16x16x64_i8 v[54:57], v[134:137], v[188:191], v[54:57]
	v_mfma_i32_16x16x64_i8 v[46:49], v[148:151], v[188:191], v[46:49]
	s_waitcnt lgkmcnt(3)
	v_mfma_i32_16x16x64_i8 v[38:41], v[134:137], v[196:199], v[38:41]
	v_mfma_i32_16x16x64_i8 v[30:33], v[148:151], v[196:199], v[30:33]
	s_waitcnt lgkmcnt(1)
	v_mfma_i32_16x16x64_i8 v[22:25], v[134:137], v[208:211], v[22:25]
	v_mfma_i32_16x16x64_i8 v[14:17], v[148:151], v[208:211], v[14:17]
	v_mfma_i32_16x16x64_i8 v[62:65], v[138:141], v[184:187], v[62:65]
	v_mfma_i32_16x16x64_i8 v[58:61], v[152:155], v[184:187], v[58:61]
	v_mfma_i32_16x16x64_i8 v[54:57], v[138:141], v[192:195], v[54:57]
	v_mfma_i32_16x16x64_i8 v[46:49], v[152:155], v[192:195], v[46:49]
	v_mfma_i32_16x16x64_i8 v[38:41], v[138:141], v[204:207], v[38:41]
	v_mfma_i32_16x16x64_i8 v[30:33], v[152:155], v[204:207], v[30:33]
	s_waitcnt lgkmcnt(0)
	v_mfma_i32_16x16x64_i8 v[22:25], v[138:141], v[212:215], v[22:25]
	v_mfma_i32_16x16x64_i8 v[14:17], v[152:155], v[212:215], v[14:17]
	s_setprio 0
	s_setprio 1
	v_mfma_i32_16x16x64_i8 v[50:53], v[156:159], v[172:175], v[50:53]
	v_mfma_i32_16x16x64_i8 v[42:45], v[164:167], v[172:175], v[42:45]
	v_mfma_i32_16x16x64_i8 v[34:37], v[156:159], v[188:191], v[34:37]
	v_mfma_i32_16x16x64_i8 v[26:29], v[164:167], v[188:191], v[26:29]
	v_mfma_i32_16x16x64_i8 v[18:21], v[156:159], v[196:199], v[18:21]
	v_mfma_i32_16x16x64_i8 v[10:13], v[164:167], v[196:199], v[10:13]
	v_mfma_i32_16x16x64_i8 v[6:9], v[156:159], v[208:211], v[6:9]
	v_mfma_i32_16x16x64_i8 v[2:5], v[164:167], v[208:211], v[2:5]
	v_mfma_i32_16x16x64_i8 v[50:53], v[160:163], v[184:187], v[50:53]
	v_mfma_i32_16x16x64_i8 v[42:45], v[168:171], v[184:187], v[42:45]
	v_mfma_i32_16x16x64_i8 v[34:37], v[160:163], v[192:195], v[34:37]
	v_mfma_i32_16x16x64_i8 v[26:29], v[168:171], v[192:195], v[26:29]
	v_mfma_i32_16x16x64_i8 v[18:21], v[160:163], v[204:207], v[18:21]
	v_mfma_i32_16x16x64_i8 v[10:13], v[168:171], v[204:207], v[10:13]
	v_mfma_i32_16x16x64_i8 v[6:9], v[160:163], v[212:215], v[6:9]
	v_mfma_i32_16x16x64_i8 v[2:5], v[168:171], v[212:215], v[2:5]
	s_setprio 0
	s_barrier
	v_add_u32_e32 v147, 0x18000, v145
	ds_read_b128 v[134:137], v147
	ds_read_b128 v[138:141], v147 offset:1024
	ds_read_b128 v[148:151], v147 offset:2048
	ds_read_b128 v[152:155], v147 offset:3072
	v_add_u32_e32 v147, 0x1c000, v145
	ds_read_b128 v[156:159], v147
	ds_read_b128 v[160:163], v147 offset:1024
	ds_read_b128 v[164:167], v147 offset:2048
	ds_read_b128 v[168:171], v147 offset:3072
	ds_read_b128 v[172:175], v146 offset:32768
	ds_read_b128 v[184:187], v146 offset:33792
	ds_read_b128 v[188:191], v146 offset:34816
	ds_read_b128 v[192:195], v146 offset:35840
	ds_read_b128 v[196:199], v146 offset:36864
	ds_read_b128 v[204:207], v146 offset:37888
	ds_read_b128 v[208:211], v146 offset:38912
	ds_read_b128 v[212:215], v146 offset:39936
	s_add_u32 s72, s40, 0x80000
	s_addc_u32 s73, s41, 0
	s_mov_b32 m0, s55
	s_nop 0
	global_load_lds_dwordx4 v1, s[72:73]
	s_add_u32 s72, s40, 0xc0000
	s_addc_u32 s73, s41, 0
	s_mov_b32 m0, s56
	s_nop 0
	global_load_lds_dwordx4 v1, s[72:73]
	s_waitcnt vmcnt(8)
	s_waitcnt lgkmcnt(0)
	s_barrier
	s_setprio 1
	s_waitcnt lgkmcnt(7)
	v_mfma_i32_16x16x64_i8 v[126:129], v[134:137], v[172:175], v[126:129]
	v_mfma_i32_16x16x64_i8 v[122:125], v[148:151], v[172:175], v[122:125]
	s_waitcnt lgkmcnt(5)
	v_mfma_i32_16x16x64_i8 v[118:121], v[134:137], v[188:191], v[118:121]
	v_mfma_i32_16x16x64_i8 v[110:113], v[148:151], v[188:191], v[110:113]
	s_waitcnt lgkmcnt(3)
	v_mfma_i32_16x16x64_i8 v[102:105], v[134:137], v[196:199], v[102:105]
	v_mfma_i32_16x16x64_i8 v[94:97], v[148:151], v[196:199], v[94:97]
	s_waitcnt lgkmcnt(1)
	v_mfma_i32_16x16x64_i8 v[86:89], v[134:137], v[208:211], v[86:89]
	v_mfma_i32_16x16x64_i8 v[78:81], v[148:151], v[208:211], v[78:81]
	v_mfma_i32_16x16x64_i8 v[126:129], v[138:141], v[184:187], v[126:129]
	v_mfma_i32_16x16x64_i8 v[122:125], v[152:155], v[184:187], v[122:125]
	v_mfma_i32_16x16x64_i8 v[118:121], v[138:141], v[192:195], v[118:121]
	v_mfma_i32_16x16x64_i8 v[110:113], v[152:155], v[192:195], v[110:113]
	v_mfma_i32_16x16x64_i8 v[102:105], v[138:141], v[204:207], v[102:105]
	v_mfma_i32_16x16x64_i8 v[94:97], v[152:155], v[204:207], v[94:97]
	s_waitcnt lgkmcnt(0)
	v_mfma_i32_16x16x64_i8 v[86:89], v[138:141], v[212:215], v[86:89]
	v_mfma_i32_16x16x64_i8 v[78:81], v[152:155], v[212:215], v[78:81]
	s_setprio 0
	s_setprio 1
	v_mfma_i32_16x16x64_i8 v[114:117], v[156:159], v[172:175], v[114:117]
	v_mfma_i32_16x16x64_i8 v[106:109], v[164:167], v[172:175], v[106:109]
	v_mfma_i32_16x16x64_i8 v[98:101], v[156:159], v[188:191], v[98:101]
	v_mfma_i32_16x16x64_i8 v[90:93], v[164:167], v[188:191], v[90:93]
	v_mfma_i32_16x16x64_i8 v[82:85], v[156:159], v[196:199], v[82:85]
	v_mfma_i32_16x16x64_i8 v[74:77], v[164:167], v[196:199], v[74:77]
	v_mfma_i32_16x16x64_i8 v[70:73], v[156:159], v[208:211], v[70:73]
	v_mfma_i32_16x16x64_i8 v[66:69], v[164:167], v[208:211], v[66:69]
	v_mfma_i32_16x16x64_i8 v[114:117], v[160:163], v[184:187], v[114:117]
	v_mfma_i32_16x16x64_i8 v[106:109], v[168:171], v[184:187], v[106:109]
	v_mfma_i32_16x16x64_i8 v[98:101], v[160:163], v[192:195], v[98:101]
	v_mfma_i32_16x16x64_i8 v[90:93], v[168:171], v[192:195], v[90:93]
	v_mfma_i32_16x16x64_i8 v[82:85], v[160:163], v[204:207], v[82:85]
	v_mfma_i32_16x16x64_i8 v[74:77], v[168:171], v[204:207], v[74:77]
	v_mfma_i32_16x16x64_i8 v[70:73], v[160:163], v[212:215], v[70:73]
	v_mfma_i32_16x16x64_i8 v[66:69], v[168:171], v[212:215], v[66:69]
	s_setprio 0
	s_add_u32 s72, s44, 0x80
	s_addc_u32 s73, s45, 0
	s_barrier
; #define PG8_STAGE(bufoff, gbase, X) do { _Pragma("unroll") for (int _i = 0; _i < 2; ++_i) { \
;         const char* gp_ = (const char*)(gbase) + (_i ? rs##X : (size_t)0); const unsigned la_ = (unsigned)(size_t)(lds + (bufoff) + ldsw + _i * 8192); \
;         asm volatile("s_mov_b32 m0, %2\n\ts_nop 0\n\tglobal_load_lds_dwordx4 %0, %1" :: "v"(voff##X), "s"(gp_), "s"(la_) : "memory", "m0"); } } while (0)
; #define PG8_LDA(dst, b, h) do { _Pragma("unroll") for (int m = 0; m < 4; ++m) _Pragma("unroll") for (int k = 0; k < 2; ++k) dst[m][k] = *(const LAS bf16x8*)(lds + PG8_SA(b, h) + aoff + m * 2048 + k * 1024); } while (0)
; #define PG8_WAIT_V(n) asm volatile("s_waitcnt vmcnt(" #n ")" ::: "memory")
; #define PG8_WAIT_L(n) asm volatile("s_waitcnt lgkmcnt(" #n ")" ::: "memory")
; #define PG8_BAR __builtin_amdgcn_s_barrier()
; #define PG8_SCHED __builtin_amdgcn_sched_barrier(0)
; template <class Epi>
; __device__ __forceinline__ void gemm_phase(LAS unsigned char* lds, const Gemm g_in, const StaticOrder& S, const Epi& E) {
;     ...
;             PG8_LDA(At, 1, 1); PG8_STAGE(PG8_SB(1, 0), b3, B); PG8_STAGE(PG8_SB(1, 1), b3 + hsB, B); PG8_STAGE(PG8_SA(1, 0), a3, A);
;             PG8_WAIT_V(8); PG8_WAIT_L(0); PG8_BAR; PG8_MMA(1, 0, At, B0); PG8_MMA(1, 1, At, B1); PG8_BAR; PG8_SCHED;
;         }
;     __device__ __forceinline__ void operator()(const f32x4 (&acc)[2][2][4][2], const Unit& u, int wr, int wc, int fr, int fq) const {
;     ...
;                     for (int bj = 0; bj < 2; ++bj) { f32x4 a0 = acc[ai][bj][m][0], a1 = acc[ai][bj][m][1];
;                         if (IN == 2) { a0 = __builtin_convertvector(__builtin_bit_cast(i32x4, a0), f32x4); a1 = __builtin_convertvector(__builtin_bit_cast(i32x4, a1), f32x4); }
;                         const f32x4 v0 = bv[m][bj][0] * ALPHA + a0 * scale, v1 = bv[m][bj][1] * ALPHA + a1 * scale;
	ds_read_b128 v[172:175], v146 offset:49152
	ds_read_b128 v[184:187], v146 offset:50176
	ds_read_b128 v[188:191], v146 offset:51200
	ds_read_b128 v[192:195], v146 offset:52224
	ds_read_b128 v[196:199], v146 offset:53248
	ds_read_b128 v[204:207], v146 offset:54272
	ds_read_b128 v[208:211], v146 offset:55296
	ds_read_b128 v[212:215], v146 offset:56320
	s_mov_b32 m0, s57
	s_nop 0
	global_load_lds_dwordx4 v142, s[72:73]
	s_add_u32 s72, s44, 0x40080
	s_addc_u32 s73, s45, 0
	s_mov_b32 m0, s58
	s_nop 0
	global_load_lds_dwordx4 v142, s[72:73]
	s_add_u32 s72, s44, 0x80080
	s_addc_u32 s73, s45, 0
	s_mov_b32 m0, s61
	s_nop 0
	global_load_lds_dwordx4 v142, s[72:73]
	s_add_u32 s44, s44, 0xc0080
	s_addc_u32 s45, s45, 0
	s_mov_b32 m0, s62
	s_nop 0
	global_load_lds_dwordx4 v142, s[44:45]
	s_add_u32 s40, s40, 0x40080
	s_mov_b32 m0, s59
	s_nop 0
	global_load_lds_dwordx4 v1, s[42:43]
	s_addc_u32 s41, s41, 0
	s_mov_b32 m0, s60
	s_nop 0
	global_load_lds_dwordx4 v1, s[40:41]
	s_waitcnt vmcnt(8)
	s_waitcnt lgkmcnt(0)
	s_barrier
	s_setprio 1
	s_waitcnt lgkmcnt(7)
	v_mfma_i32_16x16x64_i8 v[62:65], v[134:137], v[172:175], v[62:65]
	v_mfma_i32_16x16x64_i8 v[58:61], v[148:151], v[172:175], v[58:61]
	s_waitcnt lgkmcnt(5)
	v_mfma_i32_16x16x64_i8 v[54:57], v[134:137], v[188:191], v[54:57]
	v_mfma_i32_16x16x64_i8 v[46:49], v[148:151], v[188:191], v[46:49]
	s_waitcnt lgkmcnt(3)
	v_mfma_i32_16x16x64_i8 v[38:41], v[134:137], v[196:199], v[38:41]
	v_mfma_i32_16x16x64_i8 v[30:33], v[148:151], v[196:199], v[30:33]
	s_waitcnt lgkmcnt(1)
	v_mfma_i32_16x16x64_i8 v[22:25], v[134:137], v[208:211], v[22:25]
	v_mfma_i32_16x16x64_i8 v[14:17], v[148:151], v[208:211], v[14:17]
	v_mfma_i32_16x16x64_i8 v[62:65], v[138:141], v[184:187], v[62:65]
	v_mfma_i32_16x16x64_i8 v[58:61], v[152:155], v[184:187], v[58:61]
	v_mfma_i32_16x16x64_i8 v[54:57], v[138:141], v[192:195], v[54:57]
	v_mfma_i32_16x16x64_i8 v[46:49], v[152:155], v[192:195], v[46:49]
	v_mfma_i32_16x16x64_i8 v[38:41], v[138:141], v[204:207], v[38:41]
	v_mfma_i32_16x16x64_i8 v[30:33], v[152:155], v[204:207], v[30:33]
	s_waitcnt lgkmcnt(0)
	v_mfma_i32_16x16x64_i8 v[22:25], v[138:141], v[212:215], v[22:25]
	v_mfma_i32_16x16x64_i8 v[14:17], v[152:155], v[212:215], v[14:17]
	s_setprio 0
	s_setprio 1
	v_mfma_i32_16x16x64_i8 v[50:53], v[156:159], v[172:175], v[50:53]
	v_mfma_i32_16x16x64_i8 v[42:45], v[164:167], v[172:175], v[42:45]
	v_mfma_i32_16x16x64_i8 v[34:37], v[156:159], v[188:191], v[34:37]
	v_mfma_i32_16x16x64_i8 v[26:29], v[164:167], v[188:191], v[26:29]
	v_mfma_i32_16x16x64_i8 v[18:21], v[156:159], v[196:199], v[18:21]
	v_mfma_i32_16x16x64_i8 v[10:13], v[164:167], v[196:199], v[10:13]
	v_mfma_i32_16x16x64_i8 v[6:9], v[156:159], v[208:211], v[6:9]
	v_mfma_i32_16x16x64_i8 v[2:5], v[164:167], v[208:211], v[2:5]
	v_mfma_i32_16x16x64_i8 v[50:53], v[160:163], v[184:187], v[50:53]
	v_mfma_i32_16x16x64_i8 v[42:45], v[168:171], v[184:187], v[42:45]
	v_mfma_i32_16x16x64_i8 v[34:37], v[160:163], v[192:195], v[34:37]
	v_mfma_i32_16x16x64_i8 v[26:29], v[168:171], v[192:195], v[26:29]
	v_mfma_i32_16x16x64_i8 v[18:21], v[160:163], v[204:207], v[18:21]
	v_mfma_i32_16x16x64_i8 v[10:13], v[168:171], v[204:207], v[10:13]
	v_mfma_i32_16x16x64_i8 v[6:9], v[160:163], v[212:215], v[6:9]
	v_mfma_i32_16x16x64_i8 v[2:5], v[168:171], v[212:215], v[2:5]
	s_setprio 0
	s_add_u32 s68, s68, 0x100
	s_addc_u32 s69, s69, 0
	s_add_u32 s38, s38, 0x100
	s_addc_u32 s39, s39, 0
	s_cmp_ge_i32 s70, s46
	s_mov_b32 s40, s70
	s_barrier
	s_cbranch_scc0 .LBB0_1368
	v_cvt_f32_i32_e32 v127, v127
	v_cvt_f32_i32_e32 v126, v126
	v_cvt_f32_i32_e32 v129, v129
	v_cvt_f32_i32_e32 v128, v128
	v_cvt_f32_i32_e32 v135, v123
	v_cvt_f32_i32_e32 v125, v125
	v_cvt_f32_i32_e32 v124, v124
	v_cvt_f32_i32_e32 v134, v122
	v_cvt_f32_i32_e32 v115, v115
	v_cvt_f32_i32_e32 v114, v114
	v_cvt_f32_i32_e32 v117, v117
	v_cvt_f32_i32_e32 v116, v116
	v_cvt_f32_i32_e32 v107, v107
	v_cvt_f32_i32_e32 v109, v109
	v_cvt_f32_i32_e32 v108, v108
	v_cvt_f32_i32_e32 v106, v106
	v_pk_mul_f32 v[122:123], v[128:129], s[16:17] op_sel_hi:[1,0]
	v_pk_mul_f32 v[128:129], v[126:127], s[16:17] op_sel_hi:[1,0]
	v_pk_mul_f32 v[126:127], v[124:125], s[16:17] op_sel_hi:[1,0]
	v_pk_mul_f32 v[124:125], v[134:135], s[16:17] op_sel_hi:[1,0]
	v_pk_mul_f32 v[140:141], v[116:117], s[16:17] op_sel_hi:[1,0]
	v_pk_mul_f32 v[138:139], v[114:115], s[16:17] op_sel_hi:[1,0]
	v_pk_mul_f32 v[136:137], v[108:109], s[16:17] op_sel_hi:[1,0]
	v_pk_mul_f32 v[134:135], v[106:107], s[16:17] op_sel_hi:[1,0]
	v_cvt_f32_i32_e32 v107, v119
	v_cvt_f32_i32_e32 v106, v118
	v_cvt_f32_i32_e32 v109, v121
	v_cvt_f32_i32_e32 v108, v120
	v_cvt_f32_i32_e32 v115, v111
	v_cvt_f32_i32_e32 v117, v113
	v_cvt_f32_i32_e32 v116, v112
	v_cvt_f32_i32_e32 v114, v110
	v_cvt_f32_i32_e32 v99, v99
	v_cvt_f32_i32_e32 v98, v98
	v_cvt_f32_i32_e32 v101, v101
	v_cvt_f32_i32_e32 v100, v100
	v_cvt_f32_i32_e32 v91, v91
	v_cvt_f32_i32_e32 v93, v93
	v_cvt_f32_i32_e32 v92, v92
	v_cvt_f32_i32_e32 v90, v90
	v_pk_mul_f32 v[112:113], v[108:109], s[16:17] op_sel_hi:[1,0]
	v_pk_mul_f32 v[110:111], v[106:107], s[16:17] op_sel_hi:[1,0]
	v_pk_mul_f32 v[108:109], v[116:117], s[16:17] op_sel_hi:[1,0]
	v_pk_mul_f32 v[106:107], v[114:115], s[16:17] op_sel_hi:[1,0]
	v_pk_mul_f32 v[120:121], v[100:101], s[16:17] op_sel_hi:[1,0]
	v_pk_mul_f32 v[118:119], v[98:99], s[16:17] op_sel_hi:[1,0]
	v_pk_mul_f32 v[116:117], v[92:93], s[16:17] op_sel_hi:[1,0]
	v_pk_mul_f32 v[114:115], v[90:91], s[16:17] op_sel_hi:[1,0]
	v_cvt_f32_i32_e32 v91, v103
	v_cvt_f32_i32_e32 v90, v102
;     __device__ __forceinline__ void operator()(const f32x4 (&acc)[2][2][4][2], const Unit& u, int wr, int wc, int fr, int fq) const {
;     ...
;                     for (int bj = 0; bj < 2; ++bj) { f32x4 a0 = acc[ai][bj][m][0], a1 = acc[ai][bj][m][1];
;                         if (IN == 2) { a0 = __builtin_convertvector(__builtin_bit_cast(i32x4, a0), f32x4); a1 = __builtin_convertvector(__builtin_bit_cast(i32x4, a1), f32x4); }
;                         const f32x4 v0 = bv[m][bj][0] * ALPHA + a0 * scale, v1 = bv[m][bj][1] * ALPHA + a1 * scale;
	v_cvt_f32_i32_e32 v93, v105
	v_cvt_f32_i32_e32 v92, v104
	v_cvt_f32_i32_e32 v99, v95
	v_cvt_f32_i32_e32 v101, v97
	v_cvt_f32_i32_e32 v100, v96
	v_cvt_f32_i32_e32 v98, v94
	v_cvt_f32_i32_e32 v83, v83
	v_cvt_f32_i32_e32 v82, v82
	v_cvt_f32_i32_e32 v85, v85
	v_cvt_f32_i32_e32 v84, v84
	v_cvt_f32_i32_e32 v75, v75
	v_cvt_f32_i32_e32 v77, v77
	v_cvt_f32_i32_e32 v76, v76
	v_cvt_f32_i32_e32 v74, v74
	v_pk_mul_f32 v[96:97], v[92:93], s[16:17] op_sel_hi:[1,0]
	v_pk_mul_f32 v[94:95], v[90:91], s[16:17] op_sel_hi:[1,0]
	v_pk_mul_f32 v[92:93], v[100:101], s[16:17] op_sel_hi:[1,0]
	v_pk_mul_f32 v[90:91], v[98:99], s[16:17] op_sel_hi:[1,0]
	v_pk_mul_f32 v[104:105], v[84:85], s[16:17] op_sel_hi:[1,0]
	v_pk_mul_f32 v[102:103], v[82:83], s[16:17] op_sel_hi:[1,0]
	v_pk_mul_f32 v[100:101], v[76:77], s[16:17] op_sel_hi:[1,0]
	v_pk_mul_f32 v[98:99], v[74:75], s[16:17] op_sel_hi:[1,0]
	v_cvt_f32_i32_e32 v75, v87
	v_cvt_f32_i32_e32 v74, v86
	v_cvt_f32_i32_e32 v77, v89
	v_cvt_f32_i32_e32 v76, v88
	v_cvt_f32_i32_e32 v83, v79
	v_cvt_f32_i32_e32 v85, v81
	v_cvt_f32_i32_e32 v84, v80
	v_cvt_f32_i32_e32 v82, v78
	v_cvt_f32_i32_e32 v71, v71
	v_cvt_f32_i32_e32 v70, v70
	v_cvt_f32_i32_e32 v73, v73
	v_cvt_f32_i32_e32 v72, v72
	v_cvt_f32_i32_e32 v67, v67
	v_cvt_f32_i32_e32 v69, v69
	v_cvt_f32_i32_e32 v68, v68
	v_cvt_f32_i32_e32 v66, v66
	v_cvt_f32_i32_e32 v51, v51
	v_cvt_f32_i32_e32 v50, v50
	v_cvt_f32_i32_e32 v53, v53
	v_cvt_f32_i32_e32 v52, v52
	v_cvt_f32_i32_e32 v43, v43
	v_cvt_f32_i32_e32 v45, v45
	v_cvt_f32_i32_e32 v44, v44
	v_cvt_f32_i32_e32 v42, v42
	v_pk_mul_f32 v[80:81], v[76:77], s[16:17] op_sel_hi:[1,0]
	v_pk_mul_f32 v[78:79], v[74:75], s[16:17] op_sel_hi:[1,0]
	v_pk_mul_f32 v[76:77], v[84:85], s[16:17] op_sel_hi:[1,0]
	v_pk_mul_f32 v[74:75], v[82:83], s[16:17] op_sel_hi:[1,0]
	v_pk_mul_f32 v[88:89], v[72:73], s[16:17] op_sel_hi:[1,0]
	v_pk_mul_f32 v[86:87], v[70:71], s[16:17] op_sel_hi:[1,0]
	v_pk_mul_f32 v[84:85], v[68:69], s[16:17] op_sel_hi:[1,0]
	v_pk_mul_f32 v[82:83], v[66:67], s[16:17] op_sel_hi:[1,0]
	v_pk_mul_f32 v[72:73], v[52:53], s[16:17] op_sel_hi:[1,0]
	v_pk_mul_f32 v[70:71], v[50:51], s[16:17] op_sel_hi:[1,0]
	v_pk_mul_f32 v[68:69], v[44:45], s[16:17] op_sel_hi:[1,0]
	v_pk_mul_f32 v[66:67], v[42:43], s[16:17] op_sel_hi:[1,0]
	v_cvt_f32_i32_e32 v43, v55
	v_cvt_f32_i32_e32 v42, v54
	v_cvt_f32_i32_e32 v45, v57
	v_cvt_f32_i32_e32 v44, v56
	v_cvt_f32_i32_e32 v51, v47
	v_cvt_f32_i32_e32 v53, v49
	v_cvt_f32_i32_e32 v52, v48
	v_cvt_f32_i32_e32 v50, v46
	v_cvt_f32_i32_e32 v35, v35
	v_cvt_f32_i32_e32 v34, v34
	v_cvt_f32_i32_e32 v37, v37
	v_cvt_f32_i32_e32 v36, v36
	v_cvt_f32_i32_e32 v27, v27
	v_cvt_f32_i32_e32 v29, v29
	v_cvt_f32_i32_e32 v28, v28
	v_cvt_f32_i32_e32 v26, v26
	v_pk_mul_f32 v[48:49], v[44:45], s[16:17] op_sel_hi:[1,0]
	v_pk_mul_f32 v[46:47], v[42:43], s[16:17] op_sel_hi:[1,0]
	v_pk_mul_f32 v[44:45], v[52:53], s[16:17] op_sel_hi:[1,0]
	v_pk_mul_f32 v[42:43], v[50:51], s[16:17] op_sel_hi:[1,0]
	v_pk_mul_f32 v[56:57], v[36:37], s[16:17] op_sel_hi:[1,0]
	v_pk_mul_f32 v[54:55], v[34:35], s[16:17] op_sel_hi:[1,0]
	v_pk_mul_f32 v[52:53], v[28:29], s[16:17] op_sel_hi:[1,0]
	v_pk_mul_f32 v[50:51], v[26:27], s[16:17] op_sel_hi:[1,0]
	v_cvt_f32_i32_e32 v27, v39
	v_cvt_f32_i32_e32 v26, v38
	v_cvt_f32_i32_e32 v29, v41
	v_cvt_f32_i32_e32 v28, v40
	v_cvt_f32_i32_e32 v35, v31
	v_cvt_f32_i32_e32 v37, v33
	v_cvt_f32_i32_e32 v36, v32
	v_cvt_f32_i32_e32 v34, v30
	v_cvt_f32_i32_e32 v19, v19
	v_cvt_f32_i32_e32 v18, v18
	v_cvt_f32_i32_e32 v21, v21
	v_cvt_f32_i32_e32 v20, v20
	v_cvt_f32_i32_e32 v11, v11
	v_cvt_f32_i32_e32 v13, v13
	v_cvt_f32_i32_e32 v12, v12
	v_cvt_f32_i32_e32 v10, v10
	v_cvt_f32_i32_e32 v63, v63
	v_cvt_f32_i32_e32 v62, v62
	v_cvt_f32_i32_e32 v65, v65
	v_cvt_f32_i32_e32 v64, v64
	v_cvt_f32_i32_e32 v59, v59
	v_cvt_f32_i32_e32 v61, v61
	v_cvt_f32_i32_e32 v60, v60
	v_cvt_f32_i32_e32 v58, v58
	v_pk_mul_f32 v[32:33], v[28:29], s[16:17] op_sel_hi:[1,0]
	v_pk_mul_f32 v[30:31], v[26:27], s[16:17] op_sel_hi:[1,0]
	v_pk_mul_f32 v[28:29], v[36:37], s[16:17] op_sel_hi:[1,0]
	v_pk_mul_f32 v[26:27], v[34:35], s[16:17] op_sel_hi:[1,0]
	v_pk_mul_f32 v[36:37], v[20:21], s[16:17] op_sel_hi:[1,0]
	v_pk_mul_f32 v[34:35], v[18:19], s[16:17] op_sel_hi:[1,0]
	v_pk_mul_f32 v[20:21], v[12:13], s[16:17] op_sel_hi:[1,0]
	v_pk_mul_f32 v[18:19], v[10:11], s[16:17] op_sel_hi:[1,0]
	v_cvt_f32_i32_e32 v11, v23
	v_cvt_f32_i32_e32 v10, v22
	v_cvt_f32_i32_e32 v13, v25
	v_cvt_f32_i32_e32 v12, v24
	v_cvt_f32_i32_e32 v23, v15
	v_cvt_f32_i32_e32 v25, v17
	v_cvt_f32_i32_e32 v24, v16
	v_cvt_f32_i32_e32 v22, v14
	v_cvt_f32_i32_e32 v7, v7
	v_cvt_f32_i32_e32 v6, v6
	v_cvt_f32_i32_e32 v9, v9
	v_cvt_f32_i32_e32 v8, v8
	v_cvt_f32_i32_e32 v3, v3
	v_cvt_f32_i32_e32 v5, v5
	v_cvt_f32_i32_e32 v4, v4
	v_cvt_f32_i32_e32 v2, v2
	v_pk_mul_f32 v[64:65], v[64:65], s[16:17] op_sel_hi:[1,0]
	v_pk_mul_f32 v[62:63], v[62:63], s[16:17] op_sel_hi:[1,0]
	v_pk_mul_f32 v[60:61], v[60:61], s[16:17] op_sel_hi:[1,0]
	v_pk_mul_f32 v[58:59], v[58:59], s[16:17] op_sel_hi:[1,0]
	v_pk_mul_f32 v[16:17], v[12:13], s[16:17] op_sel_hi:[1,0]
	v_pk_mul_f32 v[14:15], v[10:11], s[16:17] op_sel_hi:[1,0]
	v_pk_mul_f32 v[12:13], v[24:25], s[16:17] op_sel_hi:[1,0]
	v_pk_mul_f32 v[10:11], v[22:23], s[16:17] op_sel_hi:[1,0]
	v_pk_mul_f32 v[8:9], v[8:9], s[16:17] op_sel_hi:[1,0]
	v_pk_mul_f32 v[6:7], v[6:7], s[16:17] op_sel_hi:[1,0]
	v_pk_mul_f32 v[4:5], v[4:5], s[16:17] op_sel_hi:[1,0]
	v_pk_mul_f32 v[2:3], v[2:3], s[16:17] op_sel_hi:[1,0]
	s_and_b64 vcc, exec, s[14:15]
	s_cbranch_vccz .LBB0_1371

; #define PG8_STAGE(bufoff, gbase, X) do { _Pragma("unroll") for (int _i = 0; _i < 2; ++_i) { \
;         const char* gp_ = (const char*)(gbase) + (_i ? rs##X : (size_t)0); const unsigned la_ = (unsigned)(size_t)(lds + (bufoff) + ldsw + _i * 8192); \
;         asm volatile("s_mov_b32 m0, %2\n\ts_nop 0\n\tglobal_load_lds_dwordx4 %0, %1" :: "v"(voff##X), "s"(gp_), "s"(la_) : "memory", "m0"); } } while (0)
; #define PG8_LDA(dst, b, h) do { _Pragma("unroll") for (int m = 0; m < 4; ++m) _Pragma("unroll") for (int k = 0; k < 2; ++k) dst[m][k] = *(const LAS bf16x8*)(lds + PG8_SA(b, h) + aoff + m * 2048 + k * 1024); } while (0)
; #define PG8_LDB(dst, b, h) do { _Pragma("unroll") for (int n = 0; n < 2; ++n) _Pragma("unroll") for (int k = 0; k < 2; ++k) dst[n][k] = *(const LAS bf16x8*)(lds + PG8_SB(b, h) + boff + n * 2048 + k * 1024); } while (0)
; #define PG8_WAIT_V(n) asm volatile("s_waitcnt vmcnt(" #n ")" ::: "memory")
; #define PG8_WAIT_L(n) asm volatile("s_waitcnt lgkmcnt(" #n ")" ::: "memory")
; #define PG8_BAR __builtin_amdgcn_s_barrier()
; #define PG8_SCHED __builtin_amdgcn_sched_barrier(0)
; template <class Epi>
; __device__ __forceinline__ void gemm_phase(LAS unsigned char* lds, const Gemm g_in, const StaticOrder& S, const Epi& E) {
;     ...
;         for (int t = 0; t < nt; t += 2) {
;             const bool last = (t == nt - 2);
;             const char* a1 = cA + (size_t)(t + 1) * kstep;
;             const char* a2 = last ? nA : cA + (size_t)(t + 2) * kstep; const char* b2 = last ? nB : cB + (size_t)(t + 2) * kstep;
;             const char* a3 = a2 + kstep; const char* b3 = b2 + kstep;
;             PG8_LDB(B0, 0, 0); PG8_LDB(B1, 0, 1); PG8_SCHED; PG8_LDA(At, 0, 0); PG8_STAGE(PG8_SA(1, 1), a1 + hsA, A);
;             PG8_WAIT_V(8); PG8_WAIT_L(0); PG8_BAR; PG8_MMA(0, 0, At, B0); PG8_MMA(0, 1, At, B1); PG8_BAR; PG8_SCHED;
;             PG8_LDA(At, 0, 1); PG8_STAGE(PG8_SB(0, 0), b2, B); PG8_STAGE(PG8_SB(0, 1), b2 + hsB, B); PG8_STAGE(PG8_SA(0, 0), a2, A);
;             PG8_WAIT_V(8); PG8_WAIT_L(0); PG8_BAR; PG8_MMA(1, 0, At, B0); PG8_MMA(1, 1, At, B1); PG8_BAR; PG8_SCHED;
.LBB0_1510:
	v_add_u32_e32 v139, 0x10000, v137
	ds_read_b128 v[140:143], v139
	ds_read_b128 v[144:147], v139 offset:1024
	ds_read_b128 v[148:151], v139 offset:2048
	ds_read_b128 v[152:155], v139 offset:3072
	v_add_u32_e32 v139, 0x14000, v137
	ds_read_b128 v[156:159], v139
	ds_read_b128 v[160:163], v139 offset:1024
	ds_read_b128 v[164:167], v139 offset:2048
	ds_read_b128 v[168:171], v139 offset:3072
	s_add_i32 s64, s28, 2
	s_add_u32 s30, s26, 0xfff40080
	s_addc_u32 s29, s27, -1
	s_cmp_eq_u32 s56, s28
	s_cselect_b32 s28, s21, s30
	s_cselect_b32 s29, s19, s29
	s_cselect_b32 s34, s61, s62
	s_cselect_b32 s35, s60, s63
	s_add_u32 s30, s28, 0x80
	s_addc_u32 s31, s29, 0
	ds_read_b128 v[172:175], v138
	ds_read_b128 v[182:185], v138 offset:1024
	ds_read_b128 v[186:189], v138 offset:2048
	ds_read_b128 v[190:193], v138 offset:3072
	ds_read_b128 v[194:197], v138 offset:4096
	ds_read_b128 v[198:201], v138 offset:5120
	ds_read_b128 v[204:207], v138 offset:6144
	ds_read_b128 v[208:211], v138 offset:7168
	s_add_u32 s66, s26, 0xfffc0000
	s_addc_u32 s67, s27, -1
	s_mov_b32 m0, s57
	s_nop 0
	global_load_lds_dwordx4 v1, s[66:67]
	s_nop 0
	s_mov_b32 m0, s58
	s_nop 0
	global_load_lds_dwordx4 v1, s[26:27]
	s_waitcnt vmcnt(8)
	s_waitcnt lgkmcnt(0)
	s_barrier
	s_setprio 1
	s_waitcnt lgkmcnt(7)
	v_mfma_i32_16x16x64_i8 v[126:129], v[140:143], v[172:175], v[126:129]
	v_mfma_i32_16x16x64_i8 v[118:121], v[148:151], v[172:175], v[118:121]
	s_waitcnt lgkmcnt(5)
	v_mfma_i32_16x16x64_i8 v[110:113], v[140:143], v[186:189], v[110:113]
	v_mfma_i32_16x16x64_i8 v[102:105], v[148:151], v[186:189], v[102:105]
	s_waitcnt lgkmcnt(3)
	v_mfma_i32_16x16x64_i8 v[94:97], v[140:143], v[194:197], v[94:97]
	v_mfma_i32_16x16x64_i8 v[86:89], v[148:151], v[194:197], v[86:89]
	s_waitcnt lgkmcnt(1)
	v_mfma_i32_16x16x64_i8 v[78:81], v[140:143], v[204:207], v[78:81]
	v_mfma_i32_16x16x64_i8 v[70:73], v[148:151], v[204:207], v[70:73]
	v_mfma_i32_16x16x64_i8 v[126:129], v[144:147], v[182:185], v[126:129]
	v_mfma_i32_16x16x64_i8 v[118:121], v[152:155], v[182:185], v[118:121]
	v_mfma_i32_16x16x64_i8 v[110:113], v[144:147], v[190:193], v[110:113]
	v_mfma_i32_16x16x64_i8 v[102:105], v[152:155], v[190:193], v[102:105]
	v_mfma_i32_16x16x64_i8 v[94:97], v[144:147], v[198:201], v[94:97]
	v_mfma_i32_16x16x64_i8 v[86:89], v[152:155], v[198:201], v[86:89]
	s_waitcnt lgkmcnt(0)
	v_mfma_i32_16x16x64_i8 v[78:81], v[144:147], v[208:211], v[78:81]
	v_mfma_i32_16x16x64_i8 v[70:73], v[152:155], v[208:211], v[70:73]
	s_setprio 0
	s_setprio 1
	v_mfma_i32_16x16x64_i8 v[122:125], v[156:159], v[172:175], v[122:125]
	v_mfma_i32_16x16x64_i8 v[114:117], v[164:167], v[172:175], v[114:117]
	v_mfma_i32_16x16x64_i8 v[106:109], v[156:159], v[186:189], v[106:109]
	v_mfma_i32_16x16x64_i8 v[98:101], v[164:167], v[186:189], v[98:101]
	v_mfma_i32_16x16x64_i8 v[90:93], v[156:159], v[194:197], v[90:93]
	v_mfma_i32_16x16x64_i8 v[82:85], v[164:167], v[194:197], v[82:85]
	v_mfma_i32_16x16x64_i8 v[74:77], v[156:159], v[204:207], v[74:77]
	v_mfma_i32_16x16x64_i8 v[66:69], v[164:167], v[204:207], v[66:69]
	v_mfma_i32_16x16x64_i8 v[122:125], v[160:163], v[182:185], v[122:125]
	v_mfma_i32_16x16x64_i8 v[114:117], v[168:171], v[182:185], v[114:117]
	v_mfma_i32_16x16x64_i8 v[106:109], v[160:163], v[190:193], v[106:109]
	v_mfma_i32_16x16x64_i8 v[98:101], v[168:171], v[190:193], v[98:101]
	v_mfma_i32_16x16x64_i8 v[90:93], v[160:163], v[198:201], v[90:93]
	v_mfma_i32_16x16x64_i8 v[82:85], v[168:171], v[198:201], v[82:85]
	v_mfma_i32_16x16x64_i8 v[74:77], v[160:163], v[208:211], v[74:77]
	v_mfma_i32_16x16x64_i8 v[66:69], v[168:171], v[208:211], v[66:69]
	s_setprio 0
	s_add_u32 s66, s34, 0x40000
	s_barrier
	ds_read_b128 v[172:175], v138 offset:16384
	ds_read_b128 v[182:185], v138 offset:17408
	ds_read_b128 v[186:189], v138 offset:18432
	ds_read_b128 v[190:193], v138 offset:19456
	ds_read_b128 v[194:197], v138 offset:20480
	ds_read_b128 v[198:201], v138 offset:21504
	ds_read_b128 v[204:207], v138 offset:22528
	ds_read_b128 v[208:211], v138 offset:23552
	s_mov_b32 m0, s41
	s_nop 0
	global_load_lds_dwordx4 v134, s[34:35]
	s_addc_u32 s67, s35, 0
	s_mov_b32 m0, s42
	s_nop 0
	global_load_lds_dwordx4 v134, s[66:67]
	s_add_u32 s66, s34, 0x80000
	s_addc_u32 s67, s35, 0
	s_mov_b32 m0, s43
	s_nop 0
	global_load_lds_dwordx4 v134, s[66:67]
	s_add_u32 s66, s34, 0xc0000
	s_addc_u32 s67, s35, 0
	s_mov_b32 m0, s44
	s_nop 0
	global_load_lds_dwordx4 v134, s[66:67]
	s_add_u32 s66, s28, 0x40000
	s_mov_b32 m0, s40
	s_nop 0
	global_load_lds_dwordx4 v1, s[28:29]
	s_addc_u32 s67, s29, 0
	s_mov_b32 m0, s45
	s_nop 0
	global_load_lds_dwordx4 v1, s[66:67]
	s_waitcnt vmcnt(8)
	s_waitcnt lgkmcnt(0)
	s_barrier
; #define PG8_STAGE(bufoff, gbase, X) do { _Pragma("unroll") for (int _i = 0; _i < 2; ++_i) { \
;         const char* gp_ = (const char*)(gbase) + (_i ? rs##X : (size_t)0); const unsigned la_ = (unsigned)(size_t)(lds + (bufoff) + ldsw + _i * 8192); \
;         asm volatile("s_mov_b32 m0, %2\n\ts_nop 0\n\tglobal_load_lds_dwordx4 %0, %1" :: "v"(voff##X), "s"(gp_), "s"(la_) : "memory", "m0"); } } while (0)
; #define PG8_LDA(dst, b, h) do { _Pragma("unroll") for (int m = 0; m < 4; ++m) _Pragma("unroll") for (int k = 0; k < 2; ++k) dst[m][k] = *(const LAS bf16x8*)(lds + PG8_SA(b, h) + aoff + m * 2048 + k * 1024); } while (0)
; #define PG8_LDB(dst, b, h) do { _Pragma("unroll") for (int n = 0; n < 2; ++n) _Pragma("unroll") for (int k = 0; k < 2; ++k) dst[n][k] = *(const LAS bf16x8*)(lds + PG8_SB(b, h) + boff + n * 2048 + k * 1024); } while (0)
; #define PG8_WAIT_V(n) asm volatile("s_waitcnt vmcnt(" #n ")" ::: "memory")
; #define PG8_WAIT_L(n) asm volatile("s_waitcnt lgkmcnt(" #n ")" ::: "memory")
; #define PG8_BAR __builtin_amdgcn_s_barrier()
; #define PG8_SCHED __builtin_amdgcn_sched_barrier(0)
; template <class Epi>
; __device__ __forceinline__ void gemm_phase(LAS unsigned char* lds, const Gemm g_in, const StaticOrder& S, const Epi& E) {
;     ...
;             PG8_WAIT_V(8); PG8_WAIT_L(0); PG8_BAR; PG8_MMA(1, 0, At, B0); PG8_MMA(1, 1, At, B1); PG8_BAR; PG8_SCHED;
;             PG8_LDB(B0, 1, 0); PG8_LDB(B1, 1, 1); PG8_SCHED; PG8_LDA(At, 1, 0); PG8_STAGE(PG8_SA(0, 1), a2 + hsA, A);
;             PG8_WAIT_V(8); PG8_WAIT_L(0); PG8_BAR; PG8_MMA(0, 0, At, B0); PG8_MMA(0, 1, At, B1); PG8_BAR; PG8_SCHED;
;             PG8_LDA(At, 1, 1); PG8_STAGE(PG8_SB(1, 0), b3, B); PG8_STAGE(PG8_SB(1, 1), b3 + hsB, B); PG8_STAGE(PG8_SA(1, 0), a3, A);
	s_setprio 1
	s_waitcnt lgkmcnt(7)
	v_mfma_i32_16x16x64_i8 v[62:65], v[140:143], v[172:175], v[62:65]
	v_mfma_i32_16x16x64_i8 v[54:57], v[148:151], v[172:175], v[54:57]
	s_waitcnt lgkmcnt(5)
	v_mfma_i32_16x16x64_i8 v[46:49], v[140:143], v[186:189], v[46:49]
	v_mfma_i32_16x16x64_i8 v[38:41], v[148:151], v[186:189], v[38:41]
	s_waitcnt lgkmcnt(3)
	v_mfma_i32_16x16x64_i8 v[30:33], v[140:143], v[194:197], v[30:33]
	v_mfma_i32_16x16x64_i8 v[22:25], v[148:151], v[194:197], v[22:25]
	s_waitcnt lgkmcnt(1)
	v_mfma_i32_16x16x64_i8 v[14:17], v[140:143], v[204:207], v[14:17]
	v_mfma_i32_16x16x64_i8 v[6:9], v[148:151], v[204:207], v[6:9]
	v_mfma_i32_16x16x64_i8 v[62:65], v[144:147], v[182:185], v[62:65]
	v_mfma_i32_16x16x64_i8 v[54:57], v[152:155], v[182:185], v[54:57]
	v_mfma_i32_16x16x64_i8 v[46:49], v[144:147], v[190:193], v[46:49]
	v_mfma_i32_16x16x64_i8 v[38:41], v[152:155], v[190:193], v[38:41]
	v_mfma_i32_16x16x64_i8 v[30:33], v[144:147], v[198:201], v[30:33]
	v_mfma_i32_16x16x64_i8 v[22:25], v[152:155], v[198:201], v[22:25]
	s_waitcnt lgkmcnt(0)
	v_mfma_i32_16x16x64_i8 v[14:17], v[144:147], v[208:211], v[14:17]
	v_mfma_i32_16x16x64_i8 v[6:9], v[152:155], v[208:211], v[6:9]
	s_setprio 0
	s_setprio 1
	v_mfma_i32_16x16x64_i8 v[58:61], v[156:159], v[172:175], v[58:61]
	v_mfma_i32_16x16x64_i8 v[50:53], v[164:167], v[172:175], v[50:53]
	v_mfma_i32_16x16x64_i8 v[42:45], v[156:159], v[186:189], v[42:45]
	v_mfma_i32_16x16x64_i8 v[34:37], v[164:167], v[186:189], v[34:37]
	v_mfma_i32_16x16x64_i8 v[26:29], v[156:159], v[194:197], v[26:29]
	v_mfma_i32_16x16x64_i8 v[18:21], v[164:167], v[194:197], v[18:21]
	v_mfma_i32_16x16x64_i8 v[10:13], v[156:159], v[204:207], v[10:13]
	v_mfma_i32_16x16x64_i8 v[2:5], v[164:167], v[204:207], v[2:5]
	v_mfma_i32_16x16x64_i8 v[58:61], v[160:163], v[182:185], v[58:61]
	v_mfma_i32_16x16x64_i8 v[50:53], v[168:171], v[182:185], v[50:53]
	v_mfma_i32_16x16x64_i8 v[42:45], v[160:163], v[190:193], v[42:45]
	v_mfma_i32_16x16x64_i8 v[34:37], v[168:171], v[190:193], v[34:37]
	v_mfma_i32_16x16x64_i8 v[26:29], v[160:163], v[198:201], v[26:29]
	v_mfma_i32_16x16x64_i8 v[18:21], v[168:171], v[198:201], v[18:21]
	v_mfma_i32_16x16x64_i8 v[10:13], v[160:163], v[208:211], v[10:13]
	v_mfma_i32_16x16x64_i8 v[2:5], v[168:171], v[208:211], v[2:5]
	s_setprio 0
	s_barrier
	v_add_u32_e32 v139, 0x18000, v137
	ds_read_b128 v[140:143], v139
	ds_read_b128 v[144:147], v139 offset:1024
	ds_read_b128 v[148:151], v139 offset:2048
	ds_read_b128 v[152:155], v139 offset:3072
	v_add_u32_e32 v139, 0x1c000, v137
	ds_read_b128 v[156:159], v139
	ds_read_b128 v[160:163], v139 offset:1024
	ds_read_b128 v[164:167], v139 offset:2048
	ds_read_b128 v[168:171], v139 offset:3072
	ds_read_b128 v[172:175], v138 offset:32768
	ds_read_b128 v[182:185], v138 offset:33792
	ds_read_b128 v[186:189], v138 offset:34816
	ds_read_b128 v[190:193], v138 offset:35840
	ds_read_b128 v[194:197], v138 offset:36864
	ds_read_b128 v[198:201], v138 offset:37888
	ds_read_b128 v[204:207], v138 offset:38912
	ds_read_b128 v[208:211], v138 offset:39936
	s_add_u32 s66, s28, 0x80000
	s_addc_u32 s67, s29, 0
	s_mov_b32 m0, s46
	s_nop 0
	global_load_lds_dwordx4 v1, s[66:67]
	s_add_u32 s66, s28, 0xc0000
	s_addc_u32 s67, s29, 0
	s_mov_b32 m0, s47
	s_nop 0
	global_load_lds_dwordx4 v1, s[66:67]
	s_waitcnt vmcnt(8)
	s_waitcnt lgkmcnt(0)
	s_barrier
	s_setprio 1
	s_waitcnt lgkmcnt(7)
	v_mfma_i32_16x16x64_i8 v[126:129], v[140:143], v[172:175], v[126:129]
	v_mfma_i32_16x16x64_i8 v[118:121], v[148:151], v[172:175], v[118:121]
	s_waitcnt lgkmcnt(5)
	v_mfma_i32_16x16x64_i8 v[110:113], v[140:143], v[186:189], v[110:113]
	v_mfma_i32_16x16x64_i8 v[102:105], v[148:151], v[186:189], v[102:105]
	s_waitcnt lgkmcnt(3)
	v_mfma_i32_16x16x64_i8 v[94:97], v[140:143], v[194:197], v[94:97]
	v_mfma_i32_16x16x64_i8 v[86:89], v[148:151], v[194:197], v[86:89]
	s_waitcnt lgkmcnt(1)
	v_mfma_i32_16x16x64_i8 v[78:81], v[140:143], v[204:207], v[78:81]
	v_mfma_i32_16x16x64_i8 v[70:73], v[148:151], v[204:207], v[70:73]
	v_mfma_i32_16x16x64_i8 v[126:129], v[144:147], v[182:185], v[126:129]
	v_mfma_i32_16x16x64_i8 v[118:121], v[152:155], v[182:185], v[118:121]
	v_mfma_i32_16x16x64_i8 v[110:113], v[144:147], v[190:193], v[110:113]
	v_mfma_i32_16x16x64_i8 v[102:105], v[152:155], v[190:193], v[102:105]
	v_mfma_i32_16x16x64_i8 v[94:97], v[144:147], v[198:201], v[94:97]
	v_mfma_i32_16x16x64_i8 v[86:89], v[152:155], v[198:201], v[86:89]
	s_waitcnt lgkmcnt(0)
	v_mfma_i32_16x16x64_i8 v[78:81], v[144:147], v[208:211], v[78:81]
	v_mfma_i32_16x16x64_i8 v[70:73], v[152:155], v[208:211], v[70:73]
	s_setprio 0
	s_setprio 1
	v_mfma_i32_16x16x64_i8 v[122:125], v[156:159], v[172:175], v[122:125]
	v_mfma_i32_16x16x64_i8 v[114:117], v[164:167], v[172:175], v[114:117]
	v_mfma_i32_16x16x64_i8 v[106:109], v[156:159], v[186:189], v[106:109]
	v_mfma_i32_16x16x64_i8 v[98:101], v[164:167], v[186:189], v[98:101]
	v_mfma_i32_16x16x64_i8 v[90:93], v[156:159], v[194:197], v[90:93]
	v_mfma_i32_16x16x64_i8 v[82:85], v[164:167], v[194:197], v[82:85]
	v_mfma_i32_16x16x64_i8 v[74:77], v[156:159], v[204:207], v[74:77]
	v_mfma_i32_16x16x64_i8 v[66:69], v[164:167], v[204:207], v[66:69]
	v_mfma_i32_16x16x64_i8 v[122:125], v[160:163], v[182:185], v[122:125]
	v_mfma_i32_16x16x64_i8 v[114:117], v[168:171], v[182:185], v[114:117]
	v_mfma_i32_16x16x64_i8 v[106:109], v[160:163], v[190:193], v[106:109]
	v_mfma_i32_16x16x64_i8 v[98:101], v[168:171], v[190:193], v[98:101]
	v_mfma_i32_16x16x64_i8 v[90:93], v[160:163], v[198:201], v[90:93]
	v_mfma_i32_16x16x64_i8 v[82:85], v[168:171], v[198:201], v[82:85]
	v_mfma_i32_16x16x64_i8 v[74:77], v[160:163], v[208:211], v[74:77]
	v_mfma_i32_16x16x64_i8 v[66:69], v[168:171], v[208:211], v[66:69]
	s_setprio 0
	s_add_u32 s66, s34, 0x80
	s_addc_u32 s67, s35, 0
	s_barrier
; #define PG8_STAGE(bufoff, gbase, X) do { _Pragma("unroll") for (int _i = 0; _i < 2; ++_i) { \
;         const char* gp_ = (const char*)(gbase) + (_i ? rs##X : (size_t)0); const unsigned la_ = (unsigned)(size_t)(lds + (bufoff) + ldsw + _i * 8192); \
;         asm volatile("s_mov_b32 m0, %2\n\ts_nop 0\n\tglobal_load_lds_dwordx4 %0, %1" :: "v"(voff##X), "s"(gp_), "s"(la_) : "memory", "m0"); } } while (0)
; #define PG8_LDA(dst, b, h) do { _Pragma("unroll") for (int m = 0; m < 4; ++m) _Pragma("unroll") for (int k = 0; k < 2; ++k) dst[m][k] = *(const LAS bf16x8*)(lds + PG8_SA(b, h) + aoff + m * 2048 + k * 1024); } while (0)
; #define PG8_WAIT_V(n) asm volatile("s_waitcnt vmcnt(" #n ")" ::: "memory")
; #define PG8_WAIT_L(n) asm volatile("s_waitcnt lgkmcnt(" #n ")" ::: "memory")
; #define PG8_BAR __builtin_amdgcn_s_barrier()
; #define PG8_SCHED __builtin_amdgcn_sched_barrier(0)
; template <class Epi>
; __device__ __forceinline__ void gemm_phase(LAS unsigned char* lds, const Gemm g_in, const StaticOrder& S, const Epi& E) {
;     ...
;             PG8_LDA(At, 1, 1); PG8_STAGE(PG8_SB(1, 0), b3, B); PG8_STAGE(PG8_SB(1, 1), b3 + hsB, B); PG8_STAGE(PG8_SA(1, 0), a3, A);
;             PG8_WAIT_V(8); PG8_WAIT_L(0); PG8_BAR; PG8_MMA(1, 0, At, B0); PG8_MMA(1, 1, At, B1); PG8_BAR; PG8_SCHED;
;         }
	ds_read_b128 v[172:175], v138 offset:49152
	ds_read_b128 v[182:185], v138 offset:50176
	ds_read_b128 v[186:189], v138 offset:51200
	ds_read_b128 v[190:193], v138 offset:52224
	ds_read_b128 v[194:197], v138 offset:53248
	ds_read_b128 v[198:201], v138 offset:54272
	ds_read_b128 v[204:207], v138 offset:55296
	ds_read_b128 v[208:211], v138 offset:56320
	s_mov_b32 m0, s50
	s_nop 0
	global_load_lds_dwordx4 v134, s[66:67]
	s_add_u32 s66, s34, 0x40080
	s_addc_u32 s67, s35, 0
	s_mov_b32 m0, s51
	s_nop 0
	global_load_lds_dwordx4 v134, s[66:67]
	s_add_u32 s66, s34, 0x80080
	s_addc_u32 s67, s35, 0
	s_mov_b32 m0, s54
	s_nop 0
	global_load_lds_dwordx4 v134, s[66:67]
	s_add_u32 s34, s34, 0xc0080
	s_addc_u32 s35, s35, 0
	s_mov_b32 m0, s55
	s_nop 0
	global_load_lds_dwordx4 v134, s[34:35]
	s_add_u32 s28, s28, 0x40080
	s_mov_b32 m0, s52
	s_nop 0
	global_load_lds_dwordx4 v1, s[30:31]
	s_addc_u32 s29, s29, 0
	s_mov_b32 m0, s53
	s_nop 0
	global_load_lds_dwordx4 v1, s[28:29]
	s_waitcnt vmcnt(8)
	s_waitcnt lgkmcnt(0)
	s_barrier
	s_setprio 1
	s_waitcnt lgkmcnt(7)
	v_mfma_i32_16x16x64_i8 v[62:65], v[140:143], v[172:175], v[62:65]
	v_mfma_i32_16x16x64_i8 v[54:57], v[148:151], v[172:175], v[54:57]
	s_waitcnt lgkmcnt(5)
	v_mfma_i32_16x16x64_i8 v[46:49], v[140:143], v[186:189], v[46:49]
	v_mfma_i32_16x16x64_i8 v[38:41], v[148:151], v[186:189], v[38:41]
	s_waitcnt lgkmcnt(3)
	v_mfma_i32_16x16x64_i8 v[30:33], v[140:143], v[194:197], v[30:33]
	v_mfma_i32_16x16x64_i8 v[22:25], v[148:151], v[194:197], v[22:25]
	s_waitcnt lgkmcnt(1)
	v_mfma_i32_16x16x64_i8 v[14:17], v[140:143], v[204:207], v[14:17]
	v_mfma_i32_16x16x64_i8 v[6:9], v[148:151], v[204:207], v[6:9]
	v_mfma_i32_16x16x64_i8 v[62:65], v[144:147], v[182:185], v[62:65]
	v_mfma_i32_16x16x64_i8 v[54:57], v[152:155], v[182:185], v[54:57]
	v_mfma_i32_16x16x64_i8 v[46:49], v[144:147], v[190:193], v[46:49]
	v_mfma_i32_16x16x64_i8 v[38:41], v[152:155], v[190:193], v[38:41]
	v_mfma_i32_16x16x64_i8 v[30:33], v[144:147], v[198:201], v[30:33]
	v_mfma_i32_16x16x64_i8 v[22:25], v[152:155], v[198:201], v[22:25]
	s_waitcnt lgkmcnt(0)
	v_mfma_i32_16x16x64_i8 v[14:17], v[144:147], v[208:211], v[14:17]
	v_mfma_i32_16x16x64_i8 v[6:9], v[152:155], v[208:211], v[6:9]
	s_setprio 0
	s_setprio 1
	v_mfma_i32_16x16x64_i8 v[58:61], v[156:159], v[172:175], v[58:61]
	v_mfma_i32_16x16x64_i8 v[50:53], v[164:167], v[172:175], v[50:53]
	v_mfma_i32_16x16x64_i8 v[42:45], v[156:159], v[186:189], v[42:45]
	v_mfma_i32_16x16x64_i8 v[34:37], v[164:167], v[186:189], v[34:37]
	v_mfma_i32_16x16x64_i8 v[26:29], v[156:159], v[194:197], v[26:29]
	v_mfma_i32_16x16x64_i8 v[18:21], v[164:167], v[194:197], v[18:21]
	v_mfma_i32_16x16x64_i8 v[10:13], v[156:159], v[204:207], v[10:13]
	v_mfma_i32_16x16x64_i8 v[2:5], v[164:167], v[204:207], v[2:5]
	v_mfma_i32_16x16x64_i8 v[58:61], v[160:163], v[182:185], v[58:61]
	v_mfma_i32_16x16x64_i8 v[50:53], v[168:171], v[182:185], v[50:53]
	v_mfma_i32_16x16x64_i8 v[42:45], v[160:163], v[190:193], v[42:45]
	v_mfma_i32_16x16x64_i8 v[34:37], v[168:171], v[190:193], v[34:37]
	v_mfma_i32_16x16x64_i8 v[26:29], v[160:163], v[198:201], v[26:29]
	v_mfma_i32_16x16x64_i8 v[18:21], v[168:171], v[198:201], v[18:21]
	v_mfma_i32_16x16x64_i8 v[10:13], v[160:163], v[208:211], v[10:13]
	v_mfma_i32_16x16x64_i8 v[2:5], v[168:171], v[208:211], v[2:5]
	s_setprio 0
	s_add_u32 s62, s62, 0x100
	s_addc_u32 s63, s63, 0
	s_add_u32 s26, s26, 0x100
	s_addc_u32 s27, s27, 0
	s_cmp_ge_i32 s64, s37
	s_mov_b32 s28, s64
	s_barrier
	s_cbranch_scc0 .LBB0_1510
	s_and_b64 vcc, exec, s[14:15]
	s_cbranch_vccz .LBB0_1513

; #define PG8_STAGE(bufoff, gbase, X) do { _Pragma("unroll") for (int _i = 0; _i < 2; ++_i) { \
;         const char* gp_ = (const char*)(gbase) + (_i ? rs##X : (size_t)0); const unsigned la_ = (unsigned)(size_t)(lds + (bufoff) + ldsw + _i * 8192); \
;         asm volatile("s_mov_b32 m0, %2\n\ts_nop 0\n\tglobal_load_lds_dwordx4 %0, %1" :: "v"(voff##X), "s"(gp_), "s"(la_) : "memory", "m0"); } } while (0)
; #define PG8_LDA(dst, b, h) do { _Pragma("unroll") for (int m = 0; m < 4; ++m) _Pragma("unroll") for (int k = 0; k < 2; ++k) dst[m][k] = *(const LAS bf16x8*)(lds + PG8_SA(b, h) + aoff + m * 2048 + k * 1024); } while (0)
; #define PG8_LDB(dst, b, h) do { _Pragma("unroll") for (int n = 0; n < 2; ++n) _Pragma("unroll") for (int k = 0; k < 2; ++k) dst[n][k] = *(const LAS bf16x8*)(lds + PG8_SB(b, h) + boff + n * 2048 + k * 1024); } while (0)
; #define PG8_WAIT_V(n) asm volatile("s_waitcnt vmcnt(" #n ")" ::: "memory")
; #define PG8_WAIT_L(n) asm volatile("s_waitcnt lgkmcnt(" #n ")" ::: "memory")
; #define PG8_BAR __builtin_amdgcn_s_barrier()
; #define PG8_SCHED __builtin_amdgcn_sched_barrier(0)
; template <class Epi>
; __device__ __forceinline__ void gemm_phase(LAS unsigned char* lds, const Gemm g_in, const StaticOrder& S, const Epi& E) {
;     ...
;         for (int t = 0; t < nt; t += 2) {
;             const bool last = (t == nt - 2);
;             const char* a1 = cA + (size_t)(t + 1) * kstep;
;             const char* a2 = last ? nA : cA + (size_t)(t + 2) * kstep; const char* b2 = last ? nB : cB + (size_t)(t + 2) * kstep;
;             const char* a3 = a2 + kstep; const char* b3 = b2 + kstep;
;             PG8_LDB(B0, 0, 0); PG8_LDB(B1, 0, 1); PG8_SCHED; PG8_LDA(At, 0, 0); PG8_STAGE(PG8_SA(1, 1), a1 + hsA, A);
;             PG8_WAIT_V(8); PG8_WAIT_L(0); PG8_BAR; PG8_MMA(0, 0, At, B0); PG8_MMA(0, 1, At, B1); PG8_BAR; PG8_SCHED;
;             PG8_LDA(At, 0, 1); PG8_STAGE(PG8_SB(0, 0), b2, B); PG8_STAGE(PG8_SB(0, 1), b2 + hsB, B); PG8_STAGE(PG8_SA(0, 0), a2, A);
;             PG8_WAIT_V(8); PG8_WAIT_L(0); PG8_BAR; PG8_MMA(1, 0, At, B0); PG8_MMA(1, 1, At, B1); PG8_BAR; PG8_SCHED;
.LBB0_1590:
	ds_read_b128 v[26:29], v198
	ds_read_b128 v[30:33], v198 offset:1024
	ds_read_b128 v[18:21], v198 offset:2048
	ds_read_b128 v[22:25], v198 offset:3072
	ds_read_b128 v[10:13], v199
	ds_read_b128 v[14:17], v199 offset:1024
	ds_read_b128 v[2:5], v199 offset:2048
	ds_read_b128 v[6:9], v199 offset:3072
	s_add_i32 s70, s38, 2
	s_add_u32 s40, s0, 0xffdfc080
	s_addc_u32 s39, s1, -1
	s_cmp_eq_u32 s61, s38
	s_cselect_b32 s38, s12, s40
	s_cselect_b32 s39, s13, s39
	s_cselect_b32 s42, s36, s68
	s_cselect_b32 s43, s37, s69
	s_add_u32 s40, s38, 0x80
	s_addc_u32 s41, s39, 0
	ds_read_b128 v[166:169], v200
	ds_read_b128 v[170:173], v200 offset:1024
	ds_read_b128 v[180:183], v200 offset:2048
	ds_read_b128 v[184:187], v200 offset:3072
	ds_read_b128 v[188:191], v200 offset:4096
	ds_read_b128 v[192:195], v200 offset:5120
	ds_read_b128 v[204:207], v200 offset:6144
	ds_read_b128 v[208:211], v200 offset:7168
	s_add_u32 s72, s0, 0xfff54000
	s_addc_u32 s73, s1, -1
	s_mov_b32 m0, s62
	s_nop 0
	global_load_lds_dwordx4 v1, s[72:73]
	s_nop 0
	s_mov_b32 m0, s63
	s_nop 0
	global_load_lds_dwordx4 v1, s[0:1]
	s_waitcnt vmcnt(8)
	s_waitcnt lgkmcnt(0)
	s_barrier
	s_setprio 1
	s_waitcnt lgkmcnt(0)
	v_mfma_f32_16x16x128_f8f6f4 v[82:85], v[26:33], v[166:173], v[82:85]
	v_mfma_f32_16x16x128_f8f6f4 v[110:113], v[18:25], v[166:173], v[110:113]
	s_waitcnt lgkmcnt(4)
	v_mfma_f32_16x16x128_f8f6f4 v[78:81], v[26:33], v[180:187], v[78:81]
	v_mfma_f32_16x16x128_f8f6f4 v[74:77], v[18:25], v[180:187], v[74:77]
	s_waitcnt lgkmcnt(2)
	v_mfma_f32_16x16x128_f8f6f4 v[62:65], v[26:33], v[188:195], v[62:65]
	v_mfma_f32_16x16x128_f8f6f4 v[58:61], v[18:25], v[188:195], v[58:61]
	s_waitcnt lgkmcnt(0)
	v_mfma_f32_16x16x128_f8f6f4 v[46:49], v[26:33], v[204:211], v[46:49]
	v_mfma_f32_16x16x128_f8f6f4 v[42:45], v[18:25], v[204:211], v[42:45]
	s_setprio 0
	s_setprio 1
	v_mfma_f32_16x16x128_f8f6f4 v[158:161], v[10:17], v[166:173], v[158:161]
	v_mfma_f32_16x16x128_f8f6f4 v[154:157], v[2:9], v[166:173], v[154:157]
	v_mfma_f32_16x16x128_f8f6f4 v[142:145], v[10:17], v[180:187], v[142:145]
	v_mfma_f32_16x16x128_f8f6f4 v[138:141], v[2:9], v[180:187], v[138:141]
	v_mfma_f32_16x16x128_f8f6f4 v[126:129], v[10:17], v[188:195], v[126:129]
	v_mfma_f32_16x16x128_f8f6f4 v[122:125], v[2:9], v[188:195], v[122:125]
	v_mfma_f32_16x16x128_f8f6f4 v[106:109], v[10:17], v[204:211], v[106:109]
	v_mfma_f32_16x16x128_f8f6f4 v[102:105], v[2:9], v[204:211], v[102:105]
	s_setprio 0
	s_add_u32 s72, s42, 0xac000
	s_barrier
	ds_read_b128 v[166:169], v200 offset:16384
	ds_read_b128 v[170:173], v200 offset:17408
	ds_read_b128 v[180:183], v200 offset:18432
	ds_read_b128 v[184:187], v200 offset:19456
	ds_read_b128 v[188:191], v200 offset:20480
	ds_read_b128 v[192:195], v200 offset:21504
	ds_read_b128 v[204:207], v200 offset:22528
	ds_read_b128 v[208:211], v200 offset:23552
	s_mov_b32 m0, s48
	s_nop 0
	global_load_lds_dwordx4 v179, s[42:43]
	s_addc_u32 s73, s43, 0
	s_mov_b32 m0, s49
	s_nop 0
	global_load_lds_dwordx4 v179, s[72:73]
	s_add_u32 s72, s42, 0x158000
	s_addc_u32 s73, s43, 0
	s_mov_b32 m0, s50
	s_nop 0
	global_load_lds_dwordx4 v179, s[72:73]
	s_add_u32 s72, s42, 0x204000
	s_addc_u32 s73, s43, 0
	s_mov_b32 m0, s51
	s_nop 0
	global_load_lds_dwordx4 v179, s[72:73]
	s_add_u32 s72, s38, 0xac000
	s_mov_b32 m0, s47
	s_nop 0
	global_load_lds_dwordx4 v1, s[38:39]
	s_addc_u32 s73, s39, 0
	s_mov_b32 m0, s52
	s_nop 0
	global_load_lds_dwordx4 v1, s[72:73]
	s_waitcnt vmcnt(8)
	s_waitcnt lgkmcnt(0)
	s_barrier
	s_setprio 1
	s_waitcnt lgkmcnt(0)
	v_mfma_f32_16x16x128_f8f6f4 v[98:101], v[26:33], v[166:173], v[98:101]
	v_mfma_f32_16x16x128_f8f6f4 v[94:97], v[18:25], v[166:173], v[94:97]
	s_waitcnt lgkmcnt(4)
	v_mfma_f32_16x16x128_f8f6f4 v[70:73], v[26:33], v[180:187], v[70:73]
	v_mfma_f32_16x16x128_f8f6f4 v[66:69], v[18:25], v[180:187], v[66:69]
	s_waitcnt lgkmcnt(2)
	v_mfma_f32_16x16x128_f8f6f4 v[54:57], v[26:33], v[188:195], v[54:57]
	v_mfma_f32_16x16x128_f8f6f4 v[50:53], v[18:25], v[188:195], v[50:53]
	s_waitcnt lgkmcnt(0)
	v_mfma_f32_16x16x128_f8f6f4 v[38:41], v[26:33], v[204:211], v[38:41]
	v_mfma_f32_16x16x128_f8f6f4 v[34:37], v[18:25], v[204:211], v[34:37]
	s_setprio 0
	s_setprio 1
	v_mfma_f32_16x16x128_f8f6f4 v[150:153], v[10:17], v[166:173], v[150:153]
	v_mfma_f32_16x16x128_f8f6f4 v[146:149], v[2:9], v[166:173], v[146:149]
	v_mfma_f32_16x16x128_f8f6f4 v[134:137], v[10:17], v[180:187], v[134:137]
	v_mfma_f32_16x16x128_f8f6f4 v[130:133], v[2:9], v[180:187], v[130:133]
	v_mfma_f32_16x16x128_f8f6f4 v[118:121], v[10:17], v[188:195], v[118:121]
	v_mfma_f32_16x16x128_f8f6f4 v[114:117], v[2:9], v[188:195], v[114:117]
	v_mfma_f32_16x16x128_f8f6f4 v[90:93], v[10:17], v[204:211], v[90:93]
	v_mfma_f32_16x16x128_f8f6f4 v[86:89], v[2:9], v[204:211], v[86:89]
	s_setprio 0
	s_barrier
	ds_read_b128 v[18:21], v201
	ds_read_b128 v[22:25], v201 offset:1024
	ds_read_b128 v[26:29], v201 offset:2048
	ds_read_b128 v[30:33], v201 offset:3072
	ds_read_b128 v[10:13], v203
	ds_read_b128 v[14:17], v203 offset:1024
	ds_read_b128 v[2:5], v203 offset:2048
	ds_read_b128 v[6:9], v203 offset:3072
	ds_read_b128 v[166:169], v200 offset:32768
	ds_read_b128 v[170:173], v200 offset:33792
	ds_read_b128 v[180:183], v200 offset:34816
	ds_read_b128 v[184:187], v200 offset:35840
	ds_read_b128 v[188:191], v200 offset:36864
	ds_read_b128 v[192:195], v200 offset:37888
	ds_read_b128 v[204:207], v200 offset:38912
	ds_read_b128 v[208:211], v200 offset:39936
	s_add_u32 s72, s38, 0x158000
	s_addc_u32 s73, s39, 0
	s_mov_b32 m0, s53
	s_nop 0
	global_load_lds_dwordx4 v1, s[72:73]
	s_add_u32 s72, s38, 0x204000
	s_addc_u32 s73, s39, 0
	s_mov_b32 m0, s54
	s_nop 0
	global_load_lds_dwordx4 v1, s[72:73]
	s_waitcnt vmcnt(8)
	s_waitcnt lgkmcnt(0)
	s_barrier
; #define PG8_STAGE(bufoff, gbase, X) do { _Pragma("unroll") for (int _i = 0; _i < 2; ++_i) { \
;         const char* gp_ = (const char*)(gbase) + (_i ? rs##X : (size_t)0); const unsigned la_ = (unsigned)(size_t)(lds + (bufoff) + ldsw + _i * 8192); \
;         asm volatile("s_mov_b32 m0, %2\n\ts_nop 0\n\tglobal_load_lds_dwordx4 %0, %1" :: "v"(voff##X), "s"(gp_), "s"(la_) : "memory", "m0"); } } while (0)
; #define PG8_LDA(dst, b, h) do { _Pragma("unroll") for (int m = 0; m < 4; ++m) _Pragma("unroll") for (int k = 0; k < 2; ++k) dst[m][k] = *(const LAS bf16x8*)(lds + PG8_SA(b, h) + aoff + m * 2048 + k * 1024); } while (0)
; #define PG8_LDB(dst, b, h) do { _Pragma("unroll") for (int n = 0; n < 2; ++n) _Pragma("unroll") for (int k = 0; k < 2; ++k) dst[n][k] = *(const LAS bf16x8*)(lds + PG8_SB(b, h) + boff + n * 2048 + k * 1024); } while (0)
; #define PG8_WAIT_V(n) asm volatile("s_waitcnt vmcnt(" #n ")" ::: "memory")
; #define PG8_WAIT_L(n) asm volatile("s_waitcnt lgkmcnt(" #n ")" ::: "memory")
; #define PG8_BAR __builtin_amdgcn_s_barrier()
; #define PG8_SCHED __builtin_amdgcn_sched_barrier(0)
; template <class Epi>
; __device__ __forceinline__ void gemm_phase(LAS unsigned char* lds, const Gemm g_in, const StaticOrder& S, const Epi& E) {
;     ...
;             PG8_WAIT_V(8); PG8_WAIT_L(0); PG8_BAR; PG8_MMA(1, 0, At, B0); PG8_MMA(1, 1, At, B1); PG8_BAR; PG8_SCHED;
;             PG8_LDB(B0, 1, 0); PG8_LDB(B1, 1, 1); PG8_SCHED; PG8_LDA(At, 1, 0); PG8_STAGE(PG8_SA(0, 1), a2 + hsA, A);
;             PG8_WAIT_V(8); PG8_WAIT_L(0); PG8_BAR; PG8_MMA(0, 0, At, B0); PG8_MMA(0, 1, At, B1); PG8_BAR; PG8_SCHED;
;             PG8_LDA(At, 1, 1); PG8_STAGE(PG8_SB(1, 0), b3, B); PG8_STAGE(PG8_SB(1, 1), b3 + hsB, B); PG8_STAGE(PG8_SA(1, 0), a3, A);
;             PG8_WAIT_V(8); PG8_WAIT_L(0); PG8_BAR; PG8_MMA(1, 0, At, B0); PG8_MMA(1, 1, At, B1); PG8_BAR; PG8_SCHED;
;         }
	s_setprio 1
	s_waitcnt lgkmcnt(0)
	v_mfma_f32_16x16x128_f8f6f4 v[82:85], v[18:25], v[166:173], v[82:85]
	v_mfma_f32_16x16x128_f8f6f4 v[110:113], v[26:33], v[166:173], v[110:113]
	s_waitcnt lgkmcnt(4)
	v_mfma_f32_16x16x128_f8f6f4 v[78:81], v[18:25], v[180:187], v[78:81]
	v_mfma_f32_16x16x128_f8f6f4 v[74:77], v[26:33], v[180:187], v[74:77]
	s_waitcnt lgkmcnt(2)
	v_mfma_f32_16x16x128_f8f6f4 v[62:65], v[18:25], v[188:195], v[62:65]
	v_mfma_f32_16x16x128_f8f6f4 v[58:61], v[26:33], v[188:195], v[58:61]
	s_waitcnt lgkmcnt(0)
	v_mfma_f32_16x16x128_f8f6f4 v[46:49], v[18:25], v[204:211], v[46:49]
	v_mfma_f32_16x16x128_f8f6f4 v[42:45], v[26:33], v[204:211], v[42:45]
	s_setprio 0
	s_setprio 1
	v_mfma_f32_16x16x128_f8f6f4 v[158:161], v[10:17], v[166:173], v[158:161]
	v_mfma_f32_16x16x128_f8f6f4 v[154:157], v[2:9], v[166:173], v[154:157]
	v_mfma_f32_16x16x128_f8f6f4 v[142:145], v[10:17], v[180:187], v[142:145]
	v_mfma_f32_16x16x128_f8f6f4 v[138:141], v[2:9], v[180:187], v[138:141]
	v_mfma_f32_16x16x128_f8f6f4 v[126:129], v[10:17], v[188:195], v[126:129]
	v_mfma_f32_16x16x128_f8f6f4 v[122:125], v[2:9], v[188:195], v[122:125]
	v_mfma_f32_16x16x128_f8f6f4 v[106:109], v[10:17], v[204:211], v[106:109]
	v_mfma_f32_16x16x128_f8f6f4 v[102:105], v[2:9], v[204:211], v[102:105]
	s_setprio 0
	s_add_u32 s72, s42, 0x80
	s_addc_u32 s73, s43, 0
	s_barrier
	ds_read_b128 v[166:169], v200 offset:49152
	ds_read_b128 v[170:173], v200 offset:50176
	ds_read_b128 v[180:183], v200 offset:51200
	ds_read_b128 v[184:187], v200 offset:52224
	ds_read_b128 v[188:191], v200 offset:53248
	ds_read_b128 v[192:195], v200 offset:54272
	ds_read_b128 v[204:207], v200 offset:55296
	ds_read_b128 v[208:211], v200 offset:56320
	s_mov_b32 m0, s55
	s_nop 0
	global_load_lds_dwordx4 v179, s[72:73]
	s_add_u32 s72, s42, 0xac080
	s_addc_u32 s73, s43, 0
	s_mov_b32 m0, s56
	s_nop 0
	global_load_lds_dwordx4 v179, s[72:73]
	s_add_u32 s72, s42, 0x158080
	s_addc_u32 s73, s43, 0
	s_mov_b32 m0, s59
	s_nop 0
	global_load_lds_dwordx4 v179, s[72:73]
	s_add_u32 s42, s42, 0x204080
	s_addc_u32 s43, s43, 0
	s_mov_b32 m0, s60
	s_nop 0
	global_load_lds_dwordx4 v179, s[42:43]
	s_add_u32 s38, s38, 0xac080
	s_mov_b32 m0, s57
	s_nop 0
	global_load_lds_dwordx4 v1, s[40:41]
	s_addc_u32 s39, s39, 0
	s_mov_b32 m0, s58
	s_nop 0
	global_load_lds_dwordx4 v1, s[38:39]
	s_waitcnt vmcnt(8)
	s_waitcnt lgkmcnt(0)
	s_barrier
	s_setprio 1
	s_waitcnt lgkmcnt(0)
	v_mfma_f32_16x16x128_f8f6f4 v[98:101], v[18:25], v[166:173], v[98:101]
	v_mfma_f32_16x16x128_f8f6f4 v[94:97], v[26:33], v[166:173], v[94:97]
	s_waitcnt lgkmcnt(4)
	v_mfma_f32_16x16x128_f8f6f4 v[70:73], v[18:25], v[180:187], v[70:73]
	v_mfma_f32_16x16x128_f8f6f4 v[66:69], v[26:33], v[180:187], v[66:69]
	s_waitcnt lgkmcnt(2)
	v_mfma_f32_16x16x128_f8f6f4 v[54:57], v[18:25], v[188:195], v[54:57]
	v_mfma_f32_16x16x128_f8f6f4 v[50:53], v[26:33], v[188:195], v[50:53]
	s_waitcnt lgkmcnt(0)
	v_mfma_f32_16x16x128_f8f6f4 v[38:41], v[18:25], v[204:211], v[38:41]
	v_mfma_f32_16x16x128_f8f6f4 v[34:37], v[26:33], v[204:211], v[34:37]
	s_setprio 0
	s_setprio 1
	v_mfma_f32_16x16x128_f8f6f4 v[150:153], v[10:17], v[166:173], v[150:153]
	v_mfma_f32_16x16x128_f8f6f4 v[146:149], v[2:9], v[166:173], v[146:149]
	v_mfma_f32_16x16x128_f8f6f4 v[134:137], v[10:17], v[180:187], v[134:137]
	v_mfma_f32_16x16x128_f8f6f4 v[130:133], v[2:9], v[180:187], v[130:133]
	v_mfma_f32_16x16x128_f8f6f4 v[118:121], v[10:17], v[188:195], v[118:121]
	v_mfma_f32_16x16x128_f8f6f4 v[114:117], v[2:9], v[188:195], v[114:117]
	v_mfma_f32_16x16x128_f8f6f4 v[90:93], v[10:17], v[204:211], v[90:93]
	v_mfma_f32_16x16x128_f8f6f4 v[86:89], v[2:9], v[204:211], v[86:89]
	s_setprio 0
	s_add_u32 s68, s68, 0x100
	s_addc_u32 s69, s69, 0
	s_add_u32 s0, s0, 0x100
	s_addc_u32 s1, s1, 0
	s_cmp_ge_i32 s70, s44
	s_mov_b32 s38, s70
	s_barrier
	s_cbranch_scc0 .LBB0_1590
;     __device__ __forceinline__ void operator()(const f32x4 (&acc)[2][2][4][2], const Unit& u, int wr, int wc, int fr, int fq) const {
;     ...
;                     for (int bj = 0; bj < 2; ++bj) { f32x4 a0 = acc[ai][bj][m][0], a1 = acc[ai][bj][m][1];
;                         if (IN == 2) { a0 = __builtin_convertvector(__builtin_bit_cast(i32x4, a0), f32x4); a1 = __builtin_convertvector(__builtin_bit_cast(i32x4, a1), f32x4); }
;                         const f32x4 v0 = bv[m][bj][0] * ALPHA + a0 * scale, v1 = bv[m][bj][1] * ALPHA + a1 * scale;
	v_pk_mul_f32 v[194:195], v[84:85], s[22:23] op_sel_hi:[1,0]
	v_pk_mul_f32 v[192:193], v[82:83], s[22:23] op_sel_hi:[1,0]
	v_pk_mul_f32 v[190:191], v[112:113], s[22:23] op_sel_hi:[1,0]
	v_pk_mul_f32 v[188:189], v[110:111], s[22:23] op_sel_hi:[1,0]
	v_pk_mul_f32 v[184:185], v[160:161], s[22:23] op_sel_hi:[1,0]
	v_pk_mul_f32 v[180:181], v[158:159], s[22:23] op_sel_hi:[1,0]
	v_pk_mul_f32 v[174:175], v[156:157], s[22:23] op_sel_hi:[1,0]
	v_pk_mul_f32 v[170:171], v[154:155], s[22:23] op_sel_hi:[1,0]
	v_pk_mul_f32 v[186:187], v[80:81], s[22:23] op_sel_hi:[1,0]
	v_pk_mul_f32 v[182:183], v[78:79], s[22:23] op_sel_hi:[1,0]
	v_pk_mul_f32 v[176:177], v[76:77], s[22:23] op_sel_hi:[1,0]
	v_pk_mul_f32 v[172:173], v[74:75], s[22:23] op_sel_hi:[1,0]
	v_pk_mul_f32 v[166:167], v[144:145], s[22:23] op_sel_hi:[1,0]
	v_pk_mul_f32 v[158:159], v[142:143], s[22:23] op_sel_hi:[1,0]
	v_pk_mul_f32 v[154:155], v[140:141], s[22:23] op_sel_hi:[1,0]
	v_pk_mul_f32 v[142:143], v[138:139], s[22:23] op_sel_hi:[1,0]
	v_pk_mul_f32 v[168:169], v[64:65], s[22:23] op_sel_hi:[1,0]
	v_pk_mul_f32 v[160:161], v[62:63], s[22:23] op_sel_hi:[1,0]
	v_pk_mul_f32 v[156:157], v[60:61], s[22:23] op_sel_hi:[1,0]
	v_pk_mul_f32 v[144:145], v[58:59], s[22:23] op_sel_hi:[1,0]
	v_pk_mul_f32 v[138:139], v[128:129], s[22:23] op_sel_hi:[1,0]
	v_pk_mul_f32 v[126:127], v[126:127], s[22:23] op_sel_hi:[1,0]
	v_pk_mul_f32 v[124:125], v[124:125], s[22:23] op_sel_hi:[1,0]
	v_pk_mul_f32 v[110:111], v[122:123], s[22:23] op_sel_hi:[1,0]
	v_pk_mul_f32 v[140:141], v[48:49], s[22:23] op_sel_hi:[1,0]
	v_pk_mul_f32 v[128:129], v[46:47], s[22:23] op_sel_hi:[1,0]
	v_pk_mul_f32 v[122:123], v[44:45], s[22:23] op_sel_hi:[1,0]
	v_pk_mul_f32 v[112:113], v[42:43], s[22:23] op_sel_hi:[1,0]
	v_pk_mul_f32 v[108:109], v[108:109], s[22:23] op_sel_hi:[1,0]
	v_pk_mul_f32 v[106:107], v[106:107], s[22:23] op_sel_hi:[1,0]
	v_pk_mul_f32 v[104:105], v[104:105], s[22:23] op_sel_hi:[1,0]
	v_pk_mul_f32 v[102:103], v[102:103], s[22:23] op_sel_hi:[1,0]
	v_pk_mul_f32 v[84:85], v[100:101], s[22:23] op_sel_hi:[1,0]
	v_pk_mul_f32 v[82:83], v[98:99], s[22:23] op_sel_hi:[1,0]
	v_pk_mul_f32 v[80:81], v[96:97], s[22:23] op_sel_hi:[1,0]
	v_pk_mul_f32 v[78:79], v[94:95], s[22:23] op_sel_hi:[1,0]
	v_pk_mul_f32 v[76:77], v[152:153], s[22:23] op_sel_hi:[1,0]
	v_pk_mul_f32 v[74:75], v[150:151], s[22:23] op_sel_hi:[1,0]
	v_pk_mul_f32 v[62:63], v[148:149], s[22:23] op_sel_hi:[1,0]
	v_pk_mul_f32 v[58:59], v[146:147], s[22:23] op_sel_hi:[1,0]
	v_pk_mul_f32 v[72:73], v[72:73], s[22:23] op_sel_hi:[1,0]
	v_pk_mul_f32 v[70:71], v[70:71], s[22:23] op_sel_hi:[1,0]
	v_pk_mul_f32 v[64:65], v[68:69], s[22:23] op_sel_hi:[1,0]
	v_pk_mul_f32 v[60:61], v[66:67], s[22:23] op_sel_hi:[1,0]
	v_pk_mul_f32 v[46:47], v[136:137], s[22:23] op_sel_hi:[1,0]
	v_pk_mul_f32 v[42:43], v[134:135], s[22:23] op_sel_hi:[1,0]
	v_pk_mul_f32 v[30:31], v[132:133], s[22:23] op_sel_hi:[1,0]
	v_pk_mul_f32 v[26:27], v[130:131], s[22:23] op_sel_hi:[1,0]
	v_pk_mul_f32 v[48:49], v[56:57], s[22:23] op_sel_hi:[1,0]
	v_pk_mul_f32 v[44:45], v[54:55], s[22:23] op_sel_hi:[1,0]
	v_pk_mul_f32 v[32:33], v[52:53], s[22:23] op_sel_hi:[1,0]
	v_pk_mul_f32 v[28:29], v[50:51], s[22:23] op_sel_hi:[1,0]
	v_pk_mul_f32 v[22:23], v[120:121], s[22:23] op_sel_hi:[1,0]
	v_pk_mul_f32 v[18:19], v[118:119], s[22:23] op_sel_hi:[1,0]
	v_pk_mul_f32 v[14:15], v[116:117], s[22:23] op_sel_hi:[1,0]
	v_pk_mul_f32 v[10:11], v[114:115], s[22:23] op_sel_hi:[1,0]
	v_pk_mul_f32 v[24:25], v[40:41], s[22:23] op_sel_hi:[1,0]
	v_pk_mul_f32 v[20:21], v[38:39], s[22:23] op_sel_hi:[1,0]
	v_pk_mul_f32 v[16:17], v[36:37], s[22:23] op_sel_hi:[1,0]
	v_pk_mul_f32 v[12:13], v[34:35], s[22:23] op_sel_hi:[1,0]
	v_pk_mul_f32 v[8:9], v[92:93], s[22:23] op_sel_hi:[1,0]
	v_pk_mul_f32 v[6:7], v[90:91], s[22:23] op_sel_hi:[1,0]
	v_pk_mul_f32 v[4:5], v[88:89], s[22:23] op_sel_hi:[1,0]
	v_pk_mul_f32 v[2:3], v[86:87], s[22:23] op_sel_hi:[1,0]
	s_and_b64 vcc, exec, s[20:21]
	s_cbranch_vccz .LBB0_1593
